# full-tile GEMM K-loops: LDS-DMA addresses as SGPR base (s[98:99] / vcc, advanced by SALU) + loop-invariant 32-bit lane offsets: no VALU address arithmetic left in the loop
# speedup vs baseline: 1.0069x; 1.0069x over previous
.LBB0_33:
	s_or_b64 exec, exec, s[52:53]
	v_mov_b32_e32 v3, v1
	v_lshl_add_u64 v[12:13], s[0:1], 0, v[2:3]
	s_waitcnt vmcnt(8)
	v_lshl_add_u64 v[16:17], s[14:15], 0, v[2:3]
	v_lshl_add_u64 v[20:21], s[16:17], 0, v[2:3]
	v_lshl_add_u64 v[130:131], s[72:73], 0, v[2:3]
	v_and_b32_e32 v146, 15, v142
	v_bfe_u32 v145, v142, 4, 2
	v_lshlrev_b32_e32 v3, 2, v142
	v_add_u32_e32 v156, 0x18000, v147
	v_lshl_add_u64 v[10:11], s[0:1], 0, v[0:1]
	v_lshl_add_u64 v[14:15], s[14:15], 0, v[0:1]
	v_lshl_add_u64 v[18:19], s[16:17], 0, v[0:1]
	v_lshl_add_u64 v[132:133], s[72:73], 0, v[0:1]
	v_lshlrev_b32_e32 v0, 6, v146
	v_lshlrev_b32_e32 v2, 4, v145
	v_and_b32_e32 v3, 32, v3
	s_mov_b64 s[14:15], 0x80
	v_readfirstlane_b32 s0, v156
	v_add_u32_e32 v157, 0x1a000, v147
	v_bitop3_b32 v22, v2, v3, v0 bitop3:0x36
	v_lshl_add_u64 v[2:3], v[10:11], 0, s[14:15]
	s_mov_b32 m0, s0
	v_readfirstlane_b32 s0, v157
	v_add_u32_e32 v158, 0x8000, v147
	s_waitcnt vmcnt(4)
	s_barrier
	global_load_lds_dwordx4 v[2:3], off
	v_lshl_add_u64 v[2:3], v[12:13], 0, s[14:15]
	s_mov_b32 m0, s0
	v_readfirstlane_b32 s0, v158
	v_add_u32_e32 v159, 0xa000, v147
	global_load_lds_dwordx4 v[2:3], off
	v_lshl_add_u64 v[2:3], v[14:15], 0, s[14:15]
	s_mov_b32 m0, s0
	v_readfirstlane_b32 s0, v159
	v_add_u32_e32 v160, 0x1c000, v147
	global_load_lds_dwordx4 v[2:3], off
	v_lshl_add_u64 v[2:3], v[16:17], 0, s[14:15]
	s_mov_b32 m0, s0
	v_readfirstlane_b32 s0, v160
	v_add_u32_e32 v161, 0x1e000, v147
	global_load_lds_dwordx4 v[2:3], off
	v_lshl_add_u64 v[2:3], v[18:19], 0, s[14:15]
	s_mov_b32 m0, s0
	v_readfirstlane_b32 s0, v161
	global_load_lds_dwordx4 v[2:3], off
	v_lshl_add_u64 v[2:3], v[20:21], 0, s[14:15]
	s_mov_b32 m0, s0
	s_sub_i32 s1, s56, s63
	global_load_lds_dwordx4 v[2:3], off
	s_sub_i32 s1, s1, s62
	v_lshlrev_b32_e32 v0, 15, v4
	s_sext_i32_i16 s1, s1
	v_and_b32_e32 v0, 0xffff0000, v0
	s_lshl_b32 s0, s57, 10
	s_lshl_b32 s1, s1, 8
	v_lshl_add_u32 v0, v5, 12, v0
	v_and_b32_e32 v2, 1, v4
	s_add_i32 s0, s0, s1
	v_lshl_or_b32 v0, v2, 6, v0
	v_lshlrev_b32_e32 v2, 15, v6
	s_ashr_i32 s1, s0, 31
	v_and_b32_e32 v2, 0xffff0000, v2
	s_lshl_b64 s[0:1], s[0:1], 12
	v_lshl_add_u32 v2, v8, 12, v2
	v_and_b32_e32 v3, 1, v6
	s_add_u32 s0, s6, s0
	v_lshl_or_b32 v2, v3, 6, v2
	v_lshl_add_u32 v0, v7, 1, v0
	s_addc_u32 s1, s7, s1
	v_lshl_add_u32 v2, v9, 1, v2
	v_mov_b32_e32 v3, v1
	v_lshl_add_u64 v[134:135], s[0:1], 0, v[0:1]
	v_lshl_add_u64 v[136:137], s[0:1], 0, v[2:3]
	s_add_u32 s0, s88, s12
	v_bfe_u32 v144, v142, 6, 2
	s_waitcnt vmcnt(6)
	s_addc_u32 s1, s89, s13
	v_lshlrev_b32_e32 v23, 13, v143
	v_lshl_or_b32 v24, v144, 12, v212
	v_lshl_add_u64 v[140:141], s[0:1], 0, v[2:3]
	v_mov_b32_e32 v2, 0
	v_lshl_add_u64 v[138:139], s[0:1], 0, v[0:1]
	s_mov_b32 s0, -2
	s_mov_b64 s[12:13], 0
	v_add_u32_e32 v151, v24, v22
	v_add_u32_e32 v0, v23, v22
	v_mov_b32_e32 v3, v2
	v_mov_b32_e32 v4, v2
	v_mov_b32_e32 v5, v2
	v_mov_b32_e32 v6, v2
	v_mov_b32_e32 v7, v2
	v_mov_b32_e32 v8, v2
	v_mov_b32_e32 v9, v2
	v_mov_b32_e32 v10, v2
	v_mov_b32_e32 v11, v2
	v_mov_b32_e32 v12, v2
	v_mov_b32_e32 v13, v2
	v_mov_b32_e32 v14, v2
	v_mov_b32_e32 v15, v2
	v_mov_b32_e32 v16, v2
	v_mov_b32_e32 v17, v2
	v_mov_b32_e32 v18, v2
	v_mov_b32_e32 v19, v2
	v_mov_b32_e32 v20, v2
	v_mov_b32_e32 v21, v2
	v_mov_b32_e32 v22, v2
	v_mov_b32_e32 v23, v2
	v_mov_b32_e32 v24, v2
	v_mov_b32_e32 v25, v2
	v_mov_b32_e32 v26, v2
	v_mov_b32_e32 v27, v2
	v_mov_b32_e32 v28, v2
	v_mov_b32_e32 v29, v2
	v_mov_b32_e32 v30, v2
	v_mov_b32_e32 v31, v2
	v_mov_b32_e32 v32, v2
	v_mov_b32_e32 v33, v2
	v_mov_b32_e32 v34, v2
	v_mov_b32_e32 v35, v2
	v_mov_b32_e32 v36, v2
	v_mov_b32_e32 v37, v2
	v_mov_b32_e32 v38, v2
	v_mov_b32_e32 v39, v2
	v_mov_b32_e32 v40, v2
	v_mov_b32_e32 v41, v2
	v_mov_b32_e32 v42, v2
	v_mov_b32_e32 v43, v2
	v_mov_b32_e32 v44, v2
	v_mov_b32_e32 v45, v2
	v_mov_b32_e32 v46, v2
	v_mov_b32_e32 v47, v2
	v_mov_b32_e32 v48, v2
	v_mov_b32_e32 v49, v2
	v_mov_b32_e32 v50, v2
	v_mov_b32_e32 v51, v2
	v_mov_b32_e32 v52, v2
	v_mov_b32_e32 v53, v2
	v_mov_b32_e32 v54, v2
	v_mov_b32_e32 v55, v2
	v_mov_b32_e32 v56, v2
	v_mov_b32_e32 v57, v2
	v_mov_b32_e32 v58, v2
	v_mov_b32_e32 v59, v2
	v_mov_b32_e32 v60, v2
	v_mov_b32_e32 v61, v2
	v_mov_b32_e32 v62, v2
	v_mov_b32_e32 v63, v2
	v_mov_b32_e32 v64, v2
	v_mov_b32_e32 v65, v2
	v_mov_b32_e32 v70, v2
	v_mov_b32_e32 v71, v2
	v_mov_b32_e32 v72, v2
	v_mov_b32_e32 v73, v2
	v_mov_b32_e32 v86, v2
	v_mov_b32_e32 v87, v2
	v_mov_b32_e32 v88, v2
	v_mov_b32_e32 v89, v2
	v_mov_b32_e32 v90, v2
	v_mov_b32_e32 v91, v2
	v_mov_b32_e32 v92, v2
	v_mov_b32_e32 v93, v2
	v_mov_b32_e32 v94, v2
	v_mov_b32_e32 v95, v2
	v_mov_b32_e32 v96, v2
	v_mov_b32_e32 v97, v2
	v_mov_b32_e32 v98, v2
	v_mov_b32_e32 v99, v2
	v_mov_b32_e32 v100, v2
	v_mov_b32_e32 v101, v2
	v_mov_b32_e32 v102, v2
	v_mov_b32_e32 v103, v2
	v_mov_b32_e32 v104, v2
	v_mov_b32_e32 v105, v2
	v_mov_b32_e32 v106, v2
	v_mov_b32_e32 v107, v2
	v_mov_b32_e32 v108, v2
	v_mov_b32_e32 v109, v2
	v_mov_b32_e32 v110, v2
	v_mov_b32_e32 v111, v2
	v_mov_b32_e32 v112, v2
	v_mov_b32_e32 v113, v2
	v_mov_b32_e32 v114, v2
	v_mov_b32_e32 v115, v2
	v_mov_b32_e32 v116, v2
	v_mov_b32_e32 v117, v2
	v_mov_b32_e32 v118, v2
	v_mov_b32_e32 v119, v2
	v_mov_b32_e32 v120, v2
	v_mov_b32_e32 v121, v2
	v_mov_b32_e32 v122, v2
	v_mov_b32_e32 v123, v2
	v_mov_b32_e32 v124, v2
	v_mov_b32_e32 v125, v2
	v_mov_b32_e32 v126, v2
	v_mov_b32_e32 v127, v2
	v_mov_b32_e32 v128, v2
	v_mov_b32_e32 v129, v2
	v_mov_b32_e32 v66, v2
	v_mov_b32_e32 v67, v2
	v_mov_b32_e32 v68, v2
	v_mov_b32_e32 v69, v2
	v_mov_b32_e32 v74, v2
	v_mov_b32_e32 v75, v2
	v_mov_b32_e32 v76, v2
	v_mov_b32_e32 v77, v2
	v_mov_b32_e32 v78, v2
	v_mov_b32_e32 v79, v2
	v_mov_b32_e32 v80, v2
	v_mov_b32_e32 v81, v2
	v_mov_b32_e32 v82, v2
	v_mov_b32_e32 v83, v2
	v_mov_b32_e32 v84, v2
	v_mov_b32_e32 v85, v2
	s_barrier
	v_add_u32_e32 v162, 0xc000, v147
	v_add_u32_e32 v163, 0xe000, v147
	v_readfirstlane_b32 s1, v147
	s_nop 1
	v_readfirstlane_b32 s98, v138
	v_readfirstlane_b32 s99, v139
	s_nop 3
	s_sub_u32 s98, s98, 0x400000
	s_subb_u32 s99, s99, 0
	v_subrev_u32_e32 v204, s98, v138
	v_add_u32_e32 v216, 0x80080, v204
	v_subrev_u32_e32 v205, s98, v140
	v_add_u32_e32 v217, 0x80080, v205
	v_readfirstlane_b32 vcc_lo, v134
	v_readfirstlane_b32 vcc_hi, v135
	s_nop 3
	s_sub_u32 vcc_lo, vcc_lo, 0x400000
	s_subb_u32 vcc_hi, vcc_hi, 0
	v_subrev_u32_e32 v210, vcc_lo, v134
	v_add_u32_e32 v218, 0x80100, v210
	v_subrev_u32_e32 v211, vcc_lo, v136
	v_add_u32_e32 v219, 0x80100, v211
	v_add_u32_e32 v228, 0x100, v204
	s_add_u32 s98, s98, s12
	s_addc_u32 s99, s99, s13
	s_add_u32 vcc_lo, vcc_lo, s12
	s_addc_u32 vcc_hi, vcc_hi, s13
	s_nop 4
.LBB0_34:
	ds_read_b128 v[164:167], v151
	ds_read_b128 v[168:171], v151 offset:1024
	ds_read_b128 v[172:175], v151 offset:2048
	ds_read_b128 v[176:179], v151 offset:3072
	s_add_i32 m0, s1, 0xc000
	ds_read_b128 v[180:183], v0
	ds_read_b128 v[184:187], v0 offset:1024
	ds_read_b128 v[188:191], v0 offset:2048
	ds_read_b128 v[192:195], v0 offset:3072
	ds_read_b128 v[196:199], v0 offset:4096
	ds_read_b128 v[200:203], v0 offset:5120
	ds_read_b128 v[222:225], v0 offset:6144
	ds_read_b128 v[232:235], v0 offset:7168
	global_load_lds_dwordx4 v216, s[98:99]
	s_add_i32 m0, s1, 0xe000
	s_nop 0
	global_load_lds_dwordx4 v217, s[98:99]
	s_waitcnt lgkmcnt(8)
	s_barrier
	s_waitcnt lgkmcnt(0)
	v_mfma_f32_16x16x32_bf16 v[126:129], v[164:167], v[180:183], v[126:129]
	v_mfma_f32_16x16x32_bf16 v[122:125], v[172:175], v[180:183], v[122:125]
	v_mfma_f32_16x16x32_bf16 v[118:121], v[164:167], v[188:191], v[118:121]
	v_mfma_f32_16x16x32_bf16 v[114:117], v[172:175], v[188:191], v[114:117]
	v_mfma_f32_16x16x32_bf16 v[110:113], v[164:167], v[196:199], v[110:113]
	v_mfma_f32_16x16x32_bf16 v[106:109], v[172:175], v[196:199], v[106:109]
	v_mfma_f32_16x16x32_bf16 v[102:105], v[164:167], v[222:225], v[102:105]
	v_mfma_f32_16x16x32_bf16 v[98:101], v[172:175], v[222:225], v[98:101]
	v_mfma_f32_16x16x32_bf16 v[126:129], v[168:171], v[184:187], v[126:129]
	v_mfma_f32_16x16x32_bf16 v[122:125], v[176:179], v[184:187], v[122:125]
	v_mfma_f32_16x16x32_bf16 v[118:121], v[168:171], v[192:195], v[118:121]
	v_mfma_f32_16x16x32_bf16 v[114:117], v[176:179], v[192:195], v[114:117]
	v_mfma_f32_16x16x32_bf16 v[110:113], v[168:171], v[200:203], v[110:113]
	v_mfma_f32_16x16x32_bf16 v[106:109], v[176:179], v[200:203], v[106:109]
	v_mfma_f32_16x16x32_bf16 v[102:105], v[168:171], v[232:235], v[102:105]
	v_mfma_f32_16x16x32_bf16 v[98:101], v[176:179], v[232:235], v[98:101]
	s_barrier
	s_add_i32 m0, s1, 0xff00
	ds_read_b128 v[236:239], v151 offset:16384
	ds_read_b128 v[240:243], v151 offset:17408
	ds_read_b128 v[244:247], v151 offset:18432
	ds_read_b128 v[248:251], v151 offset:19456
	global_load_lds_dwordx4 v210, vcc offset:256
	s_add_i32 m0, s1, 0x11f00
	s_nop 0
	global_load_lds_dwordx4 v211, vcc offset:256
	s_barrier
	s_waitcnt lgkmcnt(0)
	v_mfma_f32_16x16x32_bf16 v[94:97], v[236:239], v[180:183], v[94:97]
	v_mfma_f32_16x16x32_bf16 v[90:93], v[244:247], v[180:183], v[90:93]
	v_mfma_f32_16x16x32_bf16 v[86:89], v[236:239], v[188:191], v[86:89]
	v_mfma_f32_16x16x32_bf16 v[70:73], v[244:247], v[188:191], v[70:73]
	v_mfma_f32_16x16x32_bf16 v[62:65], v[236:239], v[196:199], v[62:65]
	v_mfma_f32_16x16x32_bf16 v[58:61], v[244:247], v[196:199], v[58:61]
	v_mfma_f32_16x16x32_bf16 v[54:57], v[236:239], v[222:225], v[54:57]
	v_mfma_f32_16x16x32_bf16 v[50:53], v[244:247], v[222:225], v[50:53]
	v_mfma_f32_16x16x32_bf16 v[94:97], v[240:243], v[184:187], v[94:97]
	v_mfma_f32_16x16x32_bf16 v[90:93], v[248:251], v[184:187], v[90:93]
	v_mfma_f32_16x16x32_bf16 v[86:89], v[240:243], v[192:195], v[86:89]
	v_mfma_f32_16x16x32_bf16 v[70:73], v[248:251], v[192:195], v[70:73]
	v_mfma_f32_16x16x32_bf16 v[62:65], v[240:243], v[200:203], v[62:65]
	v_mfma_f32_16x16x32_bf16 v[58:61], v[248:251], v[200:203], v[58:61]
	v_mfma_f32_16x16x32_bf16 v[54:57], v[240:243], v[232:235], v[54:57]
	v_mfma_f32_16x16x32_bf16 v[50:53], v[248:251], v[232:235], v[50:53]
	s_mov_b32 m0, s1
	s_barrier
	ds_read_b128 v[180:183], v0 offset:16384
	ds_read_b128 v[184:187], v0 offset:17408
	ds_read_b128 v[188:191], v0 offset:18432
	ds_read_b128 v[192:195], v0 offset:19456
	ds_read_b128 v[196:199], v0 offset:20480
	ds_read_b128 v[200:203], v0 offset:21504
	ds_read_b128 v[222:225], v0 offset:22528
	ds_read_b128 v[232:235], v0 offset:23552
	global_load_lds_dwordx4 v228, s[98:99]
	s_add_i32 m0, s1, 0x1f00
	s_nop 0
	global_load_lds_dwordx4 v205, s[98:99] offset:256
	s_barrier
	s_waitcnt lgkmcnt(0)
	v_mfma_f32_16x16x32_bf16 v[46:49], v[164:167], v[180:183], v[46:49]
	v_mfma_f32_16x16x32_bf16 v[42:45], v[172:175], v[180:183], v[42:45]
	v_mfma_f32_16x16x32_bf16 v[38:41], v[164:167], v[188:191], v[38:41]
	v_mfma_f32_16x16x32_bf16 v[34:37], v[172:175], v[188:191], v[34:37]
	v_mfma_f32_16x16x32_bf16 v[30:33], v[164:167], v[196:199], v[30:33]
	v_mfma_f32_16x16x32_bf16 v[26:29], v[172:175], v[196:199], v[26:29]
	v_mfma_f32_16x16x32_bf16 v[22:25], v[164:167], v[222:225], v[22:25]
	v_mfma_f32_16x16x32_bf16 v[18:21], v[172:175], v[222:225], v[18:21]
	v_mfma_f32_16x16x32_bf16 v[46:49], v[168:171], v[184:187], v[46:49]
	v_mfma_f32_16x16x32_bf16 v[42:45], v[176:179], v[184:187], v[42:45]
	v_mfma_f32_16x16x32_bf16 v[38:41], v[168:171], v[192:195], v[38:41]
	v_mfma_f32_16x16x32_bf16 v[34:37], v[176:179], v[192:195], v[34:37]
	v_mfma_f32_16x16x32_bf16 v[30:33], v[168:171], v[200:203], v[30:33]
	v_mfma_f32_16x16x32_bf16 v[26:29], v[176:179], v[200:203], v[26:29]
	v_mfma_f32_16x16x32_bf16 v[22:25], v[168:171], v[232:235], v[22:25]
	v_mfma_f32_16x16x32_bf16 v[18:21], v[176:179], v[232:235], v[18:21]
	s_barrier
	s_add_i32 m0, s1, 0x14000
	s_nop 0
	global_load_lds_dwordx4 v218, vcc
	s_add_i32 m0, s1, 0x16000
	s_nop 0
	global_load_lds_dwordx4 v219, vcc
	s_waitcnt vmcnt(6)
	s_barrier
	v_mfma_f32_16x16x32_bf16 v[14:17], v[236:239], v[180:183], v[14:17]
	v_mfma_f32_16x16x32_bf16 v[10:13], v[244:247], v[180:183], v[10:13]
	v_mfma_f32_16x16x32_bf16 v[6:9], v[236:239], v[188:191], v[6:9]
	v_mfma_f32_16x16x32_bf16 v[2:5], v[244:247], v[188:191], v[2:5]
	v_mfma_f32_16x16x32_bf16 v[66:69], v[236:239], v[196:199], v[66:69]
	v_mfma_f32_16x16x32_bf16 v[74:77], v[244:247], v[196:199], v[74:77]
	v_mfma_f32_16x16x32_bf16 v[78:81], v[236:239], v[222:225], v[78:81]
	v_mfma_f32_16x16x32_bf16 v[82:85], v[244:247], v[222:225], v[82:85]
	v_mfma_f32_16x16x32_bf16 v[14:17], v[240:243], v[184:187], v[14:17]
	v_mfma_f32_16x16x32_bf16 v[10:13], v[248:251], v[184:187], v[10:13]
	v_mfma_f32_16x16x32_bf16 v[6:9], v[240:243], v[192:195], v[6:9]
	v_mfma_f32_16x16x32_bf16 v[2:5], v[248:251], v[192:195], v[2:5]
	v_mfma_f32_16x16x32_bf16 v[66:69], v[240:243], v[200:203], v[66:69]
	v_mfma_f32_16x16x32_bf16 v[74:77], v[248:251], v[200:203], v[74:77]
	v_mfma_f32_16x16x32_bf16 v[78:81], v[240:243], v[232:235], v[78:81]
	v_mfma_f32_16x16x32_bf16 v[82:85], v[248:251], v[232:235], v[82:85]
	s_barrier
	ds_read_b128 v[164:167], v151 offset:32768
	ds_read_b128 v[168:171], v151 offset:33792
	ds_read_b128 v[172:175], v151 offset:34816
	ds_read_b128 v[176:179], v151 offset:35840
	s_add_i32 m0, s1, 0x3f80
	ds_read_b128 v[180:183], v0 offset:32768
	ds_read_b128 v[184:187], v0 offset:33792
	ds_read_b128 v[188:191], v0 offset:34816
	ds_read_b128 v[192:195], v0 offset:35840
	ds_read_b128 v[196:199], v0 offset:36864
	ds_read_b128 v[200:203], v0 offset:37888
	ds_read_b128 v[222:225], v0 offset:38912
	ds_read_b128 v[232:235], v0 offset:39936
	global_load_lds_dwordx4 v216, s[98:99] offset:128
	s_add_i32 m0, s1, 0x5f80
	s_nop 0
	global_load_lds_dwordx4 v217, s[98:99] offset:128
	s_waitcnt lgkmcnt(8)
	s_barrier
	s_waitcnt lgkmcnt(0)
	v_mfma_f32_16x16x32_bf16 v[126:129], v[164:167], v[180:183], v[126:129]
	v_mfma_f32_16x16x32_bf16 v[122:125], v[172:175], v[180:183], v[122:125]
	v_mfma_f32_16x16x32_bf16 v[118:121], v[164:167], v[188:191], v[118:121]
	v_mfma_f32_16x16x32_bf16 v[114:117], v[172:175], v[188:191], v[114:117]
	v_mfma_f32_16x16x32_bf16 v[110:113], v[164:167], v[196:199], v[110:113]
	v_mfma_f32_16x16x32_bf16 v[106:109], v[172:175], v[196:199], v[106:109]
	v_mfma_f32_16x16x32_bf16 v[102:105], v[164:167], v[222:225], v[102:105]
	v_mfma_f32_16x16x32_bf16 v[98:101], v[172:175], v[222:225], v[98:101]
	v_mfma_f32_16x16x32_bf16 v[126:129], v[168:171], v[184:187], v[126:129]
	v_mfma_f32_16x16x32_bf16 v[122:125], v[176:179], v[184:187], v[122:125]
	v_mfma_f32_16x16x32_bf16 v[118:121], v[168:171], v[192:195], v[118:121]
	v_mfma_f32_16x16x32_bf16 v[114:117], v[176:179], v[192:195], v[114:117]
	v_mfma_f32_16x16x32_bf16 v[110:113], v[168:171], v[200:203], v[110:113]
	v_mfma_f32_16x16x32_bf16 v[106:109], v[176:179], v[200:203], v[106:109]
	v_mfma_f32_16x16x32_bf16 v[102:105], v[168:171], v[232:235], v[102:105]
	v_mfma_f32_16x16x32_bf16 v[98:101], v[176:179], v[232:235], v[98:101]
	s_barrier
	s_add_i32 m0, s1, 0x17e80
	ds_read_b128 v[236:239], v151 offset:49152
	ds_read_b128 v[240:243], v151 offset:50176
	ds_read_b128 v[244:247], v151 offset:51200
	ds_read_b128 v[248:251], v151 offset:52224
	global_load_lds_dwordx4 v210, vcc offset:384
	s_add_i32 m0, s1, 0x19e80
	s_nop 0
	global_load_lds_dwordx4 v211, vcc offset:384
	s_barrier
	s_waitcnt lgkmcnt(0)
	v_mfma_f32_16x16x32_bf16 v[94:97], v[236:239], v[180:183], v[94:97]
	v_mfma_f32_16x16x32_bf16 v[90:93], v[244:247], v[180:183], v[90:93]
	v_mfma_f32_16x16x32_bf16 v[86:89], v[236:239], v[188:191], v[86:89]
	v_mfma_f32_16x16x32_bf16 v[70:73], v[244:247], v[188:191], v[70:73]
	v_mfma_f32_16x16x32_bf16 v[62:65], v[236:239], v[196:199], v[62:65]
	v_mfma_f32_16x16x32_bf16 v[58:61], v[244:247], v[196:199], v[58:61]
	v_mfma_f32_16x16x32_bf16 v[54:57], v[236:239], v[222:225], v[54:57]
	v_mfma_f32_16x16x32_bf16 v[50:53], v[244:247], v[222:225], v[50:53]
	v_mfma_f32_16x16x32_bf16 v[94:97], v[240:243], v[184:187], v[94:97]
	v_mfma_f32_16x16x32_bf16 v[90:93], v[248:251], v[184:187], v[90:93]
	v_mfma_f32_16x16x32_bf16 v[86:89], v[240:243], v[192:195], v[86:89]
	v_mfma_f32_16x16x32_bf16 v[70:73], v[248:251], v[192:195], v[70:73]
	v_mfma_f32_16x16x32_bf16 v[62:65], v[240:243], v[200:203], v[62:65]
	v_mfma_f32_16x16x32_bf16 v[58:61], v[248:251], v[200:203], v[58:61]
	v_mfma_f32_16x16x32_bf16 v[54:57], v[240:243], v[232:235], v[54:57]
	v_mfma_f32_16x16x32_bf16 v[50:53], v[248:251], v[232:235], v[50:53]
	s_add_i32 m0, s1, 0x7e80
	s_barrier
	ds_read_b128 v[180:183], v0 offset:49152
	ds_read_b128 v[184:187], v0 offset:50176
	ds_read_b128 v[188:191], v0 offset:51200
	ds_read_b128 v[192:195], v0 offset:52224
	ds_read_b128 v[196:199], v0 offset:53248
	ds_read_b128 v[200:203], v0 offset:54272
	ds_read_b128 v[222:225], v0 offset:55296
	ds_read_b128 v[232:235], v0 offset:56320
	global_load_lds_dwordx4 v204, s[98:99] offset:384
	s_add_i32 m0, s1, 0x9e80
	s_nop 0
	global_load_lds_dwordx4 v205, s[98:99] offset:384
	s_barrier
	s_waitcnt lgkmcnt(0)
	v_mfma_f32_16x16x32_bf16 v[46:49], v[164:167], v[180:183], v[46:49]
	v_mfma_f32_16x16x32_bf16 v[42:45], v[172:175], v[180:183], v[42:45]
	v_mfma_f32_16x16x32_bf16 v[38:41], v[164:167], v[188:191], v[38:41]
	v_mfma_f32_16x16x32_bf16 v[34:37], v[172:175], v[188:191], v[34:37]
	v_mfma_f32_16x16x32_bf16 v[30:33], v[164:167], v[196:199], v[30:33]
	v_mfma_f32_16x16x32_bf16 v[26:29], v[172:175], v[196:199], v[26:29]
	v_mfma_f32_16x16x32_bf16 v[22:25], v[164:167], v[222:225], v[22:25]
	v_mfma_f32_16x16x32_bf16 v[18:21], v[172:175], v[222:225], v[18:21]
	v_mfma_f32_16x16x32_bf16 v[46:49], v[168:171], v[184:187], v[46:49]
	v_mfma_f32_16x16x32_bf16 v[42:45], v[176:179], v[184:187], v[42:45]
	v_mfma_f32_16x16x32_bf16 v[38:41], v[168:171], v[192:195], v[38:41]
	v_mfma_f32_16x16x32_bf16 v[34:37], v[176:179], v[192:195], v[34:37]
	v_mfma_f32_16x16x32_bf16 v[30:33], v[168:171], v[200:203], v[30:33]
	v_mfma_f32_16x16x32_bf16 v[26:29], v[176:179], v[200:203], v[26:29]
	v_mfma_f32_16x16x32_bf16 v[22:25], v[168:171], v[232:235], v[22:25]
	v_mfma_f32_16x16x32_bf16 v[18:21], v[176:179], v[232:235], v[18:21]
	s_barrier
	s_add_i32 m0, s1, 0x1bf80
	s_nop 0
	global_load_lds_dwordx4 v218, vcc offset:128
	s_add_i32 m0, s1, 0x1df80
	s_nop 0
	global_load_lds_dwordx4 v219, vcc offset:128
	s_waitcnt vmcnt(6)
	s_barrier
	v_mfma_f32_16x16x32_bf16 v[14:17], v[236:239], v[180:183], v[14:17]
	v_mfma_f32_16x16x32_bf16 v[10:13], v[244:247], v[180:183], v[10:13]
	v_mfma_f32_16x16x32_bf16 v[6:9], v[236:239], v[188:191], v[6:9]
	v_mfma_f32_16x16x32_bf16 v[2:5], v[244:247], v[188:191], v[2:5]
	v_mfma_f32_16x16x32_bf16 v[66:69], v[236:239], v[196:199], v[66:69]
	v_mfma_f32_16x16x32_bf16 v[74:77], v[244:247], v[196:199], v[74:77]
	v_mfma_f32_16x16x32_bf16 v[78:81], v[236:239], v[222:225], v[78:81]
	v_mfma_f32_16x16x32_bf16 v[82:85], v[244:247], v[222:225], v[82:85]
	v_mfma_f32_16x16x32_bf16 v[14:17], v[240:243], v[184:187], v[14:17]
	v_mfma_f32_16x16x32_bf16 v[10:13], v[248:251], v[184:187], v[10:13]
	v_mfma_f32_16x16x32_bf16 v[6:9], v[240:243], v[192:195], v[6:9]
	v_mfma_f32_16x16x32_bf16 v[2:5], v[248:251], v[192:195], v[2:5]
	v_mfma_f32_16x16x32_bf16 v[66:69], v[240:243], v[200:203], v[66:69]
	v_mfma_f32_16x16x32_bf16 v[74:77], v[248:251], v[200:203], v[74:77]
	v_mfma_f32_16x16x32_bf16 v[78:81], v[240:243], v[232:235], v[78:81]
	v_mfma_f32_16x16x32_bf16 v[82:85], v[248:251], v[232:235], v[82:85]
	s_add_i32 s0, s0, 2
	s_add_u32 s12, s12, 0x100
	s_addc_u32 s13, s13, 0
	s_add_u32 s98, s98, 0x100
	s_addc_u32 s99, s99, 0
	s_add_u32 vcc_lo, vcc_lo, 0x100
	s_addc_u32 vcc_hi, vcc_hi, 0
	s_cmp_lt_u32 s0, 28
	s_barrier
	s_cbranch_scc1 .LBB0_34
	s_add_i32 s1, s1, 0x1e000
	s_mov_b64 s[12:13], 0xf80
	v_readfirstlane_b32 s0, v162
	v_lshl_add_u64 v[132:133], v[132:133], 0, s[12:13]
	s_mov_b32 m0, s0
	v_readfirstlane_b32 s0, v163
	ds_read_b128 v[134:137], v151
	ds_read_b128 v[138:141], v151 offset:1024
	ds_read_b128 v[152:155], v151 offset:2048
	ds_read_b128 v[156:159], v151 offset:3072
	ds_read_b128 v[164:167], v0
	ds_read_b128 v[168:171], v0 offset:1024
	ds_read_b128 v[172:175], v0 offset:2048
	ds_read_b128 v[176:179], v0 offset:3072
	ds_read_b128 v[180:183], v0 offset:4096
	ds_read_b128 v[184:187], v0 offset:5120
	ds_read_b128 v[188:191], v0 offset:6144
	ds_read_b128 v[192:195], v0 offset:7168
	global_load_lds_dwordx4 v[132:133], off
	v_lshl_add_u64 v[130:131], v[130:131], 0, s[12:13]
	s_mov_b32 m0, s0
	s_nop 0
	global_load_lds_dwordx4 v[130:131], off
	s_barrier
	s_waitcnt lgkmcnt(0)
	s_setprio 1
	s_waitcnt lgkmcnt(0)
	v_mfma_f32_16x16x32_bf16 v[122:125], v[152:155], v[164:167], v[122:125]
	v_mfma_f32_16x16x32_bf16 v[118:121], v[134:137], v[172:175], v[118:121]
	v_mfma_f32_16x16x32_bf16 v[114:117], v[152:155], v[172:175], v[114:117]
	v_mfma_f32_16x16x32_bf16 v[102:105], v[134:137], v[188:191], v[102:105]
	v_mfma_f32_16x16x32_bf16 v[98:101], v[152:155], v[188:191], v[98:101]
	v_mfma_f32_16x16x32_bf16 v[126:129], v[134:137], v[164:167], v[126:129]
	v_mfma_f32_16x16x32_bf16 v[122:125], v[156:159], v[168:171], v[122:125]
	v_mfma_f32_16x16x32_bf16 v[118:121], v[138:141], v[176:179], v[118:121]
	v_mfma_f32_16x16x32_bf16 v[114:117], v[156:159], v[176:179], v[114:117]
	v_mfma_f32_16x16x32_bf16 v[110:113], v[134:137], v[180:183], v[110:113]
	v_mfma_f32_16x16x32_bf16 v[106:109], v[152:155], v[180:183], v[106:109]
	v_mfma_f32_16x16x32_bf16 v[102:105], v[138:141], v[192:195], v[102:105]
	v_mfma_f32_16x16x32_bf16 v[98:101], v[156:159], v[192:195], v[98:101]
	v_mfma_f32_16x16x32_bf16 v[126:129], v[138:141], v[168:171], v[126:129]
	v_mfma_f32_16x16x32_bf16 v[130:133], v[138:141], v[184:187], v[110:113]
	v_mfma_f32_16x16x32_bf16 v[160:163], v[156:159], v[184:187], v[106:109]
	s_setprio 0
	s_barrier
	ds_read_b128 v[106:109], v151 offset:16384
	ds_read_b128 v[110:113], v151 offset:17408
	ds_read_b128 v[196:199], v151 offset:18432
	ds_read_b128 v[200:203], v151 offset:19456
	s_barrier
	s_waitcnt lgkmcnt(0)
	s_setprio 1
	s_waitcnt lgkmcnt(3)
	v_mfma_f32_16x16x32_bf16 v[86:89], v[106:109], v[172:175], v[86:89]
	s_waitcnt lgkmcnt(1)
	v_mfma_f32_16x16x32_bf16 v[70:73], v[196:199], v[172:175], v[70:73]
	v_mfma_f32_16x16x32_bf16 v[62:65], v[106:109], v[180:183], v[62:65]
	v_mfma_f32_16x16x32_bf16 v[58:61], v[196:199], v[180:183], v[58:61]
	v_mfma_f32_16x16x32_bf16 v[54:57], v[106:109], v[188:191], v[54:57]
	v_mfma_f32_16x16x32_bf16 v[50:53], v[196:199], v[188:191], v[50:53]
	v_mfma_f32_16x16x32_bf16 v[94:97], v[106:109], v[164:167], v[94:97]
	v_mfma_f32_16x16x32_bf16 v[90:93], v[196:199], v[164:167], v[90:93]
	v_mfma_f32_16x16x32_bf16 v[86:89], v[110:113], v[176:179], v[86:89]
	s_waitcnt lgkmcnt(0)
	v_mfma_f32_16x16x32_bf16 v[70:73], v[200:203], v[176:179], v[70:73]
	v_mfma_f32_16x16x32_bf16 v[62:65], v[110:113], v[184:187], v[62:65]
	v_mfma_f32_16x16x32_bf16 v[58:61], v[200:203], v[184:187], v[58:61]
	v_mfma_f32_16x16x32_bf16 v[54:57], v[110:113], v[192:195], v[54:57]
	v_mfma_f32_16x16x32_bf16 v[50:53], v[200:203], v[192:195], v[50:53]
	v_mfma_f32_16x16x32_bf16 v[222:225], v[110:113], v[168:171], v[94:97]
	v_mfma_f32_16x16x32_bf16 v[164:167], v[200:203], v[168:171], v[90:93]
	s_setprio 0
	s_barrier
	s_nop 0
	ds_read_b128 v[90:93], v0 offset:16384
	ds_read_b128 v[94:97], v0 offset:17408
	ds_read_b128 v[168:171], v0 offset:18432
	ds_read_b128 v[172:175], v0 offset:19456
	ds_read_b128 v[176:179], v0 offset:20480
	ds_read_b128 v[180:183], v0 offset:21504
	ds_read_b128 v[184:187], v0 offset:22528
	ds_read_b128 v[188:191], v0 offset:23552
	s_waitcnt vmcnt(4)
	s_barrier
	s_waitcnt lgkmcnt(0)
	s_setprio 1
	s_waitcnt lgkmcnt(7)
	v_mfma_f32_16x16x32_bf16 v[46:49], v[134:137], v[90:93], v[46:49]
	v_mfma_f32_16x16x32_bf16 v[42:45], v[152:155], v[90:93], v[42:45]
	s_waitcnt lgkmcnt(5)
	v_mfma_f32_16x16x32_bf16 v[38:41], v[134:137], v[168:171], v[38:41]
	v_mfma_f32_16x16x32_bf16 v[34:37], v[152:155], v[168:171], v[34:37]
	s_waitcnt lgkmcnt(3)
	v_mfma_f32_16x16x32_bf16 v[30:33], v[134:137], v[176:179], v[30:33]
	v_mfma_f32_16x16x32_bf16 v[26:29], v[152:155], v[176:179], v[26:29]
	s_waitcnt lgkmcnt(1)
	v_mfma_f32_16x16x32_bf16 v[22:25], v[134:137], v[184:187], v[22:25]
	v_mfma_f32_16x16x32_bf16 v[18:21], v[152:155], v[184:187], v[18:21]
	v_mfma_f32_16x16x32_bf16 v[46:49], v[138:141], v[94:97], v[46:49]
	v_mfma_f32_16x16x32_bf16 v[42:45], v[156:159], v[94:97], v[42:45]
	v_mfma_f32_16x16x32_bf16 v[38:41], v[138:141], v[172:175], v[38:41]
	v_mfma_f32_16x16x32_bf16 v[34:37], v[156:159], v[172:175], v[34:37]
	v_mfma_f32_16x16x32_bf16 v[30:33], v[138:141], v[180:183], v[30:33]
	v_mfma_f32_16x16x32_bf16 v[26:29], v[156:159], v[180:183], v[26:29]
	s_waitcnt lgkmcnt(0)
	v_mfma_f32_16x16x32_bf16 v[22:25], v[138:141], v[188:191], v[22:25]
	v_mfma_f32_16x16x32_bf16 v[18:21], v[156:159], v[188:191], v[18:21]
	s_setprio 0
	s_setprio 1
	v_mfma_f32_16x16x32_bf16 v[10:13], v[196:199], v[90:93], v[10:13]
	v_mfma_f32_16x16x32_bf16 v[152:155], v[200:203], v[94:97], v[10:13]
	v_mfma_f32_16x16x32_bf16 v[10:13], v[106:109], v[176:179], v[66:69]
	v_mfma_f32_16x16x32_bf16 v[156:159], v[110:113], v[180:183], v[10:13]
	v_mfma_f32_16x16x32_bf16 v[10:13], v[196:199], v[176:179], v[74:77]
	v_mfma_f32_16x16x32_bf16 v[6:9], v[106:109], v[168:171], v[6:9]
	v_mfma_f32_16x16x32_bf16 v[2:5], v[196:199], v[168:171], v[2:5]
	v_mfma_f32_16x16x32_bf16 v[168:171], v[200:203], v[180:183], v[10:13]
	v_mfma_f32_16x16x32_bf16 v[10:13], v[106:109], v[184:187], v[78:81]
	v_mfma_f32_16x16x32_bf16 v[14:17], v[106:109], v[90:93], v[14:17]
	v_mfma_f32_16x16x32_bf16 v[6:9], v[110:113], v[172:175], v[6:9]
	v_mfma_f32_16x16x32_bf16 v[2:5], v[200:203], v[172:175], v[2:5]
	v_mfma_f32_16x16x32_bf16 v[172:175], v[110:113], v[188:191], v[10:13]
	v_mfma_f32_16x16x32_bf16 v[10:13], v[196:199], v[184:187], v[82:85]
	v_mfma_f32_16x16x32_bf16 v[134:137], v[110:113], v[94:97], v[14:17]
	v_mfma_f32_16x16x32_bf16 v[176:179], v[200:203], v[188:191], v[10:13]
	s_setprio 0
	s_barrier
	s_nop 3
	ds_read_b128 v[10:13], v151 offset:32768
	ds_read_b128 v[14:17], v151 offset:33792
	ds_read_b128 v[180:183], v151 offset:34816
	ds_read_b128 v[184:187], v151 offset:35840
	ds_read_b128 v[66:69], v0 offset:32768
	ds_read_b128 v[82:85], v0 offset:33792
	ds_read_b128 v[188:191], v0 offset:34816
	ds_read_b128 v[192:195], v0 offset:35840
	ds_read_b128 v[196:199], v0 offset:36864
	ds_read_b128 v[200:203], v0 offset:37888
	ds_read_b128 v[232:235], v0 offset:38912
	ds_read_b128 v[236:239], v0 offset:39936
	s_waitcnt vmcnt(2)
	s_barrier
	s_waitcnt lgkmcnt(0)
	s_setprio 1
	s_waitcnt lgkmcnt(7)
	v_mfma_f32_16x16x32_bf16 v[74:77], v[10:13], v[66:69], v[126:129]
	s_waitcnt lgkmcnt(6)
	v_mfma_f32_16x16x32_bf16 v[138:141], v[14:17], v[82:85], v[74:77]
	v_mfma_f32_16x16x32_bf16 v[74:77], v[180:183], v[66:69], v[122:125]
	v_mfma_f32_16x16x32_bf16 v[122:125], v[184:187], v[82:85], v[74:77]
	s_waitcnt lgkmcnt(5)
	v_mfma_f32_16x16x32_bf16 v[74:77], v[10:13], v[188:191], v[118:121]
	s_waitcnt lgkmcnt(4)
	v_mfma_f32_16x16x32_bf16 v[110:113], v[14:17], v[192:195], v[74:77]
	v_mfma_f32_16x16x32_bf16 v[74:77], v[180:183], v[188:191], v[114:117]
	v_mfma_f32_16x16x32_bf16 v[106:109], v[184:187], v[192:195], v[74:77]
	s_waitcnt lgkmcnt(3)
	v_mfma_f32_16x16x32_bf16 v[74:77], v[10:13], v[196:199], v[130:133]
	s_waitcnt lgkmcnt(2)
	v_mfma_f32_16x16x32_bf16 v[94:97], v[14:17], v[200:203], v[74:77]
	v_mfma_f32_16x16x32_bf16 v[74:77], v[180:183], v[196:199], v[160:163]
	v_mfma_f32_16x16x32_bf16 v[90:93], v[184:187], v[200:203], v[74:77]
	s_waitcnt lgkmcnt(1)
	v_mfma_f32_16x16x32_bf16 v[74:77], v[10:13], v[232:235], v[102:105]
	s_waitcnt lgkmcnt(0)
	v_mfma_f32_16x16x32_bf16 v[78:81], v[14:17], v[236:239], v[74:77]
	v_mfma_f32_16x16x32_bf16 v[74:77], v[180:183], v[232:235], v[98:101]
	v_mfma_f32_16x16x32_bf16 v[74:77], v[184:187], v[236:239], v[74:77]
	s_setprio 0
	s_barrier
	ds_read_b128 v[126:129], v151 offset:49152
	ds_read_b128 v[130:133], v151 offset:50176
	ds_read_b128 v[160:163], v151 offset:51200
	ds_read_b128 v[148:151], v151 offset:52224
	s_waitcnt vmcnt(0)
	s_barrier
	s_waitcnt lgkmcnt(0)
	s_setprio 1
	s_waitcnt lgkmcnt(3)
	v_mfma_f32_16x16x32_bf16 v[98:101], v[126:129], v[66:69], v[222:225]
	s_waitcnt lgkmcnt(1)
	v_mfma_f32_16x16x32_bf16 v[66:69], v[160:163], v[66:69], v[164:167]
	s_waitcnt lgkmcnt(0)
	v_mfma_f32_16x16x32_bf16 v[114:117], v[148:151], v[82:85], v[66:69]
	v_mfma_f32_16x16x32_bf16 v[66:69], v[126:129], v[188:191], v[86:89]
	v_mfma_f32_16x16x32_bf16 v[102:105], v[130:133], v[192:195], v[66:69]
	v_mfma_f32_16x16x32_bf16 v[66:69], v[160:163], v[188:191], v[70:73]
	v_mfma_f32_16x16x32_bf16 v[62:65], v[126:129], v[196:199], v[62:65]
	v_mfma_f32_16x16x32_bf16 v[58:61], v[160:163], v[196:199], v[58:61]
	v_mfma_f32_16x16x32_bf16 v[54:57], v[126:129], v[232:235], v[54:57]
	v_mfma_f32_16x16x32_bf16 v[50:53], v[160:163], v[232:235], v[50:53]
	v_mfma_f32_16x16x32_bf16 v[118:121], v[130:133], v[82:85], v[98:101]
	v_mfma_f32_16x16x32_bf16 v[98:101], v[148:151], v[192:195], v[66:69]
	v_mfma_f32_16x16x32_bf16 v[86:89], v[130:133], v[200:203], v[62:65]
	v_mfma_f32_16x16x32_bf16 v[82:85], v[148:151], v[200:203], v[58:61]
	v_mfma_f32_16x16x32_bf16 v[70:73], v[130:133], v[236:239], v[54:57]
	v_mfma_f32_16x16x32_bf16 v[66:69], v[148:151], v[236:239], v[50:53]
	s_setprio 0
	s_barrier
	s_nop 0
	ds_read_b128 v[50:53], v0 offset:49152
	ds_read_b128 v[164:167], v0 offset:50176
	ds_read_b128 v[188:191], v0 offset:51200
	ds_read_b128 v[192:195], v0 offset:52224
	ds_read_b128 v[196:199], v0 offset:53248
	ds_read_b128 v[200:203], v0 offset:54272
	ds_read_b128 v[222:225], v0 offset:55296
	ds_read_b128 v[232:235], v0 offset:56320
	s_barrier
	s_waitcnt lgkmcnt(0)
	s_setprio 1
	s_waitcnt lgkmcnt(7)
	v_mfma_f32_16x16x32_bf16 v[46:49], v[10:13], v[50:53], v[46:49]
	s_waitcnt lgkmcnt(5)
	v_mfma_f32_16x16x32_bf16 v[38:41], v[10:13], v[188:191], v[38:41]
	s_waitcnt lgkmcnt(3)
	v_mfma_f32_16x16x32_bf16 v[30:33], v[10:13], v[196:199], v[30:33]
	s_waitcnt lgkmcnt(1)
	v_mfma_f32_16x16x32_bf16 v[10:13], v[10:13], v[222:225], v[22:25]
	v_mfma_f32_16x16x32_bf16 v[62:65], v[14:17], v[164:167], v[46:49]
	v_mfma_f32_16x16x32_bf16 v[42:45], v[180:183], v[50:53], v[42:45]
	v_mfma_f32_16x16x32_bf16 v[46:49], v[14:17], v[192:195], v[38:41]
	v_mfma_f32_16x16x32_bf16 v[34:37], v[180:183], v[188:191], v[34:37]
	v_mfma_f32_16x16x32_bf16 v[30:33], v[14:17], v[200:203], v[30:33]
	v_mfma_f32_16x16x32_bf16 v[26:29], v[180:183], v[196:199], v[26:29]
	s_waitcnt lgkmcnt(0)
	v_mfma_f32_16x16x32_bf16 v[14:17], v[14:17], v[232:235], v[10:13]
	v_mfma_f32_16x16x32_bf16 v[10:13], v[180:183], v[222:225], v[18:21]
	v_mfma_f32_16x16x32_bf16 v[58:61], v[184:187], v[164:167], v[42:45]
	v_mfma_f32_16x16x32_bf16 v[42:45], v[184:187], v[192:195], v[34:37]
	v_mfma_f32_16x16x32_bf16 v[26:29], v[184:187], v[200:203], v[26:29]
	v_mfma_f32_16x16x32_bf16 v[10:13], v[184:187], v[232:235], v[10:13]
	s_setprio 0
	s_setprio 1
	v_mfma_f32_16x16x32_bf16 v[2:5], v[160:163], v[188:191], v[2:5]
	v_mfma_f32_16x16x32_bf16 v[18:21], v[126:129], v[50:53], v[134:137]
	v_mfma_f32_16x16x32_bf16 v[34:37], v[148:151], v[192:195], v[2:5]
	v_mfma_f32_16x16x32_bf16 v[2:5], v[126:129], v[196:199], v[156:159]
	v_mfma_f32_16x16x32_bf16 v[54:57], v[130:133], v[164:167], v[18:21]
	v_mfma_f32_16x16x32_bf16 v[18:21], v[160:163], v[50:53], v[152:155]
	v_mfma_f32_16x16x32_bf16 v[22:25], v[130:133], v[200:203], v[2:5]
	v_mfma_f32_16x16x32_bf16 v[2:5], v[160:163], v[196:199], v[168:171]
	v_mfma_f32_16x16x32_bf16 v[50:53], v[148:151], v[164:167], v[18:21]
	v_mfma_f32_16x16x32_bf16 v[6:9], v[126:129], v[188:191], v[6:9]
	v_mfma_f32_16x16x32_bf16 v[18:21], v[148:151], v[200:203], v[2:5]
	v_mfma_f32_16x16x32_bf16 v[2:5], v[126:129], v[222:225], v[172:175]
	v_mfma_f32_16x16x32_bf16 v[38:41], v[130:133], v[192:195], v[6:9]
	v_mfma_f32_16x16x32_bf16 v[6:9], v[130:133], v[232:235], v[2:5]
	v_mfma_f32_16x16x32_bf16 v[2:5], v[160:163], v[222:225], v[176:179]
	v_mfma_f32_16x16x32_bf16 v[2:5], v[148:151], v[232:235], v[2:5]
	s_setprio 0
	s_movk_i32 s0, 0x100
	v_cmp_gt_u32_e32 vcc, s0, v142
	s_barrier
	s_and_saveexec_b64 s[0:1], vcc
	s_cbranch_execz .LBB0_37
	s_barrier

.LBB0_84:
	s_or_b64 exec, exec, s[52:53]
	v_mov_b32_e32 v3, v1
	v_lshl_add_u64 v[12:13], s[0:1], 0, v[2:3]
	v_lshl_add_u64 v[16:17], s[12:13], 0, v[2:3]
	v_lshl_add_u64 v[20:21], s[14:15], 0, v[2:3]
	v_lshl_add_u64 v[130:131], s[16:17], 0, v[2:3]
	v_and_b32_e32 v146, 15, v142
	v_bfe_u32 v145, v142, 4, 2
	v_lshlrev_b32_e32 v3, 2, v142
	v_add_u32_e32 v156, 0x18000, v147
	v_lshl_add_u64 v[10:11], s[0:1], 0, v[0:1]
	v_lshl_add_u64 v[14:15], s[12:13], 0, v[0:1]
	v_lshl_add_u64 v[18:19], s[14:15], 0, v[0:1]
	v_lshl_add_u64 v[132:133], s[16:17], 0, v[0:1]
	v_lshlrev_b32_e32 v0, 6, v146
	v_lshlrev_b32_e32 v2, 4, v145
	v_and_b32_e32 v3, 32, v3
	s_mov_b64 s[12:13], 0x80
	v_readfirstlane_b32 s0, v156
	v_add_u32_e32 v157, 0x1a000, v147
	v_bitop3_b32 v22, v2, v3, v0 bitop3:0x36
	v_lshl_add_u64 v[2:3], v[10:11], 0, s[12:13]
	s_mov_b32 m0, s0
	v_readfirstlane_b32 s0, v157
	v_add_u32_e32 v158, 0x8000, v147
	s_waitcnt vmcnt(4)
	s_barrier
	global_load_lds_dwordx4 v[2:3], off
	v_lshl_add_u64 v[2:3], v[12:13], 0, s[12:13]
	s_mov_b32 m0, s0
	v_readfirstlane_b32 s0, v158
	v_add_u32_e32 v159, 0xa000, v147
	global_load_lds_dwordx4 v[2:3], off
	v_lshl_add_u64 v[2:3], v[14:15], 0, s[12:13]
	s_mov_b32 m0, s0
	v_readfirstlane_b32 s0, v159
	v_add_u32_e32 v160, 0x1c000, v147
	global_load_lds_dwordx4 v[2:3], off
	v_lshl_add_u64 v[2:3], v[16:17], 0, s[12:13]
	s_mov_b32 m0, s0
	v_readfirstlane_b32 s0, v160
	v_add_u32_e32 v161, 0x1e000, v147
	global_load_lds_dwordx4 v[2:3], off
	v_lshl_add_u64 v[2:3], v[18:19], 0, s[12:13]
	s_mov_b32 m0, s0
	v_readfirstlane_b32 s0, v161
	global_load_lds_dwordx4 v[2:3], off
	v_lshl_add_u64 v[2:3], v[20:21], 0, s[12:13]
	s_mov_b32 m0, s0
	s_sub_i32 s1, s57, s64
	global_load_lds_dwordx4 v[2:3], off
	s_sub_i32 s1, s1, s63
	v_lshlrev_b32_e32 v0, 15, v4
	s_sext_i32_i16 s1, s1
	v_and_b32_e32 v0, 0xffff0000, v0
	s_lshl_b32 s0, s62, 10
	s_lshl_b32 s1, s1, 8
	v_lshl_add_u32 v0, v5, 12, v0
	v_and_b32_e32 v2, 1, v4
	s_add_i32 s0, s0, s1
	v_lshl_or_b32 v0, v2, 6, v0
	v_lshlrev_b32_e32 v2, 15, v6
	s_ashr_i32 s1, s0, 31
	v_and_b32_e32 v2, 0xffff0000, v2
	s_lshl_b64 s[0:1], s[0:1], 12
	v_lshl_add_u32 v2, v8, 12, v2
	v_and_b32_e32 v3, 1, v6
	s_add_u32 s0, s4, s0
	v_lshl_or_b32 v2, v3, 6, v2
	v_lshl_add_u32 v0, v7, 1, v0
	s_addc_u32 s1, s5, s1
	v_lshl_add_u32 v2, v9, 1, v2
	v_mov_b32_e32 v3, v1
	s_waitcnt vmcnt(6)
	v_lshl_add_u64 v[134:135], s[0:1], 0, v[0:1]
	v_lshl_add_u64 v[136:137], s[0:1], 0, v[2:3]
	s_add_u32 s0, s88, s10
	v_bfe_u32 v144, v142, 6, 2
	s_addc_u32 s1, s89, s11
	v_lshlrev_b32_e32 v23, 13, v143
	v_lshl_or_b32 v24, v144, 12, v212
	v_lshl_add_u64 v[140:141], s[0:1], 0, v[2:3]
	v_mov_b32_e32 v2, 0
	s_barrier
	v_lshl_add_u64 v[138:139], s[0:1], 0, v[0:1]
	s_mov_b32 s0, -2
	s_mov_b64 s[10:11], 0
	v_add_u32_e32 v151, v24, v22
	v_add_u32_e32 v0, v23, v22
	v_mov_b32_e32 v3, v2
	v_mov_b32_e32 v4, v2
	v_mov_b32_e32 v5, v2
	v_mov_b32_e32 v6, v2
	v_mov_b32_e32 v7, v2
	v_mov_b32_e32 v8, v2
	v_mov_b32_e32 v9, v2
	v_mov_b32_e32 v10, v2
	v_mov_b32_e32 v11, v2
	v_mov_b32_e32 v12, v2
	v_mov_b32_e32 v13, v2
	v_mov_b32_e32 v14, v2
	v_mov_b32_e32 v15, v2
	v_mov_b32_e32 v16, v2
	v_mov_b32_e32 v17, v2
	v_mov_b32_e32 v18, v2
	v_mov_b32_e32 v19, v2
	v_mov_b32_e32 v20, v2
	v_mov_b32_e32 v21, v2
	v_mov_b32_e32 v22, v2
	v_mov_b32_e32 v23, v2
	v_mov_b32_e32 v24, v2
	v_mov_b32_e32 v25, v2
	v_mov_b32_e32 v26, v2
	v_mov_b32_e32 v27, v2
	v_mov_b32_e32 v28, v2
	v_mov_b32_e32 v29, v2
	v_mov_b32_e32 v30, v2
	v_mov_b32_e32 v31, v2
	v_mov_b32_e32 v32, v2
	v_mov_b32_e32 v33, v2
	v_mov_b32_e32 v34, v2
	v_mov_b32_e32 v35, v2
	v_mov_b32_e32 v36, v2
	v_mov_b32_e32 v37, v2
	v_mov_b32_e32 v38, v2
	v_mov_b32_e32 v39, v2
	v_mov_b32_e32 v40, v2
	v_mov_b32_e32 v41, v2
	v_mov_b32_e32 v42, v2
	v_mov_b32_e32 v43, v2
	v_mov_b32_e32 v44, v2
	v_mov_b32_e32 v45, v2
	v_mov_b32_e32 v46, v2
	v_mov_b32_e32 v47, v2
	v_mov_b32_e32 v48, v2
	v_mov_b32_e32 v49, v2
	v_mov_b32_e32 v50, v2
	v_mov_b32_e32 v51, v2
	v_mov_b32_e32 v52, v2
	v_mov_b32_e32 v53, v2
	v_mov_b32_e32 v54, v2
	v_mov_b32_e32 v55, v2
	v_mov_b32_e32 v56, v2
	v_mov_b32_e32 v57, v2
	v_mov_b32_e32 v58, v2
	v_mov_b32_e32 v59, v2
	v_mov_b32_e32 v60, v2
	v_mov_b32_e32 v61, v2
	v_mov_b32_e32 v62, v2
	v_mov_b32_e32 v63, v2
	v_mov_b32_e32 v64, v2
	v_mov_b32_e32 v65, v2
	v_mov_b32_e32 v66, v2
	v_mov_b32_e32 v67, v2
	v_mov_b32_e32 v68, v2
	v_mov_b32_e32 v69, v2
	v_mov_b32_e32 v70, v2
	v_mov_b32_e32 v71, v2
	v_mov_b32_e32 v72, v2
	v_mov_b32_e32 v73, v2
	v_mov_b32_e32 v74, v2
	v_mov_b32_e32 v75, v2
	v_mov_b32_e32 v76, v2
	v_mov_b32_e32 v77, v2
	v_mov_b32_e32 v78, v2
	v_mov_b32_e32 v79, v2
	v_mov_b32_e32 v80, v2
	v_mov_b32_e32 v81, v2
	v_mov_b32_e32 v82, v2
	v_mov_b32_e32 v83, v2
	v_mov_b32_e32 v84, v2
	v_mov_b32_e32 v85, v2
	v_mov_b32_e32 v86, v2
	v_mov_b32_e32 v87, v2
	v_mov_b32_e32 v88, v2
	v_mov_b32_e32 v89, v2
	v_mov_b32_e32 v90, v2
	v_mov_b32_e32 v91, v2
	v_mov_b32_e32 v92, v2
	v_mov_b32_e32 v93, v2
	v_mov_b32_e32 v94, v2
	v_mov_b32_e32 v95, v2
	v_mov_b32_e32 v96, v2
	v_mov_b32_e32 v97, v2
	v_mov_b32_e32 v98, v2
	v_mov_b32_e32 v99, v2
	v_mov_b32_e32 v100, v2
	v_mov_b32_e32 v101, v2
	v_mov_b32_e32 v102, v2
	v_mov_b32_e32 v103, v2
	v_mov_b32_e32 v104, v2
	v_mov_b32_e32 v105, v2
	v_mov_b32_e32 v106, v2
	v_mov_b32_e32 v107, v2
	v_mov_b32_e32 v108, v2
	v_mov_b32_e32 v109, v2
	v_mov_b32_e32 v110, v2
	v_mov_b32_e32 v111, v2
	v_mov_b32_e32 v112, v2
	v_mov_b32_e32 v113, v2
	v_mov_b32_e32 v114, v2
	v_mov_b32_e32 v115, v2
	v_mov_b32_e32 v116, v2
	v_mov_b32_e32 v117, v2
	v_mov_b32_e32 v118, v2
	v_mov_b32_e32 v119, v2
	v_mov_b32_e32 v120, v2
	v_mov_b32_e32 v121, v2
	v_mov_b32_e32 v122, v2
	v_mov_b32_e32 v123, v2
	v_mov_b32_e32 v124, v2
	v_mov_b32_e32 v125, v2
	v_mov_b32_e32 v126, v2
	v_mov_b32_e32 v127, v2
	v_mov_b32_e32 v128, v2
	v_mov_b32_e32 v129, v2
	v_add_u32_e32 v162, 0xc000, v147
	v_add_u32_e32 v163, 0xe000, v147
	v_readfirstlane_b32 s1, v147
	s_nop 1
	v_readfirstlane_b32 s98, v138
	v_readfirstlane_b32 s99, v139
	s_nop 3
	s_sub_u32 s98, s98, 0x400000
	s_subb_u32 s99, s99, 0
	v_subrev_u32_e32 v204, s98, v138
	v_add_u32_e32 v216, 0x80080, v204
	v_subrev_u32_e32 v205, s98, v140
	v_add_u32_e32 v217, 0x80080, v205
	v_readfirstlane_b32 vcc_lo, v134
	v_readfirstlane_b32 vcc_hi, v135
	s_nop 3
	s_sub_u32 vcc_lo, vcc_lo, 0x400000
	s_subb_u32 vcc_hi, vcc_hi, 0
	v_subrev_u32_e32 v210, vcc_lo, v134
	v_add_u32_e32 v218, 0x80100, v210
	v_subrev_u32_e32 v211, vcc_lo, v136
	v_add_u32_e32 v219, 0x80100, v211
	v_add_u32_e32 v228, 0x100, v204
	s_add_u32 s98, s98, s10
	s_addc_u32 s99, s99, s11
	s_add_u32 vcc_lo, vcc_lo, s10
	s_addc_u32 vcc_hi, vcc_hi, s11
	s_nop 4
.LBB0_85:
	ds_read_b128 v[164:167], v151
	ds_read_b128 v[168:171], v151 offset:1024
	ds_read_b128 v[172:175], v151 offset:2048
	ds_read_b128 v[176:179], v151 offset:3072
	s_add_i32 m0, s1, 0xc000
	ds_read_b128 v[180:183], v0
	ds_read_b128 v[184:187], v0 offset:1024
	ds_read_b128 v[188:191], v0 offset:2048
	ds_read_b128 v[192:195], v0 offset:3072
	ds_read_b128 v[196:199], v0 offset:4096
	ds_read_b128 v[200:203], v0 offset:5120
	ds_read_b128 v[222:225], v0 offset:6144
	ds_read_b128 v[232:235], v0 offset:7168
	global_load_lds_dwordx4 v216, s[98:99]
	s_add_i32 m0, s1, 0xe000
	s_nop 0
	global_load_lds_dwordx4 v217, s[98:99]
	s_waitcnt lgkmcnt(8)
	s_barrier
	s_waitcnt lgkmcnt(0)
	v_mfma_f32_16x16x32_bf16 v[126:129], v[164:167], v[180:183], v[126:129]
	v_mfma_f32_16x16x32_bf16 v[122:125], v[172:175], v[180:183], v[122:125]
	v_mfma_f32_16x16x32_bf16 v[118:121], v[164:167], v[188:191], v[118:121]
	v_mfma_f32_16x16x32_bf16 v[114:117], v[172:175], v[188:191], v[114:117]
	v_mfma_f32_16x16x32_bf16 v[110:113], v[164:167], v[196:199], v[110:113]
	v_mfma_f32_16x16x32_bf16 v[106:109], v[172:175], v[196:199], v[106:109]
	v_mfma_f32_16x16x32_bf16 v[102:105], v[164:167], v[222:225], v[102:105]
	v_mfma_f32_16x16x32_bf16 v[98:101], v[172:175], v[222:225], v[98:101]
	v_mfma_f32_16x16x32_bf16 v[126:129], v[168:171], v[184:187], v[126:129]
	v_mfma_f32_16x16x32_bf16 v[122:125], v[176:179], v[184:187], v[122:125]
	v_mfma_f32_16x16x32_bf16 v[118:121], v[168:171], v[192:195], v[118:121]
	v_mfma_f32_16x16x32_bf16 v[114:117], v[176:179], v[192:195], v[114:117]
	v_mfma_f32_16x16x32_bf16 v[110:113], v[168:171], v[200:203], v[110:113]
	v_mfma_f32_16x16x32_bf16 v[106:109], v[176:179], v[200:203], v[106:109]
	v_mfma_f32_16x16x32_bf16 v[102:105], v[168:171], v[232:235], v[102:105]
	v_mfma_f32_16x16x32_bf16 v[98:101], v[176:179], v[232:235], v[98:101]
	s_barrier
	s_add_i32 m0, s1, 0xff00
	ds_read_b128 v[236:239], v151 offset:16384
	ds_read_b128 v[240:243], v151 offset:17408
	ds_read_b128 v[244:247], v151 offset:18432
	ds_read_b128 v[248:251], v151 offset:19456
	global_load_lds_dwordx4 v210, vcc offset:256
	s_add_i32 m0, s1, 0x11f00
	s_nop 0
	global_load_lds_dwordx4 v211, vcc offset:256
	s_barrier
	s_waitcnt lgkmcnt(0)
	v_mfma_f32_16x16x32_bf16 v[94:97], v[236:239], v[180:183], v[94:97]
	v_mfma_f32_16x16x32_bf16 v[90:93], v[244:247], v[180:183], v[90:93]
	v_mfma_f32_16x16x32_bf16 v[86:89], v[236:239], v[188:191], v[86:89]
	v_mfma_f32_16x16x32_bf16 v[82:85], v[244:247], v[188:191], v[82:85]
	v_mfma_f32_16x16x32_bf16 v[78:81], v[236:239], v[196:199], v[78:81]
	v_mfma_f32_16x16x32_bf16 v[74:77], v[244:247], v[196:199], v[74:77]
	v_mfma_f32_16x16x32_bf16 v[70:73], v[236:239], v[222:225], v[70:73]
	v_mfma_f32_16x16x32_bf16 v[66:69], v[244:247], v[222:225], v[66:69]
	v_mfma_f32_16x16x32_bf16 v[94:97], v[240:243], v[184:187], v[94:97]
	v_mfma_f32_16x16x32_bf16 v[90:93], v[248:251], v[184:187], v[90:93]
	v_mfma_f32_16x16x32_bf16 v[86:89], v[240:243], v[192:195], v[86:89]
	v_mfma_f32_16x16x32_bf16 v[82:85], v[248:251], v[192:195], v[82:85]
	v_mfma_f32_16x16x32_bf16 v[78:81], v[240:243], v[200:203], v[78:81]
	v_mfma_f32_16x16x32_bf16 v[74:77], v[248:251], v[200:203], v[74:77]
	v_mfma_f32_16x16x32_bf16 v[70:73], v[240:243], v[232:235], v[70:73]
	v_mfma_f32_16x16x32_bf16 v[66:69], v[248:251], v[232:235], v[66:69]
	s_mov_b32 m0, s1
	s_barrier
	ds_read_b128 v[180:183], v0 offset:16384
	ds_read_b128 v[184:187], v0 offset:17408
	ds_read_b128 v[188:191], v0 offset:18432
	ds_read_b128 v[192:195], v0 offset:19456
	ds_read_b128 v[196:199], v0 offset:20480
	ds_read_b128 v[200:203], v0 offset:21504
	ds_read_b128 v[222:225], v0 offset:22528
	ds_read_b128 v[232:235], v0 offset:23552
	global_load_lds_dwordx4 v228, s[98:99]
	s_add_i32 m0, s1, 0x1f00
	s_nop 0
	global_load_lds_dwordx4 v205, s[98:99] offset:256
	s_barrier
	s_waitcnt lgkmcnt(0)
	v_mfma_f32_16x16x32_bf16 v[62:65], v[164:167], v[180:183], v[62:65]
	v_mfma_f32_16x16x32_bf16 v[58:61], v[172:175], v[180:183], v[58:61]
	v_mfma_f32_16x16x32_bf16 v[54:57], v[164:167], v[188:191], v[54:57]
	v_mfma_f32_16x16x32_bf16 v[50:53], v[172:175], v[188:191], v[50:53]
	v_mfma_f32_16x16x32_bf16 v[46:49], v[164:167], v[196:199], v[46:49]
	v_mfma_f32_16x16x32_bf16 v[42:45], v[172:175], v[196:199], v[42:45]
	v_mfma_f32_16x16x32_bf16 v[38:41], v[164:167], v[222:225], v[38:41]
	v_mfma_f32_16x16x32_bf16 v[34:37], v[172:175], v[222:225], v[34:37]
	v_mfma_f32_16x16x32_bf16 v[62:65], v[168:171], v[184:187], v[62:65]
	v_mfma_f32_16x16x32_bf16 v[58:61], v[176:179], v[184:187], v[58:61]
	v_mfma_f32_16x16x32_bf16 v[54:57], v[168:171], v[192:195], v[54:57]
	v_mfma_f32_16x16x32_bf16 v[50:53], v[176:179], v[192:195], v[50:53]
	v_mfma_f32_16x16x32_bf16 v[46:49], v[168:171], v[200:203], v[46:49]
	v_mfma_f32_16x16x32_bf16 v[42:45], v[176:179], v[200:203], v[42:45]
	v_mfma_f32_16x16x32_bf16 v[38:41], v[168:171], v[232:235], v[38:41]
	v_mfma_f32_16x16x32_bf16 v[34:37], v[176:179], v[232:235], v[34:37]
	s_barrier
	s_add_i32 m0, s1, 0x14000
	s_nop 0
	global_load_lds_dwordx4 v218, vcc
	s_add_i32 m0, s1, 0x16000
	s_nop 0
	global_load_lds_dwordx4 v219, vcc
	s_waitcnt vmcnt(6)
	s_barrier
	v_mfma_f32_16x16x32_bf16 v[30:33], v[236:239], v[180:183], v[30:33]
	v_mfma_f32_16x16x32_bf16 v[26:29], v[244:247], v[180:183], v[26:29]
	v_mfma_f32_16x16x32_bf16 v[22:25], v[236:239], v[188:191], v[22:25]
	v_mfma_f32_16x16x32_bf16 v[18:21], v[244:247], v[188:191], v[18:21]
	v_mfma_f32_16x16x32_bf16 v[14:17], v[236:239], v[196:199], v[14:17]
	v_mfma_f32_16x16x32_bf16 v[10:13], v[244:247], v[196:199], v[10:13]
	v_mfma_f32_16x16x32_bf16 v[6:9], v[236:239], v[222:225], v[6:9]
	v_mfma_f32_16x16x32_bf16 v[2:5], v[244:247], v[222:225], v[2:5]
	v_mfma_f32_16x16x32_bf16 v[30:33], v[240:243], v[184:187], v[30:33]
	v_mfma_f32_16x16x32_bf16 v[26:29], v[248:251], v[184:187], v[26:29]
	v_mfma_f32_16x16x32_bf16 v[22:25], v[240:243], v[192:195], v[22:25]
	v_mfma_f32_16x16x32_bf16 v[18:21], v[248:251], v[192:195], v[18:21]
	v_mfma_f32_16x16x32_bf16 v[14:17], v[240:243], v[200:203], v[14:17]
	v_mfma_f32_16x16x32_bf16 v[10:13], v[248:251], v[200:203], v[10:13]
	v_mfma_f32_16x16x32_bf16 v[6:9], v[240:243], v[232:235], v[6:9]
	v_mfma_f32_16x16x32_bf16 v[2:5], v[248:251], v[232:235], v[2:5]
	s_barrier
	ds_read_b128 v[164:167], v151 offset:32768
	ds_read_b128 v[168:171], v151 offset:33792
	ds_read_b128 v[172:175], v151 offset:34816
	ds_read_b128 v[176:179], v151 offset:35840
	s_add_i32 m0, s1, 0x3f80
	ds_read_b128 v[180:183], v0 offset:32768
	ds_read_b128 v[184:187], v0 offset:33792
	ds_read_b128 v[188:191], v0 offset:34816
	ds_read_b128 v[192:195], v0 offset:35840
	ds_read_b128 v[196:199], v0 offset:36864
	ds_read_b128 v[200:203], v0 offset:37888
	ds_read_b128 v[222:225], v0 offset:38912
	ds_read_b128 v[232:235], v0 offset:39936
	global_load_lds_dwordx4 v216, s[98:99] offset:128
	s_add_i32 m0, s1, 0x5f80
	s_nop 0
	global_load_lds_dwordx4 v217, s[98:99] offset:128
	s_waitcnt lgkmcnt(8)
	s_barrier
	s_waitcnt lgkmcnt(0)
	v_mfma_f32_16x16x32_bf16 v[126:129], v[164:167], v[180:183], v[126:129]
	v_mfma_f32_16x16x32_bf16 v[122:125], v[172:175], v[180:183], v[122:125]
	v_mfma_f32_16x16x32_bf16 v[118:121], v[164:167], v[188:191], v[118:121]
	v_mfma_f32_16x16x32_bf16 v[114:117], v[172:175], v[188:191], v[114:117]
	v_mfma_f32_16x16x32_bf16 v[110:113], v[164:167], v[196:199], v[110:113]
	v_mfma_f32_16x16x32_bf16 v[106:109], v[172:175], v[196:199], v[106:109]
	v_mfma_f32_16x16x32_bf16 v[102:105], v[164:167], v[222:225], v[102:105]
	v_mfma_f32_16x16x32_bf16 v[98:101], v[172:175], v[222:225], v[98:101]
	v_mfma_f32_16x16x32_bf16 v[126:129], v[168:171], v[184:187], v[126:129]
	v_mfma_f32_16x16x32_bf16 v[122:125], v[176:179], v[184:187], v[122:125]
	v_mfma_f32_16x16x32_bf16 v[118:121], v[168:171], v[192:195], v[118:121]
	v_mfma_f32_16x16x32_bf16 v[114:117], v[176:179], v[192:195], v[114:117]
	v_mfma_f32_16x16x32_bf16 v[110:113], v[168:171], v[200:203], v[110:113]
	v_mfma_f32_16x16x32_bf16 v[106:109], v[176:179], v[200:203], v[106:109]
	v_mfma_f32_16x16x32_bf16 v[102:105], v[168:171], v[232:235], v[102:105]
	v_mfma_f32_16x16x32_bf16 v[98:101], v[176:179], v[232:235], v[98:101]
	s_barrier
	s_add_i32 m0, s1, 0x17e80
	ds_read_b128 v[236:239], v151 offset:49152
	ds_read_b128 v[240:243], v151 offset:50176
	ds_read_b128 v[244:247], v151 offset:51200
	ds_read_b128 v[248:251], v151 offset:52224
	global_load_lds_dwordx4 v210, vcc offset:384
	s_add_i32 m0, s1, 0x19e80
	s_nop 0
	global_load_lds_dwordx4 v211, vcc offset:384
	s_barrier
	s_waitcnt lgkmcnt(0)
	v_mfma_f32_16x16x32_bf16 v[94:97], v[236:239], v[180:183], v[94:97]
	v_mfma_f32_16x16x32_bf16 v[90:93], v[244:247], v[180:183], v[90:93]
	v_mfma_f32_16x16x32_bf16 v[86:89], v[236:239], v[188:191], v[86:89]
	v_mfma_f32_16x16x32_bf16 v[82:85], v[244:247], v[188:191], v[82:85]
	v_mfma_f32_16x16x32_bf16 v[78:81], v[236:239], v[196:199], v[78:81]
	v_mfma_f32_16x16x32_bf16 v[74:77], v[244:247], v[196:199], v[74:77]
	v_mfma_f32_16x16x32_bf16 v[70:73], v[236:239], v[222:225], v[70:73]
	v_mfma_f32_16x16x32_bf16 v[66:69], v[244:247], v[222:225], v[66:69]
	v_mfma_f32_16x16x32_bf16 v[94:97], v[240:243], v[184:187], v[94:97]
	v_mfma_f32_16x16x32_bf16 v[90:93], v[248:251], v[184:187], v[90:93]
	v_mfma_f32_16x16x32_bf16 v[86:89], v[240:243], v[192:195], v[86:89]
	v_mfma_f32_16x16x32_bf16 v[82:85], v[248:251], v[192:195], v[82:85]
	v_mfma_f32_16x16x32_bf16 v[78:81], v[240:243], v[200:203], v[78:81]
	v_mfma_f32_16x16x32_bf16 v[74:77], v[248:251], v[200:203], v[74:77]
	v_mfma_f32_16x16x32_bf16 v[70:73], v[240:243], v[232:235], v[70:73]
	v_mfma_f32_16x16x32_bf16 v[66:69], v[248:251], v[232:235], v[66:69]
	s_add_i32 m0, s1, 0x7e80
	s_barrier
	ds_read_b128 v[180:183], v0 offset:49152
	ds_read_b128 v[184:187], v0 offset:50176
	ds_read_b128 v[188:191], v0 offset:51200
	ds_read_b128 v[192:195], v0 offset:52224
	ds_read_b128 v[196:199], v0 offset:53248
	ds_read_b128 v[200:203], v0 offset:54272
	ds_read_b128 v[222:225], v0 offset:55296
	ds_read_b128 v[232:235], v0 offset:56320
	global_load_lds_dwordx4 v204, s[98:99] offset:384
	s_add_i32 m0, s1, 0x9e80
	s_nop 0
	global_load_lds_dwordx4 v205, s[98:99] offset:384
	s_barrier
	s_waitcnt lgkmcnt(0)
	v_mfma_f32_16x16x32_bf16 v[62:65], v[164:167], v[180:183], v[62:65]
	v_mfma_f32_16x16x32_bf16 v[58:61], v[172:175], v[180:183], v[58:61]
	v_mfma_f32_16x16x32_bf16 v[54:57], v[164:167], v[188:191], v[54:57]
	v_mfma_f32_16x16x32_bf16 v[50:53], v[172:175], v[188:191], v[50:53]
	v_mfma_f32_16x16x32_bf16 v[46:49], v[164:167], v[196:199], v[46:49]
	v_mfma_f32_16x16x32_bf16 v[42:45], v[172:175], v[196:199], v[42:45]
	v_mfma_f32_16x16x32_bf16 v[38:41], v[164:167], v[222:225], v[38:41]
	v_mfma_f32_16x16x32_bf16 v[34:37], v[172:175], v[222:225], v[34:37]
	v_mfma_f32_16x16x32_bf16 v[62:65], v[168:171], v[184:187], v[62:65]
	v_mfma_f32_16x16x32_bf16 v[58:61], v[176:179], v[184:187], v[58:61]
	v_mfma_f32_16x16x32_bf16 v[54:57], v[168:171], v[192:195], v[54:57]
	v_mfma_f32_16x16x32_bf16 v[50:53], v[176:179], v[192:195], v[50:53]
	v_mfma_f32_16x16x32_bf16 v[46:49], v[168:171], v[200:203], v[46:49]
	v_mfma_f32_16x16x32_bf16 v[42:45], v[176:179], v[200:203], v[42:45]
	v_mfma_f32_16x16x32_bf16 v[38:41], v[168:171], v[232:235], v[38:41]
	v_mfma_f32_16x16x32_bf16 v[34:37], v[176:179], v[232:235], v[34:37]
	s_barrier
	s_add_i32 m0, s1, 0x1bf80
	s_nop 0
	global_load_lds_dwordx4 v218, vcc offset:128
	s_add_i32 m0, s1, 0x1df80
	s_nop 0
	global_load_lds_dwordx4 v219, vcc offset:128
	s_waitcnt vmcnt(6)
	s_barrier
	v_mfma_f32_16x16x32_bf16 v[30:33], v[236:239], v[180:183], v[30:33]
	v_mfma_f32_16x16x32_bf16 v[26:29], v[244:247], v[180:183], v[26:29]
	v_mfma_f32_16x16x32_bf16 v[22:25], v[236:239], v[188:191], v[22:25]
	v_mfma_f32_16x16x32_bf16 v[18:21], v[244:247], v[188:191], v[18:21]
	v_mfma_f32_16x16x32_bf16 v[14:17], v[236:239], v[196:199], v[14:17]
	v_mfma_f32_16x16x32_bf16 v[10:13], v[244:247], v[196:199], v[10:13]
	v_mfma_f32_16x16x32_bf16 v[6:9], v[236:239], v[222:225], v[6:9]
	v_mfma_f32_16x16x32_bf16 v[2:5], v[244:247], v[222:225], v[2:5]
	v_mfma_f32_16x16x32_bf16 v[30:33], v[240:243], v[184:187], v[30:33]
	v_mfma_f32_16x16x32_bf16 v[26:29], v[248:251], v[184:187], v[26:29]
	v_mfma_f32_16x16x32_bf16 v[22:25], v[240:243], v[192:195], v[22:25]
	v_mfma_f32_16x16x32_bf16 v[18:21], v[248:251], v[192:195], v[18:21]
	v_mfma_f32_16x16x32_bf16 v[14:17], v[240:243], v[200:203], v[14:17]
	v_mfma_f32_16x16x32_bf16 v[10:13], v[248:251], v[200:203], v[10:13]
	v_mfma_f32_16x16x32_bf16 v[6:9], v[240:243], v[232:235], v[6:9]
	v_mfma_f32_16x16x32_bf16 v[2:5], v[248:251], v[232:235], v[2:5]
	s_add_i32 s0, s0, 2
	s_add_u32 s10, s10, 0x100
	s_addc_u32 s11, s11, 0
	s_add_u32 s98, s98, 0x100
	s_addc_u32 s99, s99, 0
	s_add_u32 vcc_lo, vcc_lo, 0x100
	s_addc_u32 vcc_hi, vcc_hi, 0
	s_cmp_lt_u32 s0, 28
	s_barrier
	s_cbranch_scc1 .LBB0_85
	s_add_i32 s1, s1, 0x1e000
	s_mov_b64 s[10:11], 0xf80
	v_readfirstlane_b32 s0, v162
	v_lshl_add_u64 v[132:133], v[132:133], 0, s[10:11]
	s_mov_b32 m0, s0
	v_readfirstlane_b32 s0, v163
	ds_read_b128 v[134:137], v151
	ds_read_b128 v[138:141], v151 offset:1024
	ds_read_b128 v[152:155], v151 offset:2048
	ds_read_b128 v[156:159], v151 offset:3072
	ds_read_b128 v[164:167], v0
	ds_read_b128 v[168:171], v0 offset:1024
	ds_read_b128 v[172:175], v0 offset:2048
	ds_read_b128 v[176:179], v0 offset:3072
	ds_read_b128 v[180:183], v0 offset:4096
	ds_read_b128 v[184:187], v0 offset:5120
	ds_read_b128 v[188:191], v0 offset:6144
	ds_read_b128 v[192:195], v0 offset:7168
	global_load_lds_dwordx4 v[132:133], off
	v_lshl_add_u64 v[130:131], v[130:131], 0, s[10:11]
	s_mov_b32 m0, s0
	s_nop 0
	global_load_lds_dwordx4 v[130:131], off
	s_barrier
	s_waitcnt lgkmcnt(0)
	s_setprio 1
	s_waitcnt lgkmcnt(0)
	v_mfma_f32_16x16x32_bf16 v[126:129], v[134:137], v[164:167], v[126:129]
	v_mfma_f32_16x16x32_bf16 v[122:125], v[152:155], v[164:167], v[122:125]
	v_mfma_f32_16x16x32_bf16 v[114:117], v[152:155], v[172:175], v[114:117]
	v_mfma_f32_16x16x32_bf16 v[106:109], v[152:155], v[180:183], v[106:109]
	v_mfma_f32_16x16x32_bf16 v[98:101], v[152:155], v[188:191], v[98:101]
	v_mfma_f32_16x16x32_bf16 v[126:129], v[138:141], v[168:171], v[126:129]
	v_mfma_f32_16x16x32_bf16 v[122:125], v[156:159], v[168:171], v[122:125]
	v_mfma_f32_16x16x32_bf16 v[118:121], v[134:137], v[172:175], v[118:121]
	v_mfma_f32_16x16x32_bf16 v[114:117], v[156:159], v[176:179], v[114:117]
	v_mfma_f32_16x16x32_bf16 v[110:113], v[134:137], v[180:183], v[110:113]
	v_mfma_f32_16x16x32_bf16 v[106:109], v[156:159], v[184:187], v[106:109]
	v_mfma_f32_16x16x32_bf16 v[102:105], v[134:137], v[188:191], v[102:105]
	v_mfma_f32_16x16x32_bf16 v[98:101], v[156:159], v[192:195], v[98:101]
	v_mfma_f32_16x16x32_bf16 v[130:133], v[138:141], v[176:179], v[118:121]
	v_mfma_f32_16x16x32_bf16 v[160:163], v[138:141], v[184:187], v[110:113]
	v_mfma_f32_16x16x32_bf16 v[196:199], v[138:141], v[192:195], v[102:105]
	s_setprio 0
	s_barrier
	s_nop 0
	ds_read_b128 v[102:105], v151 offset:16384
	ds_read_b128 v[110:113], v151 offset:17408
	ds_read_b128 v[118:121], v151 offset:18432
	ds_read_b128 v[200:203], v151 offset:19456
	s_barrier
	s_waitcnt lgkmcnt(0)
	s_setprio 1
	s_waitcnt lgkmcnt(1)
	v_mfma_f32_16x16x32_bf16 v[90:93], v[118:121], v[164:167], v[90:93]
	v_mfma_f32_16x16x32_bf16 v[86:89], v[102:105], v[172:175], v[86:89]
	v_mfma_f32_16x16x32_bf16 v[82:85], v[118:121], v[172:175], v[82:85]
	v_mfma_f32_16x16x32_bf16 v[78:81], v[102:105], v[180:183], v[78:81]
	v_mfma_f32_16x16x32_bf16 v[70:73], v[102:105], v[188:191], v[70:73]
	v_mfma_f32_16x16x32_bf16 v[94:97], v[102:105], v[164:167], v[94:97]
	s_waitcnt lgkmcnt(0)
	v_mfma_f32_16x16x32_bf16 v[90:93], v[200:203], v[168:171], v[90:93]
	v_mfma_f32_16x16x32_bf16 v[86:89], v[110:113], v[176:179], v[86:89]
	v_mfma_f32_16x16x32_bf16 v[82:85], v[200:203], v[176:179], v[82:85]
	v_mfma_f32_16x16x32_bf16 v[78:81], v[110:113], v[184:187], v[78:81]
	v_mfma_f32_16x16x32_bf16 v[74:77], v[118:121], v[180:183], v[74:77]
	v_mfma_f32_16x16x32_bf16 v[70:73], v[110:113], v[192:195], v[70:73]
	v_mfma_f32_16x16x32_bf16 v[66:69], v[118:121], v[188:191], v[66:69]
	v_mfma_f32_16x16x32_bf16 v[222:225], v[110:113], v[168:171], v[94:97]
	v_mfma_f32_16x16x32_bf16 v[164:167], v[200:203], v[184:187], v[74:77]
	v_mfma_f32_16x16x32_bf16 v[168:171], v[200:203], v[192:195], v[66:69]
	s_setprio 0
	s_barrier
	s_nop 2
	ds_read_b128 v[66:69], v0 offset:16384
	ds_read_b128 v[74:77], v0 offset:17408
	ds_read_b128 v[94:97], v0 offset:18432
	ds_read_b128 v[172:175], v0 offset:19456
	ds_read_b128 v[176:179], v0 offset:20480
	ds_read_b128 v[180:183], v0 offset:21504
	ds_read_b128 v[184:187], v0 offset:22528
	ds_read_b128 v[188:191], v0 offset:23552
	s_waitcnt vmcnt(4)
	s_barrier
	s_waitcnt lgkmcnt(0)
	s_setprio 1
	s_waitcnt lgkmcnt(5)
	v_mfma_f32_16x16x32_bf16 v[54:57], v[134:137], v[94:97], v[54:57]
	v_mfma_f32_16x16x32_bf16 v[50:53], v[152:155], v[94:97], v[50:53]
	v_mfma_f32_16x16x32_bf16 v[62:65], v[134:137], v[66:69], v[62:65]
	v_mfma_f32_16x16x32_bf16 v[58:61], v[152:155], v[66:69], v[58:61]
	s_waitcnt lgkmcnt(4)
	v_mfma_f32_16x16x32_bf16 v[54:57], v[138:141], v[172:175], v[54:57]
	v_mfma_f32_16x16x32_bf16 v[50:53], v[156:159], v[172:175], v[50:53]
	s_waitcnt lgkmcnt(3)
	v_mfma_f32_16x16x32_bf16 v[46:49], v[134:137], v[176:179], v[46:49]
	v_mfma_f32_16x16x32_bf16 v[42:45], v[152:155], v[176:179], v[42:45]
	s_waitcnt lgkmcnt(1)
	v_mfma_f32_16x16x32_bf16 v[38:41], v[134:137], v[184:187], v[38:41]
	v_mfma_f32_16x16x32_bf16 v[34:37], v[152:155], v[184:187], v[34:37]
	v_mfma_f32_16x16x32_bf16 v[192:195], v[138:141], v[74:77], v[62:65]
	v_mfma_f32_16x16x32_bf16 v[232:235], v[156:159], v[74:77], v[58:61]
	v_mfma_f32_16x16x32_bf16 v[236:239], v[138:141], v[180:183], v[46:49]
	v_mfma_f32_16x16x32_bf16 v[240:243], v[156:159], v[180:183], v[42:45]
	s_waitcnt lgkmcnt(0)
	v_mfma_f32_16x16x32_bf16 v[134:137], v[138:141], v[188:191], v[38:41]
	v_mfma_f32_16x16x32_bf16 v[138:141], v[156:159], v[188:191], v[34:37]
	s_setprio 0
	s_setprio 1
	v_mfma_f32_16x16x32_bf16 v[30:33], v[102:105], v[66:69], v[30:33]
	v_mfma_f32_16x16x32_bf16 v[26:29], v[118:121], v[66:69], v[26:29]
	v_mfma_f32_16x16x32_bf16 v[14:17], v[102:105], v[176:179], v[14:17]
	v_mfma_f32_16x16x32_bf16 v[10:13], v[118:121], v[176:179], v[10:13]
	v_mfma_f32_16x16x32_bf16 v[30:33], v[110:113], v[74:77], v[30:33]
	v_mfma_f32_16x16x32_bf16 v[26:29], v[200:203], v[74:77], v[26:29]
	v_mfma_f32_16x16x32_bf16 v[22:25], v[102:105], v[94:97], v[22:25]
	v_mfma_f32_16x16x32_bf16 v[18:21], v[118:121], v[94:97], v[18:21]
	v_mfma_f32_16x16x32_bf16 v[14:17], v[110:113], v[180:183], v[14:17]
	v_mfma_f32_16x16x32_bf16 v[10:13], v[200:203], v[180:183], v[10:13]
	v_mfma_f32_16x16x32_bf16 v[6:9], v[102:105], v[184:187], v[6:9]
	v_mfma_f32_16x16x32_bf16 v[2:5], v[118:121], v[184:187], v[2:5]
	v_mfma_f32_16x16x32_bf16 v[152:155], v[110:113], v[172:175], v[22:25]
	v_mfma_f32_16x16x32_bf16 v[156:159], v[200:203], v[172:175], v[18:21]
	v_mfma_f32_16x16x32_bf16 v[172:175], v[110:113], v[188:191], v[6:9]
	v_mfma_f32_16x16x32_bf16 v[176:179], v[200:203], v[188:191], v[2:5]
	s_setprio 0
	s_barrier
	s_nop 1
	ds_read_b128 v[2:5], v151 offset:32768
	ds_read_b128 v[6:9], v151 offset:33792
	ds_read_b128 v[180:183], v151 offset:34816
	ds_read_b128 v[184:187], v151 offset:35840
	ds_read_b128 v[18:21], v0 offset:32768
	ds_read_b128 v[22:25], v0 offset:33792
	ds_read_b128 v[38:41], v0 offset:34816
	ds_read_b128 v[46:49], v0 offset:35840
	ds_read_b128 v[58:61], v0 offset:36864
	ds_read_b128 v[66:69], v0 offset:37888
	ds_read_b128 v[188:191], v0 offset:38912
	ds_read_b128 v[200:203], v0 offset:39936
	s_waitcnt vmcnt(2)
	s_barrier
	s_waitcnt lgkmcnt(0)
	s_setprio 1
	s_waitcnt lgkmcnt(7)
	v_mfma_f32_16x16x32_bf16 v[34:37], v[2:5], v[18:21], v[126:129]
	s_waitcnt lgkmcnt(6)
	v_mfma_f32_16x16x32_bf16 v[118:121], v[6:9], v[22:25], v[34:37]
	v_mfma_f32_16x16x32_bf16 v[34:37], v[180:183], v[18:21], v[122:125]
	v_mfma_f32_16x16x32_bf16 v[110:113], v[184:187], v[22:25], v[34:37]
	s_waitcnt lgkmcnt(5)
	v_mfma_f32_16x16x32_bf16 v[34:37], v[2:5], v[38:41], v[130:133]
	s_waitcnt lgkmcnt(4)
	v_mfma_f32_16x16x32_bf16 v[102:105], v[6:9], v[46:49], v[34:37]
	v_mfma_f32_16x16x32_bf16 v[34:37], v[180:183], v[38:41], v[114:117]
	v_mfma_f32_16x16x32_bf16 v[94:97], v[184:187], v[46:49], v[34:37]
	s_waitcnt lgkmcnt(3)
	v_mfma_f32_16x16x32_bf16 v[34:37], v[2:5], v[58:61], v[160:163]
	s_waitcnt lgkmcnt(2)
	v_mfma_f32_16x16x32_bf16 v[74:77], v[6:9], v[66:69], v[34:37]
	v_mfma_f32_16x16x32_bf16 v[34:37], v[180:183], v[58:61], v[106:109]
	v_mfma_f32_16x16x32_bf16 v[62:65], v[184:187], v[66:69], v[34:37]
	s_waitcnt lgkmcnt(1)
	v_mfma_f32_16x16x32_bf16 v[34:37], v[2:5], v[188:191], v[196:199]
	s_waitcnt lgkmcnt(0)
	v_mfma_f32_16x16x32_bf16 v[42:45], v[6:9], v[200:203], v[34:37]
	v_mfma_f32_16x16x32_bf16 v[34:37], v[180:183], v[188:191], v[98:101]
	v_mfma_f32_16x16x32_bf16 v[34:37], v[184:187], v[200:203], v[34:37]
	s_setprio 0
	s_barrier
	ds_read_b128 v[130:133], v151 offset:49152
	ds_read_b128 v[160:163], v151 offset:50176
	ds_read_b128 v[196:199], v151 offset:51200
	ds_read_b128 v[148:151], v151 offset:52224
	s_waitcnt vmcnt(0)
	s_barrier
	s_waitcnt lgkmcnt(0)
	s_setprio 1
	s_waitcnt lgkmcnt(3)
	v_mfma_f32_16x16x32_bf16 v[98:101], v[130:133], v[18:21], v[222:225]
	s_waitcnt lgkmcnt(1)
	v_mfma_f32_16x16x32_bf16 v[18:21], v[196:199], v[18:21], v[90:93]
	s_waitcnt lgkmcnt(0)
	v_mfma_f32_16x16x32_bf16 v[122:125], v[148:151], v[22:25], v[18:21]
	v_mfma_f32_16x16x32_bf16 v[18:21], v[130:133], v[38:41], v[86:89]
	v_mfma_f32_16x16x32_bf16 v[114:117], v[160:163], v[46:49], v[18:21]
	v_mfma_f32_16x16x32_bf16 v[18:21], v[196:199], v[38:41], v[82:85]
	v_mfma_f32_16x16x32_bf16 v[106:109], v[148:151], v[46:49], v[18:21]
	v_mfma_f32_16x16x32_bf16 v[18:21], v[130:133], v[58:61], v[78:81]
	v_mfma_f32_16x16x32_bf16 v[126:129], v[160:163], v[22:25], v[98:101]
	v_mfma_f32_16x16x32_bf16 v[98:101], v[160:163], v[66:69], v[18:21]
	v_mfma_f32_16x16x32_bf16 v[18:21], v[196:199], v[58:61], v[164:167]
	v_mfma_f32_16x16x32_bf16 v[90:93], v[148:151], v[66:69], v[18:21]
	v_mfma_f32_16x16x32_bf16 v[18:21], v[130:133], v[188:191], v[70:73]
	v_mfma_f32_16x16x32_bf16 v[66:69], v[160:163], v[200:203], v[18:21]
	v_mfma_f32_16x16x32_bf16 v[18:21], v[196:199], v[188:191], v[168:171]
	v_mfma_f32_16x16x32_bf16 v[58:61], v[148:151], v[200:203], v[18:21]
	s_setprio 0
	s_barrier
	ds_read_b128 v[82:85], v0 offset:49152
	ds_read_b128 v[164:167], v0 offset:50176
	ds_read_b128 v[168:171], v0 offset:51200
	ds_read_b128 v[188:191], v0 offset:52224
	ds_read_b128 v[200:203], v0 offset:53248
	ds_read_b128 v[222:225], v0 offset:54272
	ds_read_b128 v[244:247], v0 offset:55296
	ds_read_b128 v[248:251], v0 offset:56320
	s_barrier
	s_waitcnt lgkmcnt(0)
	s_setprio 1
	s_waitcnt lgkmcnt(7)
	v_mfma_f32_16x16x32_bf16 v[18:21], v[2:5], v[82:85], v[192:195]
	s_waitcnt lgkmcnt(6)
	v_mfma_f32_16x16x32_bf16 v[78:81], v[6:9], v[164:167], v[18:21]
	v_mfma_f32_16x16x32_bf16 v[18:21], v[180:183], v[82:85], v[232:235]
	v_mfma_f32_16x16x32_bf16 v[70:73], v[184:187], v[164:167], v[18:21]
	s_waitcnt lgkmcnt(5)
	v_mfma_f32_16x16x32_bf16 v[18:21], v[2:5], v[168:171], v[54:57]
	s_waitcnt lgkmcnt(4)
	v_mfma_f32_16x16x32_bf16 v[46:49], v[6:9], v[188:191], v[18:21]
	v_mfma_f32_16x16x32_bf16 v[18:21], v[180:183], v[168:171], v[50:53]
	v_mfma_f32_16x16x32_bf16 v[38:41], v[184:187], v[188:191], v[18:21]
	s_waitcnt lgkmcnt(3)
	v_mfma_f32_16x16x32_bf16 v[18:21], v[2:5], v[200:203], v[236:239]
	s_waitcnt lgkmcnt(1)
	v_mfma_f32_16x16x32_bf16 v[2:5], v[2:5], v[244:247], v[134:137]
	v_mfma_f32_16x16x32_bf16 v[22:25], v[6:9], v[222:225], v[18:21]
	v_mfma_f32_16x16x32_bf16 v[18:21], v[180:183], v[200:203], v[240:243]
	s_waitcnt lgkmcnt(0)
	v_mfma_f32_16x16x32_bf16 v[6:9], v[6:9], v[248:251], v[2:5]
	v_mfma_f32_16x16x32_bf16 v[2:5], v[180:183], v[244:247], v[138:141]
	v_mfma_f32_16x16x32_bf16 v[18:21], v[184:187], v[222:225], v[18:21]
	v_mfma_f32_16x16x32_bf16 v[2:5], v[184:187], v[248:251], v[2:5]
	s_setprio 0
	s_setprio 1
	v_mfma_f32_16x16x32_bf16 v[26:29], v[196:199], v[82:85], v[26:29]
	v_mfma_f32_16x16x32_bf16 v[30:33], v[130:133], v[82:85], v[30:33]
	v_mfma_f32_16x16x32_bf16 v[82:85], v[148:151], v[164:167], v[26:29]
	v_mfma_f32_16x16x32_bf16 v[26:29], v[130:133], v[168:171], v[152:155]
	v_mfma_f32_16x16x32_bf16 v[54:57], v[160:163], v[188:191], v[26:29]
	v_mfma_f32_16x16x32_bf16 v[26:29], v[196:199], v[168:171], v[156:159]
	v_mfma_f32_16x16x32_bf16 v[10:13], v[196:199], v[200:203], v[10:13]
	v_mfma_f32_16x16x32_bf16 v[50:53], v[148:151], v[188:191], v[26:29]
	v_mfma_f32_16x16x32_bf16 v[14:17], v[130:133], v[200:203], v[14:17]
	v_mfma_f32_16x16x32_bf16 v[26:29], v[148:151], v[222:225], v[10:13]
	v_mfma_f32_16x16x32_bf16 v[10:13], v[130:133], v[244:247], v[172:175]
	v_mfma_f32_16x16x32_bf16 v[86:89], v[160:163], v[164:167], v[30:33]
	v_mfma_f32_16x16x32_bf16 v[30:33], v[160:163], v[222:225], v[14:17]
	v_mfma_f32_16x16x32_bf16 v[14:17], v[160:163], v[248:251], v[10:13]
	v_mfma_f32_16x16x32_bf16 v[10:13], v[196:199], v[244:247], v[176:179]
	v_mfma_f32_16x16x32_bf16 v[10:13], v[148:151], v[248:251], v[10:13]
	s_setprio 0
	s_movk_i32 s0, 0x100
	v_cmp_gt_u32_e32 vcc, s0, v142
	s_barrier
	s_and_saveexec_b64 s[0:1], vcc
	s_cbranch_execz .LBB0_81
	s_barrier
	s_branch .LBB0_81

.LBB0_108:
	ds_read_b128 v[104:107], v99
	ds_read_b128 v[108:111], v99 offset:1024
	ds_read_b128 v[112:115], v99 offset:2048
	ds_read_b128 v[116:119], v99 offset:3072
	v_lshl_add_u64 v[152:153], v[74:75], 0, s[10:11]
	v_lshl_add_u64 v[164:165], v[152:153], 0, s[60:61]
	s_add_i32 m0, s1, 0xc000
	ds_read_b128 v[120:123], v0
	ds_read_b128 v[124:127], v0 offset:1024
	ds_read_b128 v[128:131], v0 offset:2048
	ds_read_b128 v[132:135], v0 offset:3072
	ds_read_b128 v[136:139], v0 offset:4096
	ds_read_b128 v[140:143], v0 offset:5120
	ds_read_b128 v[144:147], v0 offset:6144
	ds_read_b128 v[148:151], v0 offset:7168
	global_load_lds_dwordx4 v[164:165], off
	v_lshl_add_u64 v[154:155], v[76:77], 0, s[10:11]
	s_add_i32 m0, s1, 0xe000
	v_lshl_add_u64 v[88:89], v[154:155], 0, s[60:61]
	global_load_lds_dwordx4 v[88:89], off
	s_waitcnt lgkmcnt(8)
	s_barrier
	s_waitcnt lgkmcnt(0)
	v_mfma_f32_16x16x32_bf16 v[62:65], v[104:107], v[120:123], v[62:65]
	v_mfma_f32_16x16x32_bf16 v[58:61], v[112:115], v[120:123], v[58:61]
	v_mfma_f32_16x16x32_bf16 v[54:57], v[104:107], v[128:131], v[54:57]
	v_mfma_f32_16x16x32_bf16 v[50:53], v[112:115], v[128:131], v[50:53]
	v_mfma_f32_16x16x32_bf16 v[46:49], v[104:107], v[136:139], v[46:49]
	v_mfma_f32_16x16x32_bf16 v[42:45], v[112:115], v[136:139], v[42:45]
	v_mfma_f32_16x16x32_bf16 v[38:41], v[104:107], v[144:147], v[38:41]
	v_mfma_f32_16x16x32_bf16 v[34:37], v[112:115], v[144:147], v[34:37]
	v_mfma_f32_16x16x32_bf16 v[62:65], v[108:111], v[124:127], v[62:65]
	v_mfma_f32_16x16x32_bf16 v[58:61], v[116:119], v[124:127], v[58:61]
	v_mfma_f32_16x16x32_bf16 v[54:57], v[108:111], v[132:135], v[54:57]
	v_mfma_f32_16x16x32_bf16 v[50:53], v[116:119], v[132:135], v[50:53]
	v_mfma_f32_16x16x32_bf16 v[46:49], v[108:111], v[140:143], v[46:49]
	v_mfma_f32_16x16x32_bf16 v[42:45], v[116:119], v[140:143], v[42:45]
	v_mfma_f32_16x16x32_bf16 v[38:41], v[108:111], v[148:151], v[38:41]
	v_mfma_f32_16x16x32_bf16 v[34:37], v[116:119], v[148:151], v[34:37]
	s_barrier
	v_lshl_add_u64 v[156:157], v[70:71], 0, s[10:11]
	s_add_i32 m0, s1, 0xff00
	s_nop 0
	global_load_lds_dwordx4 v[156:157], off offset:256
	v_lshl_add_u64 v[158:159], v[72:73], 0, s[10:11]
	s_add_i32 m0, s1, 0x11f00
	s_nop 0
	global_load_lds_dwordx4 v[158:159], off offset:256
	v_lshl_add_u64 v[90:91], v[152:153], 0, s[74:75]
	s_mov_b32 m0, s1
	s_barrier
	s_waitcnt lgkmcnt(0)
	s_barrier
	ds_read_b128 v[120:123], v0 offset:16384
	ds_read_b128 v[124:127], v0 offset:17408
	ds_read_b128 v[128:131], v0 offset:18432
	ds_read_b128 v[132:135], v0 offset:19456
	ds_read_b128 v[136:139], v0 offset:20480
	ds_read_b128 v[140:143], v0 offset:21504
	ds_read_b128 v[144:147], v0 offset:22528
	ds_read_b128 v[148:151], v0 offset:23552
	global_load_lds_dwordx4 v[90:91], off
	s_add_i32 m0, s1, 0x1f00
	s_nop 0
	global_load_lds_dwordx4 v[154:155], off offset:256
	s_barrier
	s_waitcnt lgkmcnt(0)
	v_mfma_f32_16x16x32_bf16 v[2:5], v[104:107], v[120:123], v[2:5]
	v_mfma_f32_16x16x32_bf16 v[6:9], v[112:115], v[120:123], v[6:9]
	v_mfma_f32_16x16x32_bf16 v[10:13], v[104:107], v[128:131], v[10:13]
	v_mfma_f32_16x16x32_bf16 v[14:17], v[112:115], v[128:131], v[14:17]
	v_mfma_f32_16x16x32_bf16 v[18:21], v[104:107], v[136:139], v[18:21]
	v_mfma_f32_16x16x32_bf16 v[22:25], v[112:115], v[136:139], v[22:25]
	v_mfma_f32_16x16x32_bf16 v[26:29], v[104:107], v[144:147], v[26:29]
	v_mfma_f32_16x16x32_bf16 v[30:33], v[112:115], v[144:147], v[30:33]
	v_mfma_f32_16x16x32_bf16 v[2:5], v[108:111], v[124:127], v[2:5]
	v_mfma_f32_16x16x32_bf16 v[6:9], v[116:119], v[124:127], v[6:9]
	v_mfma_f32_16x16x32_bf16 v[10:13], v[108:111], v[132:135], v[10:13]
	v_mfma_f32_16x16x32_bf16 v[14:17], v[116:119], v[132:135], v[14:17]
	v_mfma_f32_16x16x32_bf16 v[18:21], v[108:111], v[140:143], v[18:21]
	v_mfma_f32_16x16x32_bf16 v[22:25], v[116:119], v[140:143], v[22:25]
	v_mfma_f32_16x16x32_bf16 v[26:29], v[108:111], v[148:151], v[26:29]
	v_mfma_f32_16x16x32_bf16 v[30:33], v[116:119], v[148:151], v[30:33]
	s_barrier
	v_lshl_add_u64 v[160:161], v[78:79], 0, s[10:11]
	s_add_i32 m0, s1, 0x13f00
	s_nop 0
	global_load_lds_dwordx4 v[160:161], off offset:256
	s_add_i32 m0, s1, 0x15f00
	v_lshl_add_u64 v[162:163], v[80:81], 0, s[10:11]
	global_load_lds_dwordx4 v[162:163], off offset:256
	s_waitcnt vmcnt(6)
	s_barrier
	s_barrier
	ds_read_b128 v[104:107], v99 offset:32768
	ds_read_b128 v[108:111], v99 offset:33792
	ds_read_b128 v[112:115], v99 offset:34816
	ds_read_b128 v[116:119], v99 offset:35840
	s_add_i32 m0, s1, 0x3f80
	ds_read_b128 v[120:123], v0 offset:32768
	ds_read_b128 v[124:127], v0 offset:33792
	ds_read_b128 v[128:131], v0 offset:34816
	ds_read_b128 v[132:135], v0 offset:35840
	ds_read_b128 v[136:139], v0 offset:36864
	ds_read_b128 v[140:143], v0 offset:37888
	ds_read_b128 v[144:147], v0 offset:38912
	ds_read_b128 v[148:151], v0 offset:39936
	global_load_lds_dwordx4 v[164:165], off offset:128
	s_add_i32 m0, s1, 0x5f80
	s_nop 0
	global_load_lds_dwordx4 v[88:89], off offset:128
	s_waitcnt lgkmcnt(8)
	s_barrier
	s_waitcnt lgkmcnt(0)
	v_mfma_f32_16x16x32_bf16 v[62:65], v[104:107], v[120:123], v[62:65]
	v_mfma_f32_16x16x32_bf16 v[58:61], v[112:115], v[120:123], v[58:61]
	v_mfma_f32_16x16x32_bf16 v[54:57], v[104:107], v[128:131], v[54:57]
	v_mfma_f32_16x16x32_bf16 v[50:53], v[112:115], v[128:131], v[50:53]
	v_mfma_f32_16x16x32_bf16 v[46:49], v[104:107], v[136:139], v[46:49]
	v_mfma_f32_16x16x32_bf16 v[42:45], v[112:115], v[136:139], v[42:45]
	v_mfma_f32_16x16x32_bf16 v[38:41], v[104:107], v[144:147], v[38:41]
	v_mfma_f32_16x16x32_bf16 v[34:37], v[112:115], v[144:147], v[34:37]
	v_mfma_f32_16x16x32_bf16 v[62:65], v[108:111], v[124:127], v[62:65]
	v_mfma_f32_16x16x32_bf16 v[58:61], v[116:119], v[124:127], v[58:61]
	v_mfma_f32_16x16x32_bf16 v[54:57], v[108:111], v[132:135], v[54:57]
	v_mfma_f32_16x16x32_bf16 v[50:53], v[116:119], v[132:135], v[50:53]
	v_mfma_f32_16x16x32_bf16 v[46:49], v[108:111], v[140:143], v[46:49]
	v_mfma_f32_16x16x32_bf16 v[42:45], v[116:119], v[140:143], v[42:45]
	v_mfma_f32_16x16x32_bf16 v[38:41], v[108:111], v[148:151], v[38:41]
	v_mfma_f32_16x16x32_bf16 v[34:37], v[116:119], v[148:151], v[34:37]
	s_barrier
	s_add_i32 m0, s1, 0x17e80
	s_nop 0
	global_load_lds_dwordx4 v[156:157], off offset:384
	s_add_i32 m0, s1, 0x19e80
	s_nop 0
	global_load_lds_dwordx4 v[158:159], off offset:384
	s_add_i32 m0, s1, 0x7e80
	s_barrier
	s_waitcnt lgkmcnt(0)
	s_barrier
	ds_read_b128 v[120:123], v0 offset:49152
	ds_read_b128 v[124:127], v0 offset:50176
	ds_read_b128 v[128:131], v0 offset:51200
	ds_read_b128 v[132:135], v0 offset:52224
	ds_read_b128 v[136:139], v0 offset:53248
	ds_read_b128 v[140:143], v0 offset:54272
	ds_read_b128 v[144:147], v0 offset:55296
	ds_read_b128 v[148:151], v0 offset:56320
	global_load_lds_dwordx4 v[152:153], off offset:384
	s_add_i32 m0, s1, 0x9e80
	s_nop 0
	global_load_lds_dwordx4 v[154:155], off offset:384
	s_barrier
	s_waitcnt lgkmcnt(0)
	v_mfma_f32_16x16x32_bf16 v[2:5], v[104:107], v[120:123], v[2:5]
	v_mfma_f32_16x16x32_bf16 v[6:9], v[112:115], v[120:123], v[6:9]
	v_mfma_f32_16x16x32_bf16 v[10:13], v[104:107], v[128:131], v[10:13]
	v_mfma_f32_16x16x32_bf16 v[14:17], v[112:115], v[128:131], v[14:17]
	v_mfma_f32_16x16x32_bf16 v[18:21], v[104:107], v[136:139], v[18:21]
	v_mfma_f32_16x16x32_bf16 v[22:25], v[112:115], v[136:139], v[22:25]
	v_mfma_f32_16x16x32_bf16 v[26:29], v[104:107], v[144:147], v[26:29]
	v_mfma_f32_16x16x32_bf16 v[30:33], v[112:115], v[144:147], v[30:33]
	v_mfma_f32_16x16x32_bf16 v[2:5], v[108:111], v[124:127], v[2:5]
	v_mfma_f32_16x16x32_bf16 v[6:9], v[116:119], v[124:127], v[6:9]
	v_mfma_f32_16x16x32_bf16 v[10:13], v[108:111], v[132:135], v[10:13]
	v_mfma_f32_16x16x32_bf16 v[14:17], v[116:119], v[132:135], v[14:17]
	v_mfma_f32_16x16x32_bf16 v[18:21], v[108:111], v[140:143], v[18:21]
	v_mfma_f32_16x16x32_bf16 v[22:25], v[116:119], v[140:143], v[22:25]
	v_mfma_f32_16x16x32_bf16 v[26:29], v[108:111], v[148:151], v[26:29]
	v_mfma_f32_16x16x32_bf16 v[30:33], v[116:119], v[148:151], v[30:33]
	s_barrier
	s_add_i32 m0, s1, 0x1be80
	s_nop 0
	global_load_lds_dwordx4 v[160:161], off offset:384
	s_add_i32 m0, s1, 0x1de80
	s_add_i32 s0, s0, 2
	global_load_lds_dwordx4 v[162:163], off offset:384
	s_waitcnt vmcnt(6)
	s_add_u32 s10, s10, 0x100
	s_addc_u32 s11, s11, 0
	s_cmp_lt_u32 s0, 28
	s_barrier
	s_barrier
	s_cbranch_scc1 .LBB0_108
	s_add_i32 s1, s1, 0x1e000
	s_mov_b64 s[10:11], 0xf80
	v_readfirstlane_b32 s0, v102
	v_lshl_add_u64 v[68:69], v[68:69], 0, s[10:11]
	s_mov_b32 m0, s0
	v_readfirstlane_b32 s0, v103
	ds_read_b128 v[70:73], v99
	ds_read_b128 v[74:77], v99 offset:1024
	ds_read_b128 v[78:81], v99 offset:2048
	ds_read_b128 v[88:91], v99 offset:3072
	ds_read_b128 v[92:95], v0
	ds_read_b128 v[104:107], v0 offset:1024
	ds_read_b128 v[108:111], v0 offset:2048
	ds_read_b128 v[112:115], v0 offset:3072
	ds_read_b128 v[116:119], v0 offset:4096
	ds_read_b128 v[120:123], v0 offset:5120
	ds_read_b128 v[124:127], v0 offset:6144
	ds_read_b128 v[128:131], v0 offset:7168
	global_load_lds_dwordx4 v[68:69], off
	v_lshl_add_u64 v[66:67], v[66:67], 0, s[10:11]
	s_mov_b32 m0, s0
	s_nop 0
	global_load_lds_dwordx4 v[66:67], off
	s_barrier
	s_waitcnt lgkmcnt(0)
	s_setprio 1
	s_waitcnt lgkmcnt(0)
	v_mfma_f32_16x16x32_bf16 v[62:65], v[70:73], v[92:95], v[62:65]
	v_mfma_f32_16x16x32_bf16 v[58:61], v[78:81], v[92:95], v[58:61]
	v_mfma_f32_16x16x32_bf16 v[54:57], v[70:73], v[108:111], v[54:57]
	v_mfma_f32_16x16x32_bf16 v[50:53], v[78:81], v[108:111], v[50:53]
	v_mfma_f32_16x16x32_bf16 v[46:49], v[70:73], v[116:119], v[46:49]
	v_mfma_f32_16x16x32_bf16 v[42:45], v[78:81], v[116:119], v[42:45]
	v_mfma_f32_16x16x32_bf16 v[38:41], v[70:73], v[124:127], v[38:41]
	v_mfma_f32_16x16x32_bf16 v[34:37], v[78:81], v[124:127], v[34:37]
	v_mfma_f32_16x16x32_bf16 v[62:65], v[74:77], v[104:107], v[62:65]
	v_mfma_f32_16x16x32_bf16 v[58:61], v[88:91], v[104:107], v[58:61]
	v_mfma_f32_16x16x32_bf16 v[54:57], v[74:77], v[112:115], v[54:57]
	v_mfma_f32_16x16x32_bf16 v[50:53], v[88:91], v[112:115], v[50:53]
	v_mfma_f32_16x16x32_bf16 v[46:49], v[74:77], v[120:123], v[46:49]
	v_mfma_f32_16x16x32_bf16 v[42:45], v[88:91], v[120:123], v[42:45]
	v_mfma_f32_16x16x32_bf16 v[38:41], v[74:77], v[128:131], v[38:41]
	v_mfma_f32_16x16x32_bf16 v[34:37], v[88:91], v[128:131], v[34:37]
	s_setprio 0
	s_barrier
	s_barrier
	s_waitcnt lgkmcnt(0)
	s_barrier
	ds_read_b128 v[66:69], v0 offset:16384
	ds_read_b128 v[92:95], v0 offset:17408
	ds_read_b128 v[100:103], v0 offset:18432
	ds_read_b128 v[104:107], v0 offset:19456
	ds_read_b128 v[108:111], v0 offset:20480
	ds_read_b128 v[112:115], v0 offset:21504
	ds_read_b128 v[116:119], v0 offset:22528
	ds_read_b128 v[120:123], v0 offset:23552
	s_waitcnt vmcnt(4)
	s_barrier
	s_waitcnt lgkmcnt(0)
	s_setprio 1
	s_waitcnt lgkmcnt(3)
	v_mfma_f32_16x16x32_bf16 v[18:21], v[70:73], v[108:111], v[18:21]
	v_mfma_f32_16x16x32_bf16 v[2:5], v[70:73], v[66:69], v[2:5]
	v_mfma_f32_16x16x32_bf16 v[6:9], v[78:81], v[66:69], v[6:9]
	s_waitcnt lgkmcnt(2)
	v_mfma_f32_16x16x32_bf16 v[66:69], v[74:77], v[112:115], v[18:21]
	v_mfma_f32_16x16x32_bf16 v[18:21], v[78:81], v[108:111], v[22:25]
	v_mfma_f32_16x16x32_bf16 v[2:5], v[74:77], v[92:95], v[2:5]
	v_mfma_f32_16x16x32_bf16 v[6:9], v[88:91], v[92:95], v[6:9]
	v_mfma_f32_16x16x32_bf16 v[10:13], v[70:73], v[100:103], v[10:13]
	v_mfma_f32_16x16x32_bf16 v[14:17], v[78:81], v[100:103], v[14:17]
	v_mfma_f32_16x16x32_bf16 v[92:95], v[88:91], v[112:115], v[18:21]
	s_waitcnt lgkmcnt(1)
	v_mfma_f32_16x16x32_bf16 v[18:21], v[70:73], v[116:119], v[26:29]
	v_mfma_f32_16x16x32_bf16 v[10:13], v[74:77], v[104:107], v[10:13]
	v_mfma_f32_16x16x32_bf16 v[14:17], v[88:91], v[104:107], v[14:17]
	s_waitcnt lgkmcnt(0)
	v_mfma_f32_16x16x32_bf16 v[70:73], v[74:77], v[120:123], v[18:21]
	v_mfma_f32_16x16x32_bf16 v[18:21], v[78:81], v[116:119], v[30:33]
	v_mfma_f32_16x16x32_bf16 v[74:77], v[88:91], v[120:123], v[18:21]
	s_setprio 0
	s_barrier
	ds_read_b128 v[78:81], v99 offset:32768
	ds_read_b128 v[88:91], v99 offset:33792
	ds_read_b128 v[100:103], v99 offset:34816
	ds_read_b128 v[96:99], v99 offset:35840
	s_nop 0
	ds_read_b128 v[18:21], v0 offset:32768
	ds_read_b128 v[22:25], v0 offset:33792
	ds_read_b128 v[26:29], v0 offset:34816
	ds_read_b128 v[30:33], v0 offset:35840
	ds_read_b128 v[104:107], v0 offset:36864
	ds_read_b128 v[108:111], v0 offset:37888
	ds_read_b128 v[112:115], v0 offset:38912
	ds_read_b128 v[116:119], v0 offset:39936
	s_waitcnt vmcnt(2)
	s_barrier
	s_waitcnt lgkmcnt(0)
	s_setprio 1
	s_waitcnt lgkmcnt(7)
	v_mfma_f32_16x16x32_bf16 v[62:65], v[78:81], v[18:21], v[62:65]
	v_mfma_f32_16x16x32_bf16 v[18:21], v[100:103], v[18:21], v[58:61]
	s_waitcnt lgkmcnt(6)
	v_mfma_f32_16x16x32_bf16 v[58:61], v[96:99], v[22:25], v[18:21]
	s_waitcnt lgkmcnt(5)
	v_mfma_f32_16x16x32_bf16 v[18:21], v[78:81], v[26:29], v[54:57]
	s_waitcnt lgkmcnt(4)
	v_mfma_f32_16x16x32_bf16 v[54:57], v[88:91], v[30:33], v[18:21]
	v_mfma_f32_16x16x32_bf16 v[18:21], v[100:103], v[26:29], v[50:53]
	v_mfma_f32_16x16x32_bf16 v[50:53], v[96:99], v[30:33], v[18:21]
	s_waitcnt lgkmcnt(3)
	v_mfma_f32_16x16x32_bf16 v[18:21], v[78:81], v[104:107], v[46:49]
	s_waitcnt lgkmcnt(2)
	v_mfma_f32_16x16x32_bf16 v[46:49], v[88:91], v[108:111], v[18:21]
	v_mfma_f32_16x16x32_bf16 v[18:21], v[100:103], v[104:107], v[42:45]
	v_mfma_f32_16x16x32_bf16 v[42:45], v[96:99], v[108:111], v[18:21]
	s_waitcnt lgkmcnt(1)
	v_mfma_f32_16x16x32_bf16 v[18:21], v[78:81], v[112:115], v[38:41]
	s_waitcnt lgkmcnt(0)
	v_mfma_f32_16x16x32_bf16 v[38:41], v[88:91], v[116:119], v[18:21]
	v_mfma_f32_16x16x32_bf16 v[18:21], v[100:103], v[112:115], v[34:37]
	v_mfma_f32_16x16x32_bf16 v[62:65], v[88:91], v[22:25], v[62:65]
	v_mfma_f32_16x16x32_bf16 v[34:37], v[96:99], v[116:119], v[18:21]
	s_setprio 0
	s_barrier
	s_waitcnt vmcnt(0)
	s_barrier
	s_waitcnt lgkmcnt(0)
	s_barrier
	s_nop 1
	ds_read_b128 v[18:21], v0 offset:49152
	ds_read_b128 v[22:25], v0 offset:50176
	ds_read_b128 v[104:107], v0 offset:51200
	ds_read_b128 v[108:111], v0 offset:52224
	ds_read_b128 v[112:115], v0 offset:53248
	ds_read_b128 v[116:119], v0 offset:54272
	ds_read_b128 v[120:123], v0 offset:55296
	ds_read_b128 v[124:127], v0 offset:56320
	s_barrier
	s_waitcnt lgkmcnt(0)
	s_setprio 1
	s_waitcnt lgkmcnt(7)
	v_mfma_f32_16x16x32_bf16 v[2:5], v[78:81], v[18:21], v[2:5]
	s_waitcnt lgkmcnt(6)
	v_mfma_f32_16x16x32_bf16 v[30:33], v[88:91], v[22:25], v[2:5]
	v_mfma_f32_16x16x32_bf16 v[2:5], v[100:103], v[18:21], v[6:9]
	v_mfma_f32_16x16x32_bf16 v[26:29], v[96:99], v[22:25], v[2:5]
	s_waitcnt lgkmcnt(5)
	v_mfma_f32_16x16x32_bf16 v[2:5], v[78:81], v[104:107], v[10:13]
	s_waitcnt lgkmcnt(4)
	v_mfma_f32_16x16x32_bf16 v[22:25], v[88:91], v[108:111], v[2:5]
	v_mfma_f32_16x16x32_bf16 v[2:5], v[100:103], v[104:107], v[14:17]
	v_mfma_f32_16x16x32_bf16 v[18:21], v[96:99], v[108:111], v[2:5]
	s_waitcnt lgkmcnt(3)
	v_mfma_f32_16x16x32_bf16 v[2:5], v[78:81], v[112:115], v[66:69]
	s_waitcnt lgkmcnt(2)
	v_mfma_f32_16x16x32_bf16 v[14:17], v[88:91], v[116:119], v[2:5]
	v_mfma_f32_16x16x32_bf16 v[2:5], v[100:103], v[112:115], v[92:95]
	v_mfma_f32_16x16x32_bf16 v[10:13], v[96:99], v[116:119], v[2:5]
	s_waitcnt lgkmcnt(1)
	v_mfma_f32_16x16x32_bf16 v[2:5], v[78:81], v[120:123], v[70:73]
	s_waitcnt lgkmcnt(0)
	v_mfma_f32_16x16x32_bf16 v[6:9], v[88:91], v[124:127], v[2:5]
	v_mfma_f32_16x16x32_bf16 v[2:5], v[100:103], v[120:123], v[74:77]
	v_mfma_f32_16x16x32_bf16 v[2:5], v[96:99], v[124:127], v[2:5]
	s_setprio 0
	s_movk_i32 s0, 0x100
	v_cmp_gt_u32_e32 vcc, s0, v82
	s_barrier
	s_and_saveexec_b64 s[0:1], vcc
	s_cbranch_execz .LBB0_111
	s_barrier

.LBB0_179:
	s_or_b64 exec, exec, s[52:53]
	v_mov_b32_e32 v3, v1
	v_lshl_add_u64 v[14:15], s[0:1], 0, v[2:3]
	v_lshl_add_u64 v[18:19], s[16:17], 0, v[2:3]
	v_lshl_add_u64 v[22:23], s[72:73], 0, v[2:3]
	v_lshl_add_u64 v[130:131], s[76:77], 0, v[2:3]
	v_and_b32_e32 v146, 15, v142
	v_bfe_u32 v145, v142, 4, 2
	v_lshlrev_b32_e32 v3, 2, v142
	v_add_u32_e32 v156, 0x18000, v147
	v_lshl_add_u64 v[12:13], s[0:1], 0, v[0:1]
	v_lshl_add_u64 v[16:17], s[16:17], 0, v[0:1]
	v_lshl_add_u64 v[20:21], s[72:73], 0, v[0:1]
	v_lshl_add_u64 v[132:133], s[76:77], 0, v[0:1]
	v_lshlrev_b32_e32 v0, 6, v146
	v_lshlrev_b32_e32 v2, 4, v145
	v_and_b32_e32 v3, 32, v3
	s_mov_b64 s[16:17], 0x80
	v_readfirstlane_b32 s0, v156
	v_add_u32_e32 v157, 0x1a000, v147
	v_bitop3_b32 v24, v2, v3, v0 bitop3:0x36
	v_lshl_add_u64 v[2:3], v[12:13], 0, s[16:17]
	s_mov_b32 m0, s0
	v_readfirstlane_b32 s0, v157
	v_add_u32_e32 v158, 0x8000, v147
	s_waitcnt vmcnt(4)
	s_barrier
	global_load_lds_dwordx4 v[2:3], off
	v_lshl_add_u64 v[2:3], v[14:15], 0, s[16:17]
	s_mov_b32 m0, s0
	v_readfirstlane_b32 s0, v158
	v_add_u32_e32 v159, 0xa000, v147
	global_load_lds_dwordx4 v[2:3], off
	v_lshl_add_u64 v[2:3], v[16:17], 0, s[16:17]
	s_mov_b32 m0, s0
	v_readfirstlane_b32 s0, v159
	v_add_u32_e32 v160, 0x1c000, v147
	global_load_lds_dwordx4 v[2:3], off
	v_lshl_add_u64 v[2:3], v[18:19], 0, s[16:17]
	s_mov_b32 m0, s0
	v_readfirstlane_b32 s0, v160
	v_add_u32_e32 v161, 0x1e000, v147
	global_load_lds_dwordx4 v[2:3], off
	v_lshl_add_u64 v[2:3], v[20:21], 0, s[16:17]
	s_mov_b32 m0, s0
	v_readfirstlane_b32 s0, v161
	global_load_lds_dwordx4 v[2:3], off
	v_lshl_add_u64 v[2:3], v[22:23], 0, s[16:17]
	s_mov_b32 m0, s0
	v_lshlrev_b32_e32 v0, 14, v4
	global_load_lds_dwordx4 v[2:3], off
	v_lshlrev_b32_e32 v2, 14, v7
	v_and_b32_e32 v0, 0x7fff8000, v0
	v_and_b32_e32 v2, 0x7fff8000, v2
	v_lshl_add_u32 v0, v5, 11, v0
	v_lshl_add_u32 v2, v9, 11, v2
	v_or_b32_e32 v0, v0, v6
	s_add_u32 s0, s57, s12
	v_or_b32_e32 v2, v2, v10
	v_readlane_b32 s36, v253, 33
	v_add_lshl_u32 v0, v0, v8, 1
	s_addc_u32 s1, s63, s13
	v_add_lshl_u32 v2, v2, v11, 1
	v_mov_b32_e32 v3, v1
	v_readlane_b32 s48, v253, 45
	v_lshl_add_u64 v[134:135], s[0:1], 0, v[0:1]
	v_lshl_add_u64 v[136:137], s[0:1], 0, v[2:3]
	v_readlane_b32 s49, v253, 46
	s_add_u32 s0, s48, s14
	v_bfe_u32 v144, v142, 6, 2
	s_waitcnt vmcnt(6)
	s_addc_u32 s1, s49, s15
	v_lshlrev_b32_e32 v25, 13, v143
	v_lshl_or_b32 v26, v144, 12, v212
	v_lshl_add_u64 v[140:141], s[0:1], 0, v[2:3]
	v_mov_b32_e32 v2, 0
	v_lshl_add_u64 v[138:139], s[0:1], 0, v[0:1]
	s_mov_b32 s0, -2
	s_mov_b64 s[12:13], 0
	v_add_u32_e32 v151, v26, v24
	v_add_u32_e32 v0, v25, v24
	v_mov_b32_e32 v3, v2
	v_mov_b32_e32 v4, v2
	v_mov_b32_e32 v5, v2
	v_mov_b32_e32 v6, v2
	v_mov_b32_e32 v7, v2
	v_mov_b32_e32 v8, v2
	v_mov_b32_e32 v9, v2
	v_mov_b32_e32 v10, v2
	v_mov_b32_e32 v11, v2
	v_mov_b32_e32 v12, v2
	v_mov_b32_e32 v13, v2
	v_mov_b32_e32 v14, v2
	v_mov_b32_e32 v15, v2
	v_mov_b32_e32 v16, v2
	v_mov_b32_e32 v17, v2
	v_mov_b32_e32 v18, v2
	v_mov_b32_e32 v19, v2
	v_mov_b32_e32 v20, v2
	v_mov_b32_e32 v21, v2
	v_mov_b32_e32 v22, v2
	v_mov_b32_e32 v23, v2
	v_mov_b32_e32 v24, v2
	v_mov_b32_e32 v25, v2
	v_mov_b32_e32 v26, v2
	v_mov_b32_e32 v27, v2
	v_mov_b32_e32 v28, v2
	v_mov_b32_e32 v29, v2
	v_mov_b32_e32 v30, v2
	v_mov_b32_e32 v31, v2
	v_mov_b32_e32 v32, v2
	v_mov_b32_e32 v33, v2
	v_mov_b32_e32 v34, v2
	v_mov_b32_e32 v35, v2
	v_mov_b32_e32 v36, v2
	v_mov_b32_e32 v37, v2
	v_mov_b32_e32 v38, v2
	v_mov_b32_e32 v39, v2
	v_mov_b32_e32 v40, v2
	v_mov_b32_e32 v41, v2
	v_mov_b32_e32 v42, v2
	v_mov_b32_e32 v43, v2
	v_mov_b32_e32 v44, v2
	v_mov_b32_e32 v45, v2
	v_mov_b32_e32 v46, v2
	v_mov_b32_e32 v47, v2
	v_mov_b32_e32 v48, v2
	v_mov_b32_e32 v49, v2
	v_mov_b32_e32 v50, v2
	v_mov_b32_e32 v51, v2
	v_mov_b32_e32 v52, v2
	v_mov_b32_e32 v53, v2
	v_mov_b32_e32 v54, v2
	v_mov_b32_e32 v55, v2
	v_mov_b32_e32 v56, v2
	v_mov_b32_e32 v57, v2
	v_mov_b32_e32 v58, v2
	v_mov_b32_e32 v59, v2
	v_mov_b32_e32 v60, v2
	v_mov_b32_e32 v61, v2
	v_mov_b32_e32 v62, v2
	v_mov_b32_e32 v63, v2
	v_mov_b32_e32 v64, v2
	v_mov_b32_e32 v65, v2
	v_mov_b32_e32 v66, v2
	v_mov_b32_e32 v67, v2
	v_mov_b32_e32 v68, v2
	v_mov_b32_e32 v69, v2
	v_mov_b32_e32 v70, v2
	v_mov_b32_e32 v71, v2
	v_mov_b32_e32 v72, v2
	v_mov_b32_e32 v73, v2
	v_mov_b32_e32 v74, v2
	v_mov_b32_e32 v75, v2
	v_mov_b32_e32 v76, v2
	v_mov_b32_e32 v77, v2
	v_mov_b32_e32 v78, v2
	v_mov_b32_e32 v79, v2
	v_mov_b32_e32 v80, v2
	v_mov_b32_e32 v81, v2
	v_mov_b32_e32 v82, v2
	v_mov_b32_e32 v83, v2
	v_mov_b32_e32 v84, v2
	v_mov_b32_e32 v85, v2
	v_mov_b32_e32 v86, v2
	v_mov_b32_e32 v87, v2
	v_mov_b32_e32 v88, v2
	v_mov_b32_e32 v89, v2
	v_mov_b32_e32 v90, v2
	v_mov_b32_e32 v91, v2
	v_mov_b32_e32 v92, v2
	v_mov_b32_e32 v93, v2
	v_mov_b32_e32 v94, v2
	v_mov_b32_e32 v95, v2
	v_mov_b32_e32 v96, v2
	v_mov_b32_e32 v97, v2
	v_mov_b32_e32 v98, v2
	v_mov_b32_e32 v99, v2
	v_mov_b32_e32 v100, v2
	v_mov_b32_e32 v101, v2
	v_mov_b32_e32 v102, v2
	v_mov_b32_e32 v103, v2
	v_mov_b32_e32 v104, v2
	v_mov_b32_e32 v105, v2
	v_mov_b32_e32 v106, v2
	v_mov_b32_e32 v107, v2
	v_mov_b32_e32 v108, v2
	v_mov_b32_e32 v109, v2
	v_mov_b32_e32 v110, v2
	v_mov_b32_e32 v111, v2
	v_mov_b32_e32 v112, v2
	v_mov_b32_e32 v113, v2
	v_mov_b32_e32 v114, v2
	v_mov_b32_e32 v115, v2
	v_mov_b32_e32 v116, v2
	v_mov_b32_e32 v117, v2
	v_mov_b32_e32 v118, v2
	v_mov_b32_e32 v119, v2
	v_mov_b32_e32 v120, v2
	v_mov_b32_e32 v121, v2
	v_mov_b32_e32 v122, v2
	v_mov_b32_e32 v123, v2
	v_mov_b32_e32 v124, v2
	v_mov_b32_e32 v125, v2
	v_mov_b32_e32 v126, v2
	v_mov_b32_e32 v127, v2
	v_mov_b32_e32 v128, v2
	v_mov_b32_e32 v129, v2
	s_barrier
	v_readlane_b32 s37, v253, 34
	v_readlane_b32 s38, v253, 35
	v_readlane_b32 s39, v253, 36
	v_readlane_b32 s40, v253, 37
	v_readlane_b32 s41, v253, 38
	v_readlane_b32 s42, v253, 39
	v_readlane_b32 s43, v253, 40
	v_readlane_b32 s44, v253, 41
	v_readlane_b32 s45, v253, 42
	v_readlane_b32 s46, v253, 43
	v_readlane_b32 s47, v253, 44
	v_readlane_b32 s50, v253, 47
	v_readlane_b32 s51, v253, 48
	v_add_u32_e32 v162, 0xc000, v147
	v_add_u32_e32 v163, 0xe000, v147
	v_readfirstlane_b32 s1, v147
	s_nop 1
	v_readfirstlane_b32 s98, v138
	v_readfirstlane_b32 s99, v139
	s_nop 3
	s_sub_u32 s98, s98, 0x400000
	s_subb_u32 s99, s99, 0
	v_subrev_u32_e32 v204, s98, v138
	v_add_u32_e32 v216, 0x80080, v204
	v_subrev_u32_e32 v205, s98, v140
	v_add_u32_e32 v217, 0x80080, v205
	v_readfirstlane_b32 vcc_lo, v134
	v_readfirstlane_b32 vcc_hi, v135
	s_nop 3
	s_sub_u32 vcc_lo, vcc_lo, 0x400000
	s_subb_u32 vcc_hi, vcc_hi, 0
	v_subrev_u32_e32 v210, vcc_lo, v134
	v_add_u32_e32 v218, 0x80100, v210
	v_subrev_u32_e32 v211, vcc_lo, v136
	v_add_u32_e32 v219, 0x80100, v211
	v_add_u32_e32 v228, 0x100, v204
	s_add_u32 s98, s98, s12
	s_addc_u32 s99, s99, s13
	s_add_u32 vcc_lo, vcc_lo, s12
	s_addc_u32 vcc_hi, vcc_hi, s13
	s_nop 4
.LBB0_180:
	ds_read_b128 v[164:167], v151
	ds_read_b128 v[168:171], v151 offset:1024
	ds_read_b128 v[172:175], v151 offset:2048
	ds_read_b128 v[176:179], v151 offset:3072
	s_add_i32 m0, s1, 0xc000
	ds_read_b128 v[180:183], v0
	ds_read_b128 v[184:187], v0 offset:1024
	ds_read_b128 v[188:191], v0 offset:2048
	ds_read_b128 v[192:195], v0 offset:3072
	ds_read_b128 v[196:199], v0 offset:4096
	ds_read_b128 v[200:203], v0 offset:5120
	ds_read_b128 v[222:225], v0 offset:6144
	ds_read_b128 v[232:235], v0 offset:7168
	global_load_lds_dwordx4 v216, s[98:99]
	s_add_i32 m0, s1, 0xe000
	s_nop 0
	global_load_lds_dwordx4 v217, s[98:99]
	s_waitcnt lgkmcnt(8)
	s_barrier
	s_waitcnt lgkmcnt(0)
	v_mfma_f32_16x16x32_bf16 v[126:129], v[164:167], v[180:183], v[126:129]
	v_mfma_f32_16x16x32_bf16 v[122:125], v[172:175], v[180:183], v[122:125]
	v_mfma_f32_16x16x32_bf16 v[118:121], v[164:167], v[188:191], v[118:121]
	v_mfma_f32_16x16x32_bf16 v[114:117], v[172:175], v[188:191], v[114:117]
	v_mfma_f32_16x16x32_bf16 v[110:113], v[164:167], v[196:199], v[110:113]
	v_mfma_f32_16x16x32_bf16 v[106:109], v[172:175], v[196:199], v[106:109]
	v_mfma_f32_16x16x32_bf16 v[102:105], v[164:167], v[222:225], v[102:105]
	v_mfma_f32_16x16x32_bf16 v[98:101], v[172:175], v[222:225], v[98:101]
	v_mfma_f32_16x16x32_bf16 v[126:129], v[168:171], v[184:187], v[126:129]
	v_mfma_f32_16x16x32_bf16 v[122:125], v[176:179], v[184:187], v[122:125]
	v_mfma_f32_16x16x32_bf16 v[118:121], v[168:171], v[192:195], v[118:121]
	v_mfma_f32_16x16x32_bf16 v[114:117], v[176:179], v[192:195], v[114:117]
	v_mfma_f32_16x16x32_bf16 v[110:113], v[168:171], v[200:203], v[110:113]
	v_mfma_f32_16x16x32_bf16 v[106:109], v[176:179], v[200:203], v[106:109]
	v_mfma_f32_16x16x32_bf16 v[102:105], v[168:171], v[232:235], v[102:105]
	v_mfma_f32_16x16x32_bf16 v[98:101], v[176:179], v[232:235], v[98:101]
	s_barrier
	s_add_i32 m0, s1, 0xff00
	ds_read_b128 v[236:239], v151 offset:16384
	ds_read_b128 v[240:243], v151 offset:17408
	ds_read_b128 v[244:247], v151 offset:18432
	ds_read_b128 v[248:251], v151 offset:19456
	global_load_lds_dwordx4 v210, vcc offset:256
	s_add_i32 m0, s1, 0x11f00
	s_nop 0
	global_load_lds_dwordx4 v211, vcc offset:256
	s_barrier
	s_waitcnt lgkmcnt(0)
	v_mfma_f32_16x16x32_bf16 v[94:97], v[236:239], v[180:183], v[94:97]
	v_mfma_f32_16x16x32_bf16 v[90:93], v[244:247], v[180:183], v[90:93]
	v_mfma_f32_16x16x32_bf16 v[86:89], v[236:239], v[188:191], v[86:89]
	v_mfma_f32_16x16x32_bf16 v[82:85], v[244:247], v[188:191], v[82:85]
	v_mfma_f32_16x16x32_bf16 v[78:81], v[236:239], v[196:199], v[78:81]
	v_mfma_f32_16x16x32_bf16 v[74:77], v[244:247], v[196:199], v[74:77]
	v_mfma_f32_16x16x32_bf16 v[70:73], v[236:239], v[222:225], v[70:73]
	v_mfma_f32_16x16x32_bf16 v[66:69], v[244:247], v[222:225], v[66:69]
	v_mfma_f32_16x16x32_bf16 v[94:97], v[240:243], v[184:187], v[94:97]
	v_mfma_f32_16x16x32_bf16 v[90:93], v[248:251], v[184:187], v[90:93]
	v_mfma_f32_16x16x32_bf16 v[86:89], v[240:243], v[192:195], v[86:89]
	v_mfma_f32_16x16x32_bf16 v[82:85], v[248:251], v[192:195], v[82:85]
	v_mfma_f32_16x16x32_bf16 v[78:81], v[240:243], v[200:203], v[78:81]
	v_mfma_f32_16x16x32_bf16 v[74:77], v[248:251], v[200:203], v[74:77]
	v_mfma_f32_16x16x32_bf16 v[70:73], v[240:243], v[232:235], v[70:73]
	v_mfma_f32_16x16x32_bf16 v[66:69], v[248:251], v[232:235], v[66:69]
	s_mov_b32 m0, s1
	s_barrier
	ds_read_b128 v[180:183], v0 offset:16384
	ds_read_b128 v[184:187], v0 offset:17408
	ds_read_b128 v[188:191], v0 offset:18432
	ds_read_b128 v[192:195], v0 offset:19456
	ds_read_b128 v[196:199], v0 offset:20480
	ds_read_b128 v[200:203], v0 offset:21504
	ds_read_b128 v[222:225], v0 offset:22528
	ds_read_b128 v[232:235], v0 offset:23552
	global_load_lds_dwordx4 v228, s[98:99]
	s_add_i32 m0, s1, 0x1f00
	s_nop 0
	global_load_lds_dwordx4 v205, s[98:99] offset:256
	s_barrier
	s_waitcnt lgkmcnt(0)
	v_mfma_f32_16x16x32_bf16 v[62:65], v[164:167], v[180:183], v[62:65]
	v_mfma_f32_16x16x32_bf16 v[58:61], v[172:175], v[180:183], v[58:61]
	v_mfma_f32_16x16x32_bf16 v[54:57], v[164:167], v[188:191], v[54:57]
	v_mfma_f32_16x16x32_bf16 v[50:53], v[172:175], v[188:191], v[50:53]
	v_mfma_f32_16x16x32_bf16 v[46:49], v[164:167], v[196:199], v[46:49]
	v_mfma_f32_16x16x32_bf16 v[42:45], v[172:175], v[196:199], v[42:45]
	v_mfma_f32_16x16x32_bf16 v[38:41], v[164:167], v[222:225], v[38:41]
	v_mfma_f32_16x16x32_bf16 v[34:37], v[172:175], v[222:225], v[34:37]
	v_mfma_f32_16x16x32_bf16 v[62:65], v[168:171], v[184:187], v[62:65]
	v_mfma_f32_16x16x32_bf16 v[58:61], v[176:179], v[184:187], v[58:61]
	v_mfma_f32_16x16x32_bf16 v[54:57], v[168:171], v[192:195], v[54:57]
	v_mfma_f32_16x16x32_bf16 v[50:53], v[176:179], v[192:195], v[50:53]
	v_mfma_f32_16x16x32_bf16 v[46:49], v[168:171], v[200:203], v[46:49]
	v_mfma_f32_16x16x32_bf16 v[42:45], v[176:179], v[200:203], v[42:45]
	v_mfma_f32_16x16x32_bf16 v[38:41], v[168:171], v[232:235], v[38:41]
	v_mfma_f32_16x16x32_bf16 v[34:37], v[176:179], v[232:235], v[34:37]
	s_barrier
	s_add_i32 m0, s1, 0x14000
	s_nop 0
	global_load_lds_dwordx4 v218, vcc
	s_add_i32 m0, s1, 0x16000
	s_nop 0
	global_load_lds_dwordx4 v219, vcc
	s_waitcnt vmcnt(6)
	s_barrier
	v_mfma_f32_16x16x32_bf16 v[30:33], v[236:239], v[180:183], v[30:33]
	v_mfma_f32_16x16x32_bf16 v[26:29], v[244:247], v[180:183], v[26:29]
	v_mfma_f32_16x16x32_bf16 v[22:25], v[236:239], v[188:191], v[22:25]
	v_mfma_f32_16x16x32_bf16 v[18:21], v[244:247], v[188:191], v[18:21]
	v_mfma_f32_16x16x32_bf16 v[14:17], v[236:239], v[196:199], v[14:17]
	v_mfma_f32_16x16x32_bf16 v[10:13], v[244:247], v[196:199], v[10:13]
	v_mfma_f32_16x16x32_bf16 v[6:9], v[236:239], v[222:225], v[6:9]
	v_mfma_f32_16x16x32_bf16 v[2:5], v[244:247], v[222:225], v[2:5]
	v_mfma_f32_16x16x32_bf16 v[30:33], v[240:243], v[184:187], v[30:33]
	v_mfma_f32_16x16x32_bf16 v[26:29], v[248:251], v[184:187], v[26:29]
	v_mfma_f32_16x16x32_bf16 v[22:25], v[240:243], v[192:195], v[22:25]
	v_mfma_f32_16x16x32_bf16 v[18:21], v[248:251], v[192:195], v[18:21]
	v_mfma_f32_16x16x32_bf16 v[14:17], v[240:243], v[200:203], v[14:17]
	v_mfma_f32_16x16x32_bf16 v[10:13], v[248:251], v[200:203], v[10:13]
	v_mfma_f32_16x16x32_bf16 v[6:9], v[240:243], v[232:235], v[6:9]
	v_mfma_f32_16x16x32_bf16 v[2:5], v[248:251], v[232:235], v[2:5]
	s_barrier
	ds_read_b128 v[164:167], v151 offset:32768
	ds_read_b128 v[168:171], v151 offset:33792
	ds_read_b128 v[172:175], v151 offset:34816
	ds_read_b128 v[176:179], v151 offset:35840
	s_add_i32 m0, s1, 0x3f80
	ds_read_b128 v[180:183], v0 offset:32768
	ds_read_b128 v[184:187], v0 offset:33792
	ds_read_b128 v[188:191], v0 offset:34816
	ds_read_b128 v[192:195], v0 offset:35840
	ds_read_b128 v[196:199], v0 offset:36864
	ds_read_b128 v[200:203], v0 offset:37888
	ds_read_b128 v[222:225], v0 offset:38912
	ds_read_b128 v[232:235], v0 offset:39936
	global_load_lds_dwordx4 v216, s[98:99] offset:128
	s_add_i32 m0, s1, 0x5f80
	s_nop 0
	global_load_lds_dwordx4 v217, s[98:99] offset:128
	s_waitcnt lgkmcnt(8)
	s_barrier
	s_waitcnt lgkmcnt(0)
	v_mfma_f32_16x16x32_bf16 v[126:129], v[164:167], v[180:183], v[126:129]
	v_mfma_f32_16x16x32_bf16 v[122:125], v[172:175], v[180:183], v[122:125]
	v_mfma_f32_16x16x32_bf16 v[118:121], v[164:167], v[188:191], v[118:121]
	v_mfma_f32_16x16x32_bf16 v[114:117], v[172:175], v[188:191], v[114:117]
	v_mfma_f32_16x16x32_bf16 v[110:113], v[164:167], v[196:199], v[110:113]
	v_mfma_f32_16x16x32_bf16 v[106:109], v[172:175], v[196:199], v[106:109]
	v_mfma_f32_16x16x32_bf16 v[102:105], v[164:167], v[222:225], v[102:105]
	v_mfma_f32_16x16x32_bf16 v[98:101], v[172:175], v[222:225], v[98:101]
	v_mfma_f32_16x16x32_bf16 v[126:129], v[168:171], v[184:187], v[126:129]
	v_mfma_f32_16x16x32_bf16 v[122:125], v[176:179], v[184:187], v[122:125]
	v_mfma_f32_16x16x32_bf16 v[118:121], v[168:171], v[192:195], v[118:121]
	v_mfma_f32_16x16x32_bf16 v[114:117], v[176:179], v[192:195], v[114:117]
	v_mfma_f32_16x16x32_bf16 v[110:113], v[168:171], v[200:203], v[110:113]
	v_mfma_f32_16x16x32_bf16 v[106:109], v[176:179], v[200:203], v[106:109]
	v_mfma_f32_16x16x32_bf16 v[102:105], v[168:171], v[232:235], v[102:105]
	v_mfma_f32_16x16x32_bf16 v[98:101], v[176:179], v[232:235], v[98:101]
	s_barrier
	s_add_i32 m0, s1, 0x17e80
	ds_read_b128 v[236:239], v151 offset:49152
	ds_read_b128 v[240:243], v151 offset:50176
	ds_read_b128 v[244:247], v151 offset:51200
	ds_read_b128 v[248:251], v151 offset:52224
	global_load_lds_dwordx4 v210, vcc offset:384
	s_add_i32 m0, s1, 0x19e80
	s_nop 0
	global_load_lds_dwordx4 v211, vcc offset:384
	s_barrier
	s_waitcnt lgkmcnt(0)
	v_mfma_f32_16x16x32_bf16 v[94:97], v[236:239], v[180:183], v[94:97]
	v_mfma_f32_16x16x32_bf16 v[90:93], v[244:247], v[180:183], v[90:93]
	v_mfma_f32_16x16x32_bf16 v[86:89], v[236:239], v[188:191], v[86:89]
	v_mfma_f32_16x16x32_bf16 v[82:85], v[244:247], v[188:191], v[82:85]
	v_mfma_f32_16x16x32_bf16 v[78:81], v[236:239], v[196:199], v[78:81]
	v_mfma_f32_16x16x32_bf16 v[74:77], v[244:247], v[196:199], v[74:77]
	v_mfma_f32_16x16x32_bf16 v[70:73], v[236:239], v[222:225], v[70:73]
	v_mfma_f32_16x16x32_bf16 v[66:69], v[244:247], v[222:225], v[66:69]
	v_mfma_f32_16x16x32_bf16 v[94:97], v[240:243], v[184:187], v[94:97]
	v_mfma_f32_16x16x32_bf16 v[90:93], v[248:251], v[184:187], v[90:93]
	v_mfma_f32_16x16x32_bf16 v[86:89], v[240:243], v[192:195], v[86:89]
	v_mfma_f32_16x16x32_bf16 v[82:85], v[248:251], v[192:195], v[82:85]
	v_mfma_f32_16x16x32_bf16 v[78:81], v[240:243], v[200:203], v[78:81]
	v_mfma_f32_16x16x32_bf16 v[74:77], v[248:251], v[200:203], v[74:77]
	v_mfma_f32_16x16x32_bf16 v[70:73], v[240:243], v[232:235], v[70:73]
	v_mfma_f32_16x16x32_bf16 v[66:69], v[248:251], v[232:235], v[66:69]
	s_add_i32 m0, s1, 0x7e80
	s_barrier
	ds_read_b128 v[180:183], v0 offset:49152
	ds_read_b128 v[184:187], v0 offset:50176
	ds_read_b128 v[188:191], v0 offset:51200
	ds_read_b128 v[192:195], v0 offset:52224
	ds_read_b128 v[196:199], v0 offset:53248
	ds_read_b128 v[200:203], v0 offset:54272
	ds_read_b128 v[222:225], v0 offset:55296
	ds_read_b128 v[232:235], v0 offset:56320
	global_load_lds_dwordx4 v204, s[98:99] offset:384
	s_add_i32 m0, s1, 0x9e80
	s_nop 0
	global_load_lds_dwordx4 v205, s[98:99] offset:384
	s_barrier
	s_waitcnt lgkmcnt(0)
	v_mfma_f32_16x16x32_bf16 v[62:65], v[164:167], v[180:183], v[62:65]
	v_mfma_f32_16x16x32_bf16 v[58:61], v[172:175], v[180:183], v[58:61]
	v_mfma_f32_16x16x32_bf16 v[54:57], v[164:167], v[188:191], v[54:57]
	v_mfma_f32_16x16x32_bf16 v[50:53], v[172:175], v[188:191], v[50:53]
	v_mfma_f32_16x16x32_bf16 v[46:49], v[164:167], v[196:199], v[46:49]
	v_mfma_f32_16x16x32_bf16 v[42:45], v[172:175], v[196:199], v[42:45]
	v_mfma_f32_16x16x32_bf16 v[38:41], v[164:167], v[222:225], v[38:41]
	v_mfma_f32_16x16x32_bf16 v[34:37], v[172:175], v[222:225], v[34:37]
	v_mfma_f32_16x16x32_bf16 v[62:65], v[168:171], v[184:187], v[62:65]
	v_mfma_f32_16x16x32_bf16 v[58:61], v[176:179], v[184:187], v[58:61]
	v_mfma_f32_16x16x32_bf16 v[54:57], v[168:171], v[192:195], v[54:57]
	v_mfma_f32_16x16x32_bf16 v[50:53], v[176:179], v[192:195], v[50:53]
	v_mfma_f32_16x16x32_bf16 v[46:49], v[168:171], v[200:203], v[46:49]
	v_mfma_f32_16x16x32_bf16 v[42:45], v[176:179], v[200:203], v[42:45]
	v_mfma_f32_16x16x32_bf16 v[38:41], v[168:171], v[232:235], v[38:41]
	v_mfma_f32_16x16x32_bf16 v[34:37], v[176:179], v[232:235], v[34:37]
	s_barrier
	s_add_i32 m0, s1, 0x1bf80
	s_nop 0
	global_load_lds_dwordx4 v218, vcc offset:128
	s_add_i32 m0, s1, 0x1df80
	s_nop 0
	global_load_lds_dwordx4 v219, vcc offset:128
	s_waitcnt vmcnt(6)
	s_barrier
	v_mfma_f32_16x16x32_bf16 v[30:33], v[236:239], v[180:183], v[30:33]
	v_mfma_f32_16x16x32_bf16 v[26:29], v[244:247], v[180:183], v[26:29]
	v_mfma_f32_16x16x32_bf16 v[22:25], v[236:239], v[188:191], v[22:25]
	v_mfma_f32_16x16x32_bf16 v[18:21], v[244:247], v[188:191], v[18:21]
	v_mfma_f32_16x16x32_bf16 v[14:17], v[236:239], v[196:199], v[14:17]
	v_mfma_f32_16x16x32_bf16 v[10:13], v[244:247], v[196:199], v[10:13]
	v_mfma_f32_16x16x32_bf16 v[6:9], v[236:239], v[222:225], v[6:9]
	v_mfma_f32_16x16x32_bf16 v[2:5], v[244:247], v[222:225], v[2:5]
	v_mfma_f32_16x16x32_bf16 v[30:33], v[240:243], v[184:187], v[30:33]
	v_mfma_f32_16x16x32_bf16 v[26:29], v[248:251], v[184:187], v[26:29]
	v_mfma_f32_16x16x32_bf16 v[22:25], v[240:243], v[192:195], v[22:25]
	v_mfma_f32_16x16x32_bf16 v[18:21], v[248:251], v[192:195], v[18:21]
	v_mfma_f32_16x16x32_bf16 v[14:17], v[240:243], v[200:203], v[14:17]
	v_mfma_f32_16x16x32_bf16 v[10:13], v[248:251], v[200:203], v[10:13]
	v_mfma_f32_16x16x32_bf16 v[6:9], v[240:243], v[232:235], v[6:9]
	v_mfma_f32_16x16x32_bf16 v[2:5], v[248:251], v[232:235], v[2:5]
	s_add_i32 s0, s0, 2
	s_add_u32 s12, s12, 0x100
	s_addc_u32 s13, s13, 0
	s_add_u32 s98, s98, 0x100
	s_addc_u32 s99, s99, 0
	s_add_u32 vcc_lo, vcc_lo, 0x100
	s_addc_u32 vcc_hi, vcc_hi, 0
	s_cmp_lt_u32 s0, 28
	s_barrier
	s_cbranch_scc1 .LBB0_180
	s_add_i32 s1, s1, 0x1e000
	s_mov_b64 s[12:13], 0xf80
	v_readfirstlane_b32 s0, v162
	v_lshl_add_u64 v[132:133], v[132:133], 0, s[12:13]
	s_mov_b32 m0, s0
	v_readfirstlane_b32 s0, v163
	ds_read_b128 v[134:137], v151
	ds_read_b128 v[138:141], v151 offset:1024
	ds_read_b128 v[152:155], v151 offset:2048
	ds_read_b128 v[156:159], v151 offset:3072
	ds_read_b128 v[164:167], v0
	ds_read_b128 v[168:171], v0 offset:1024
	ds_read_b128 v[172:175], v0 offset:2048
	ds_read_b128 v[176:179], v0 offset:3072
	ds_read_b128 v[180:183], v0 offset:4096
	ds_read_b128 v[184:187], v0 offset:5120
	ds_read_b128 v[188:191], v0 offset:6144
	ds_read_b128 v[192:195], v0 offset:7168
	global_load_lds_dwordx4 v[132:133], off
	v_lshl_add_u64 v[130:131], v[130:131], 0, s[12:13]
	s_mov_b32 m0, s0
	s_nop 0
	global_load_lds_dwordx4 v[130:131], off
	s_barrier
	s_waitcnt lgkmcnt(0)
	s_setprio 1
	s_waitcnt lgkmcnt(0)
	v_mfma_f32_16x16x32_bf16 v[126:129], v[134:137], v[164:167], v[126:129]
	v_mfma_f32_16x16x32_bf16 v[122:125], v[152:155], v[164:167], v[122:125]
	v_mfma_f32_16x16x32_bf16 v[114:117], v[152:155], v[172:175], v[114:117]
	v_mfma_f32_16x16x32_bf16 v[106:109], v[152:155], v[180:183], v[106:109]
	v_mfma_f32_16x16x32_bf16 v[98:101], v[152:155], v[188:191], v[98:101]
	v_mfma_f32_16x16x32_bf16 v[126:129], v[138:141], v[168:171], v[126:129]
	v_mfma_f32_16x16x32_bf16 v[122:125], v[156:159], v[168:171], v[122:125]
	v_mfma_f32_16x16x32_bf16 v[118:121], v[134:137], v[172:175], v[118:121]
	v_mfma_f32_16x16x32_bf16 v[114:117], v[156:159], v[176:179], v[114:117]
	v_mfma_f32_16x16x32_bf16 v[110:113], v[134:137], v[180:183], v[110:113]
	v_mfma_f32_16x16x32_bf16 v[106:109], v[156:159], v[184:187], v[106:109]
	v_mfma_f32_16x16x32_bf16 v[102:105], v[134:137], v[188:191], v[102:105]
	v_mfma_f32_16x16x32_bf16 v[98:101], v[156:159], v[192:195], v[98:101]
	v_mfma_f32_16x16x32_bf16 v[130:133], v[138:141], v[176:179], v[118:121]
	v_mfma_f32_16x16x32_bf16 v[160:163], v[138:141], v[184:187], v[110:113]
	v_mfma_f32_16x16x32_bf16 v[196:199], v[138:141], v[192:195], v[102:105]
	s_setprio 0
	s_barrier
	s_nop 0
	ds_read_b128 v[102:105], v151 offset:16384
	ds_read_b128 v[110:113], v151 offset:17408
	ds_read_b128 v[118:121], v151 offset:18432
	ds_read_b128 v[200:203], v151 offset:19456
	s_barrier
	s_waitcnt lgkmcnt(0)
	s_setprio 1
	s_waitcnt lgkmcnt(1)
	v_mfma_f32_16x16x32_bf16 v[90:93], v[118:121], v[164:167], v[90:93]
	v_mfma_f32_16x16x32_bf16 v[82:85], v[118:121], v[172:175], v[82:85]
	v_mfma_f32_16x16x32_bf16 v[74:77], v[118:121], v[180:183], v[74:77]
	v_mfma_f32_16x16x32_bf16 v[66:69], v[118:121], v[188:191], v[66:69]
	v_mfma_f32_16x16x32_bf16 v[94:97], v[102:105], v[164:167], v[94:97]
	s_waitcnt lgkmcnt(0)
	v_mfma_f32_16x16x32_bf16 v[90:93], v[200:203], v[168:171], v[90:93]
	v_mfma_f32_16x16x32_bf16 v[86:89], v[102:105], v[172:175], v[86:89]
	v_mfma_f32_16x16x32_bf16 v[82:85], v[200:203], v[176:179], v[82:85]
	v_mfma_f32_16x16x32_bf16 v[78:81], v[102:105], v[180:183], v[78:81]
	v_mfma_f32_16x16x32_bf16 v[74:77], v[200:203], v[184:187], v[74:77]
	v_mfma_f32_16x16x32_bf16 v[70:73], v[102:105], v[188:191], v[70:73]
	v_mfma_f32_16x16x32_bf16 v[66:69], v[200:203], v[192:195], v[66:69]
	v_mfma_f32_16x16x32_bf16 v[222:225], v[110:113], v[168:171], v[94:97]
	v_mfma_f32_16x16x32_bf16 v[164:167], v[110:113], v[176:179], v[86:89]
	v_mfma_f32_16x16x32_bf16 v[168:171], v[110:113], v[184:187], v[78:81]
	v_mfma_f32_16x16x32_bf16 v[172:175], v[110:113], v[192:195], v[70:73]
	s_setprio 0
	s_barrier
	s_nop 0
	ds_read_b128 v[70:73], v0 offset:16384
	ds_read_b128 v[78:81], v0 offset:17408
	ds_read_b128 v[86:89], v0 offset:18432
	ds_read_b128 v[94:97], v0 offset:19456
	ds_read_b128 v[176:179], v0 offset:20480
	ds_read_b128 v[180:183], v0 offset:21504
	ds_read_b128 v[184:187], v0 offset:22528
	ds_read_b128 v[188:191], v0 offset:23552
	s_waitcnt vmcnt(4)
	s_barrier
	s_waitcnt lgkmcnt(0)
	s_setprio 1
	s_waitcnt lgkmcnt(7)
	v_mfma_f32_16x16x32_bf16 v[62:65], v[134:137], v[70:73], v[62:65]
	v_mfma_f32_16x16x32_bf16 v[58:61], v[152:155], v[70:73], v[58:61]
	s_waitcnt lgkmcnt(5)
	v_mfma_f32_16x16x32_bf16 v[50:53], v[152:155], v[86:89], v[50:53]
	s_waitcnt lgkmcnt(3)
	v_mfma_f32_16x16x32_bf16 v[42:45], v[152:155], v[176:179], v[42:45]
	s_waitcnt lgkmcnt(1)
	v_mfma_f32_16x16x32_bf16 v[34:37], v[152:155], v[184:187], v[34:37]
	v_mfma_f32_16x16x32_bf16 v[62:65], v[138:141], v[78:81], v[62:65]
	v_mfma_f32_16x16x32_bf16 v[58:61], v[156:159], v[78:81], v[58:61]
	v_mfma_f32_16x16x32_bf16 v[54:57], v[134:137], v[86:89], v[54:57]
	v_mfma_f32_16x16x32_bf16 v[50:53], v[156:159], v[94:97], v[50:53]
	v_mfma_f32_16x16x32_bf16 v[46:49], v[134:137], v[176:179], v[46:49]
	v_mfma_f32_16x16x32_bf16 v[42:45], v[156:159], v[180:183], v[42:45]
	v_mfma_f32_16x16x32_bf16 v[38:41], v[134:137], v[184:187], v[38:41]
	s_waitcnt lgkmcnt(0)
	v_mfma_f32_16x16x32_bf16 v[34:37], v[156:159], v[188:191], v[34:37]
	v_mfma_f32_16x16x32_bf16 v[192:195], v[138:141], v[94:97], v[54:57]
	v_mfma_f32_16x16x32_bf16 v[232:235], v[138:141], v[180:183], v[46:49]
	v_mfma_f32_16x16x32_bf16 v[134:137], v[138:141], v[188:191], v[38:41]
	s_setprio 0
	s_setprio 1
	v_mfma_f32_16x16x32_bf16 v[26:29], v[118:121], v[70:73], v[26:29]
	v_mfma_f32_16x16x32_bf16 v[18:21], v[118:121], v[86:89], v[18:21]
	v_mfma_f32_16x16x32_bf16 v[10:13], v[118:121], v[176:179], v[10:13]
	v_mfma_f32_16x16x32_bf16 v[2:5], v[118:121], v[184:187], v[2:5]
	v_mfma_f32_16x16x32_bf16 v[30:33], v[102:105], v[70:73], v[30:33]
	v_mfma_f32_16x16x32_bf16 v[26:29], v[200:203], v[78:81], v[26:29]
	v_mfma_f32_16x16x32_bf16 v[22:25], v[102:105], v[86:89], v[22:25]
	v_mfma_f32_16x16x32_bf16 v[18:21], v[200:203], v[94:97], v[18:21]
	v_mfma_f32_16x16x32_bf16 v[14:17], v[102:105], v[176:179], v[14:17]
	v_mfma_f32_16x16x32_bf16 v[10:13], v[200:203], v[180:183], v[10:13]
	v_mfma_f32_16x16x32_bf16 v[6:9], v[102:105], v[184:187], v[6:9]
	v_mfma_f32_16x16x32_bf16 v[2:5], v[200:203], v[188:191], v[2:5]
	v_mfma_f32_16x16x32_bf16 v[138:141], v[110:113], v[78:81], v[30:33]
	v_mfma_f32_16x16x32_bf16 v[152:155], v[110:113], v[94:97], v[22:25]
	v_mfma_f32_16x16x32_bf16 v[156:159], v[110:113], v[180:183], v[14:17]
	v_mfma_f32_16x16x32_bf16 v[176:179], v[110:113], v[188:191], v[6:9]
	s_setprio 0
	s_barrier
	s_nop 0
	ds_read_b128 v[6:9], v151 offset:32768
	ds_read_b128 v[14:17], v151 offset:33792
	ds_read_b128 v[180:183], v151 offset:34816
	ds_read_b128 v[184:187], v151 offset:35840
	ds_read_b128 v[22:25], v0 offset:32768
	ds_read_b128 v[30:33], v0 offset:33792
	ds_read_b128 v[38:41], v0 offset:34816
	ds_read_b128 v[46:49], v0 offset:35840
	ds_read_b128 v[54:57], v0 offset:36864
	ds_read_b128 v[188:191], v0 offset:37888
	ds_read_b128 v[200:203], v0 offset:38912
	ds_read_b128 v[236:239], v0 offset:39936
	s_waitcnt vmcnt(2)
	s_barrier
	s_waitcnt lgkmcnt(0)
	s_setprio 1
	s_waitcnt lgkmcnt(7)
	v_mfma_f32_16x16x32_bf16 v[70:73], v[6:9], v[22:25], v[126:129]
	s_waitcnt lgkmcnt(6)
	v_mfma_f32_16x16x32_bf16 v[126:129], v[14:17], v[30:33], v[70:73]
	v_mfma_f32_16x16x32_bf16 v[70:73], v[180:183], v[22:25], v[122:125]
	v_mfma_f32_16x16x32_bf16 v[118:121], v[184:187], v[30:33], v[70:73]
	s_waitcnt lgkmcnt(5)
	v_mfma_f32_16x16x32_bf16 v[70:73], v[6:9], v[38:41], v[130:133]
	s_waitcnt lgkmcnt(4)
	v_mfma_f32_16x16x32_bf16 v[110:113], v[14:17], v[46:49], v[70:73]
	v_mfma_f32_16x16x32_bf16 v[70:73], v[180:183], v[38:41], v[114:117]
	v_mfma_f32_16x16x32_bf16 v[102:105], v[184:187], v[46:49], v[70:73]
	s_waitcnt lgkmcnt(3)
	v_mfma_f32_16x16x32_bf16 v[70:73], v[6:9], v[54:57], v[160:163]
	s_waitcnt lgkmcnt(2)
	v_mfma_f32_16x16x32_bf16 v[94:97], v[14:17], v[188:191], v[70:73]
	v_mfma_f32_16x16x32_bf16 v[70:73], v[180:183], v[54:57], v[106:109]
	v_mfma_f32_16x16x32_bf16 v[86:89], v[184:187], v[188:191], v[70:73]
	s_waitcnt lgkmcnt(1)
	v_mfma_f32_16x16x32_bf16 v[70:73], v[6:9], v[200:203], v[196:199]
	s_waitcnt lgkmcnt(0)
	v_mfma_f32_16x16x32_bf16 v[78:81], v[14:17], v[236:239], v[70:73]
	v_mfma_f32_16x16x32_bf16 v[70:73], v[180:183], v[200:203], v[98:101]
	v_mfma_f32_16x16x32_bf16 v[70:73], v[184:187], v[236:239], v[70:73]
	s_setprio 0
	s_barrier
	ds_read_b128 v[130:133], v151 offset:49152
	ds_read_b128 v[160:163], v151 offset:50176
	ds_read_b128 v[196:199], v151 offset:51200
	ds_read_b128 v[148:151], v151 offset:52224
	s_waitcnt vmcnt(0)
	s_barrier
	s_waitcnt lgkmcnt(0)
	s_setprio 1
	s_waitcnt lgkmcnt(3)
	v_mfma_f32_16x16x32_bf16 v[98:101], v[130:133], v[22:25], v[222:225]
	s_waitcnt lgkmcnt(1)
	v_mfma_f32_16x16x32_bf16 v[22:25], v[196:199], v[22:25], v[90:93]
	s_waitcnt lgkmcnt(0)
	v_mfma_f32_16x16x32_bf16 v[114:117], v[148:151], v[30:33], v[22:25]
	v_mfma_f32_16x16x32_bf16 v[22:25], v[130:133], v[38:41], v[164:167]
	v_mfma_f32_16x16x32_bf16 v[106:109], v[160:163], v[46:49], v[22:25]
	v_mfma_f32_16x16x32_bf16 v[22:25], v[196:199], v[38:41], v[82:85]
	v_mfma_f32_16x16x32_bf16 v[122:125], v[160:163], v[30:33], v[98:101]
	v_mfma_f32_16x16x32_bf16 v[98:101], v[148:151], v[46:49], v[22:25]
	v_mfma_f32_16x16x32_bf16 v[22:25], v[130:133], v[54:57], v[168:171]
	v_mfma_f32_16x16x32_bf16 v[90:93], v[160:163], v[188:191], v[22:25]
	v_mfma_f32_16x16x32_bf16 v[22:25], v[196:199], v[54:57], v[74:77]
	v_mfma_f32_16x16x32_bf16 v[82:85], v[148:151], v[188:191], v[22:25]
	v_mfma_f32_16x16x32_bf16 v[22:25], v[130:133], v[200:203], v[172:175]
	v_mfma_f32_16x16x32_bf16 v[74:77], v[160:163], v[236:239], v[22:25]
	v_mfma_f32_16x16x32_bf16 v[22:25], v[196:199], v[200:203], v[66:69]
	v_mfma_f32_16x16x32_bf16 v[66:69], v[148:151], v[236:239], v[22:25]
	s_setprio 0
	s_barrier
	ds_read_b128 v[164:167], v0 offset:49152
	ds_read_b128 v[168:171], v0 offset:50176
	ds_read_b128 v[172:175], v0 offset:51200
	ds_read_b128 v[188:191], v0 offset:52224
	ds_read_b128 v[200:203], v0 offset:53248
	ds_read_b128 v[222:225], v0 offset:54272
	ds_read_b128 v[236:239], v0 offset:55296
	ds_read_b128 v[240:243], v0 offset:56320
	s_barrier
	s_waitcnt lgkmcnt(0)
	s_setprio 1
	s_waitcnt lgkmcnt(7)
	v_mfma_f32_16x16x32_bf16 v[22:25], v[6:9], v[164:167], v[62:65]
	s_waitcnt lgkmcnt(6)
	v_mfma_f32_16x16x32_bf16 v[62:65], v[14:17], v[168:171], v[22:25]
	v_mfma_f32_16x16x32_bf16 v[22:25], v[180:183], v[164:167], v[58:61]
	v_mfma_f32_16x16x32_bf16 v[54:57], v[184:187], v[168:171], v[22:25]
	s_waitcnt lgkmcnt(5)
	v_mfma_f32_16x16x32_bf16 v[22:25], v[6:9], v[172:175], v[192:195]
	s_waitcnt lgkmcnt(4)
	v_mfma_f32_16x16x32_bf16 v[46:49], v[14:17], v[188:191], v[22:25]
	v_mfma_f32_16x16x32_bf16 v[22:25], v[180:183], v[172:175], v[50:53]
	v_mfma_f32_16x16x32_bf16 v[38:41], v[184:187], v[188:191], v[22:25]
	s_waitcnt lgkmcnt(3)
	v_mfma_f32_16x16x32_bf16 v[22:25], v[6:9], v[200:203], v[232:235]
	s_waitcnt lgkmcnt(1)
	v_mfma_f32_16x16x32_bf16 v[6:9], v[6:9], v[236:239], v[134:137]
	v_mfma_f32_16x16x32_bf16 v[30:33], v[14:17], v[222:225], v[22:25]
	v_mfma_f32_16x16x32_bf16 v[22:25], v[180:183], v[200:203], v[42:45]
	s_waitcnt lgkmcnt(0)
	v_mfma_f32_16x16x32_bf16 v[14:17], v[14:17], v[240:243], v[6:9]
	v_mfma_f32_16x16x32_bf16 v[6:9], v[180:183], v[236:239], v[34:37]
	v_mfma_f32_16x16x32_bf16 v[22:25], v[184:187], v[222:225], v[22:25]
	v_mfma_f32_16x16x32_bf16 v[6:9], v[184:187], v[240:243], v[6:9]
	s_setprio 0
	s_setprio 1
	v_mfma_f32_16x16x32_bf16 v[34:37], v[130:133], v[164:167], v[138:141]
	v_mfma_f32_16x16x32_bf16 v[26:29], v[196:199], v[164:167], v[26:29]
	v_mfma_f32_16x16x32_bf16 v[18:21], v[196:199], v[172:175], v[18:21]
	v_mfma_f32_16x16x32_bf16 v[58:61], v[160:163], v[168:171], v[34:37]
	v_mfma_f32_16x16x32_bf16 v[50:53], v[148:151], v[168:171], v[26:29]
	v_mfma_f32_16x16x32_bf16 v[26:29], v[130:133], v[172:175], v[152:155]
	v_mfma_f32_16x16x32_bf16 v[34:37], v[148:151], v[188:191], v[18:21]
	v_mfma_f32_16x16x32_bf16 v[18:21], v[130:133], v[200:203], v[156:159]
	v_mfma_f32_16x16x32_bf16 v[10:13], v[196:199], v[200:203], v[10:13]
	v_mfma_f32_16x16x32_bf16 v[42:45], v[160:163], v[188:191], v[26:29]
	v_mfma_f32_16x16x32_bf16 v[26:29], v[160:163], v[222:225], v[18:21]
	v_mfma_f32_16x16x32_bf16 v[18:21], v[148:151], v[222:225], v[10:13]
	v_mfma_f32_16x16x32_bf16 v[10:13], v[130:133], v[236:239], v[176:179]
	v_mfma_f32_16x16x32_bf16 v[2:5], v[196:199], v[236:239], v[2:5]
	v_mfma_f32_16x16x32_bf16 v[10:13], v[160:163], v[240:243], v[10:13]
	v_mfma_f32_16x16x32_bf16 v[2:5], v[148:151], v[240:243], v[2:5]
	s_setprio 0
	s_movk_i32 s0, 0x100
	v_cmp_gt_u32_e32 vcc, s0, v142
	s_barrier
	s_and_saveexec_b64 s[0:1], vcc
	s_cbranch_execz .LBB0_183
	s_barrier

.LBB0_677:
	s_or_b64 exec, exec, s[16:17]
	v_mov_b32_e32 v3, v1
	v_lshl_add_u64 v[12:13], s[0:1], 0, v[2:3]
	v_lshl_add_u64 v[16:17], s[10:11], 0, v[2:3]
	v_lshl_add_u64 v[20:21], s[12:13], 0, v[2:3]
	v_lshl_add_u64 v[130:131], s[14:15], 0, v[2:3]
	v_and_b32_e32 v146, 15, v142
	v_bfe_u32 v145, v142, 4, 2
	v_lshlrev_b32_e32 v3, 2, v142
	v_add_u32_e32 v156, 0x18000, v147
	v_lshl_add_u64 v[10:11], s[0:1], 0, v[0:1]
	v_lshl_add_u64 v[14:15], s[10:11], 0, v[0:1]
	v_lshl_add_u64 v[18:19], s[12:13], 0, v[0:1]
	v_lshl_add_u64 v[132:133], s[14:15], 0, v[0:1]
	v_lshlrev_b32_e32 v0, 6, v146
	v_lshlrev_b32_e32 v2, 4, v145
	v_and_b32_e32 v3, 32, v3
	s_mov_b64 s[10:11], 0x80
	v_readfirstlane_b32 s0, v156
	v_add_u32_e32 v157, 0x1a000, v147
	v_bitop3_b32 v22, v2, v3, v0 bitop3:0x36
	v_lshl_add_u64 v[2:3], v[10:11], 0, s[10:11]
	s_mov_b32 m0, s0
	v_readfirstlane_b32 s0, v157
	v_add_u32_e32 v158, 0x8000, v147
	s_waitcnt vmcnt(4)
	s_barrier
	global_load_lds_dwordx4 v[2:3], off
	v_lshl_add_u64 v[2:3], v[12:13], 0, s[10:11]
	s_mov_b32 m0, s0
	v_readfirstlane_b32 s0, v158
	v_add_u32_e32 v159, 0xa000, v147
	global_load_lds_dwordx4 v[2:3], off
	v_lshl_add_u64 v[2:3], v[14:15], 0, s[10:11]
	s_mov_b32 m0, s0
	v_readfirstlane_b32 s0, v159
	v_add_u32_e32 v160, 0x1c000, v147
	global_load_lds_dwordx4 v[2:3], off
	v_lshl_add_u64 v[2:3], v[16:17], 0, s[10:11]
	s_mov_b32 m0, s0
	v_readfirstlane_b32 s0, v160
	v_add_u32_e32 v161, 0x1e000, v147
	global_load_lds_dwordx4 v[2:3], off
	v_lshl_add_u64 v[2:3], v[18:19], 0, s[10:11]
	s_mov_b32 m0, s0
	v_readfirstlane_b32 s0, v161
	global_load_lds_dwordx4 v[2:3], off
	v_lshl_add_u64 v[2:3], v[20:21], 0, s[10:11]
	s_mov_b32 m0, s0
	s_sub_i32 s1, s57, s64
	global_load_lds_dwordx4 v[2:3], off
	s_sub_i32 s1, s1, s63
	v_lshlrev_b32_e32 v0, 15, v4
	s_sext_i32_i16 s1, s1
	v_and_b32_e32 v0, 0xffff0000, v0
	s_lshl_b32 s0, s62, 10
	s_lshl_b32 s1, s1, 8
	v_lshl_add_u32 v0, v5, 12, v0
	v_and_b32_e32 v2, 1, v4
	s_add_i32 s0, s0, s1
	v_lshl_or_b32 v0, v2, 6, v0
	v_lshlrev_b32_e32 v2, 15, v6
	s_ashr_i32 s1, s0, 31
	v_and_b32_e32 v2, 0xffff0000, v2
	s_lshl_b64 s[0:1], s[0:1], 12
	v_lshl_add_u32 v2, v8, 12, v2
	v_and_b32_e32 v3, 1, v6
	s_add_u32 s0, s52, s0
	v_lshl_or_b32 v2, v3, 6, v2
	v_lshl_add_u32 v0, v7, 1, v0
	s_addc_u32 s1, s53, s1
	v_lshl_add_u32 v2, v9, 1, v2
	v_mov_b32_e32 v3, v1
	v_lshl_add_u64 v[134:135], s[0:1], 0, v[0:1]
	v_lshl_add_u64 v[136:137], s[0:1], 0, v[2:3]
	s_add_u32 s0, s88, s8
	v_bfe_u32 v144, v142, 6, 2
	s_waitcnt vmcnt(6)
	s_addc_u32 s1, s89, s9
	v_lshlrev_b32_e32 v23, 13, v143
	v_lshl_or_b32 v24, v144, 12, v212
	v_lshl_add_u64 v[140:141], s[0:1], 0, v[2:3]
	v_mov_b32_e32 v2, 0
	v_lshl_add_u64 v[138:139], s[0:1], 0, v[0:1]
	s_mov_b32 s0, -2
	s_mov_b64 s[8:9], 0
	v_add_u32_e32 v151, v24, v22
	v_add_u32_e32 v0, v23, v22
	v_mov_b32_e32 v3, v2
	v_mov_b32_e32 v4, v2
	v_mov_b32_e32 v5, v2
	v_mov_b32_e32 v6, v2
	v_mov_b32_e32 v7, v2
	v_mov_b32_e32 v8, v2
	v_mov_b32_e32 v9, v2
	v_mov_b32_e32 v10, v2
	v_mov_b32_e32 v11, v2
	v_mov_b32_e32 v12, v2
	v_mov_b32_e32 v13, v2
	v_mov_b32_e32 v14, v2
	v_mov_b32_e32 v15, v2
	v_mov_b32_e32 v16, v2
	v_mov_b32_e32 v17, v2
	v_mov_b32_e32 v18, v2
	v_mov_b32_e32 v19, v2
	v_mov_b32_e32 v20, v2
	v_mov_b32_e32 v21, v2
	v_mov_b32_e32 v22, v2
	v_mov_b32_e32 v23, v2
	v_mov_b32_e32 v24, v2
	v_mov_b32_e32 v25, v2
	v_mov_b32_e32 v26, v2
	v_mov_b32_e32 v27, v2
	v_mov_b32_e32 v28, v2
	v_mov_b32_e32 v29, v2
	v_mov_b32_e32 v30, v2
	v_mov_b32_e32 v31, v2
	v_mov_b32_e32 v32, v2
	v_mov_b32_e32 v33, v2
	v_mov_b32_e32 v34, v2
	v_mov_b32_e32 v35, v2
	v_mov_b32_e32 v36, v2
	v_mov_b32_e32 v37, v2
	v_mov_b32_e32 v38, v2
	v_mov_b32_e32 v39, v2
	v_mov_b32_e32 v40, v2
	v_mov_b32_e32 v41, v2
	v_mov_b32_e32 v42, v2
	v_mov_b32_e32 v43, v2
	v_mov_b32_e32 v44, v2
	v_mov_b32_e32 v45, v2
	v_mov_b32_e32 v46, v2
	v_mov_b32_e32 v47, v2
	v_mov_b32_e32 v48, v2
	v_mov_b32_e32 v49, v2
	v_mov_b32_e32 v50, v2
	v_mov_b32_e32 v51, v2
	v_mov_b32_e32 v52, v2
	v_mov_b32_e32 v53, v2
	v_mov_b32_e32 v54, v2
	v_mov_b32_e32 v55, v2
	v_mov_b32_e32 v56, v2
	v_mov_b32_e32 v57, v2
	v_mov_b32_e32 v58, v2
	v_mov_b32_e32 v59, v2
	v_mov_b32_e32 v60, v2
	v_mov_b32_e32 v61, v2
	v_mov_b32_e32 v62, v2
	v_mov_b32_e32 v63, v2
	v_mov_b32_e32 v64, v2
	v_mov_b32_e32 v65, v2
	v_mov_b32_e32 v66, v2
	v_mov_b32_e32 v67, v2
	v_mov_b32_e32 v68, v2
	v_mov_b32_e32 v69, v2
	v_mov_b32_e32 v70, v2
	v_mov_b32_e32 v71, v2
	v_mov_b32_e32 v72, v2
	v_mov_b32_e32 v73, v2
	v_mov_b32_e32 v74, v2
	v_mov_b32_e32 v75, v2
	v_mov_b32_e32 v76, v2
	v_mov_b32_e32 v77, v2
	v_mov_b32_e32 v78, v2
	v_mov_b32_e32 v79, v2
	v_mov_b32_e32 v80, v2
	v_mov_b32_e32 v81, v2
	v_mov_b32_e32 v82, v2
	v_mov_b32_e32 v83, v2
	v_mov_b32_e32 v84, v2
	v_mov_b32_e32 v85, v2
	v_mov_b32_e32 v86, v2
	v_mov_b32_e32 v87, v2
	v_mov_b32_e32 v88, v2
	v_mov_b32_e32 v89, v2
	v_mov_b32_e32 v90, v2
	v_mov_b32_e32 v91, v2
	v_mov_b32_e32 v92, v2
	v_mov_b32_e32 v93, v2
	v_mov_b32_e32 v94, v2
	v_mov_b32_e32 v95, v2
	v_mov_b32_e32 v96, v2
	v_mov_b32_e32 v97, v2
	v_mov_b32_e32 v98, v2
	v_mov_b32_e32 v99, v2
	v_mov_b32_e32 v100, v2
	v_mov_b32_e32 v101, v2
	v_mov_b32_e32 v102, v2
	v_mov_b32_e32 v103, v2
	v_mov_b32_e32 v104, v2
	v_mov_b32_e32 v105, v2
	v_mov_b32_e32 v106, v2
	v_mov_b32_e32 v107, v2
	v_mov_b32_e32 v108, v2
	v_mov_b32_e32 v109, v2
	v_mov_b32_e32 v110, v2
	v_mov_b32_e32 v111, v2
	v_mov_b32_e32 v112, v2
	v_mov_b32_e32 v113, v2
	v_mov_b32_e32 v114, v2
	v_mov_b32_e32 v115, v2
	v_mov_b32_e32 v116, v2
	v_mov_b32_e32 v117, v2
	v_mov_b32_e32 v118, v2
	v_mov_b32_e32 v119, v2
	v_mov_b32_e32 v120, v2
	v_mov_b32_e32 v121, v2
	v_mov_b32_e32 v122, v2
	v_mov_b32_e32 v123, v2
	v_mov_b32_e32 v124, v2
	v_mov_b32_e32 v125, v2
	v_mov_b32_e32 v126, v2
	v_mov_b32_e32 v127, v2
	v_mov_b32_e32 v128, v2
	v_mov_b32_e32 v129, v2
	s_barrier
	v_add_u32_e32 v162, 0xc000, v147
	v_add_u32_e32 v163, 0xe000, v147
	v_readfirstlane_b32 s1, v147
	s_nop 1
	v_readfirstlane_b32 s98, v138
	v_readfirstlane_b32 s99, v139
	s_nop 3
	s_sub_u32 s98, s98, 0x400000
	s_subb_u32 s99, s99, 0
	v_subrev_u32_e32 v204, s98, v138
	v_add_u32_e32 v210, 0x80080, v204
	v_subrev_u32_e32 v205, s98, v140
	v_add_u32_e32 v211, 0x80080, v205
	v_readfirstlane_b32 vcc_lo, v134
	v_readfirstlane_b32 vcc_hi, v135
	s_nop 3
	s_sub_u32 vcc_lo, vcc_lo, 0x400000
	s_subb_u32 vcc_hi, vcc_hi, 0
	v_subrev_u32_e32 v216, vcc_lo, v134
	v_add_u32_e32 v228, 0x80100, v216
	v_subrev_u32_e32 v217, vcc_lo, v136
	v_add_u32_e32 v229, 0x80100, v217
	v_add_u32_e32 v218, 0x100, v204
	s_add_u32 s98, s98, s8
	s_addc_u32 s99, s99, s9
	s_add_u32 vcc_lo, vcc_lo, s8
	s_addc_u32 vcc_hi, vcc_hi, s9
	s_nop 4
.LBB0_678:
	ds_read_b128 v[164:167], v151
	ds_read_b128 v[168:171], v151 offset:1024
	ds_read_b128 v[172:175], v151 offset:2048
	ds_read_b128 v[176:179], v151 offset:3072
	s_add_i32 m0, s1, 0xc000
	ds_read_b128 v[180:183], v0
	ds_read_b128 v[184:187], v0 offset:1024
	ds_read_b128 v[188:191], v0 offset:2048
	ds_read_b128 v[192:195], v0 offset:3072
	ds_read_b128 v[196:199], v0 offset:4096
	ds_read_b128 v[200:203], v0 offset:5120
	ds_read_b128 v[232:235], v0 offset:6144
	ds_read_b128 v[236:239], v0 offset:7168
	global_load_lds_dwordx4 v210, s[98:99]
	s_add_i32 m0, s1, 0xe000
	s_nop 0
	global_load_lds_dwordx4 v211, s[98:99]
	s_waitcnt lgkmcnt(8)
	s_barrier
	s_waitcnt lgkmcnt(0)
	v_mfma_f32_16x16x32_bf16 v[126:129], v[164:167], v[180:183], v[126:129]
	v_mfma_f32_16x16x32_bf16 v[122:125], v[172:175], v[180:183], v[122:125]
	v_mfma_f32_16x16x32_bf16 v[118:121], v[164:167], v[188:191], v[118:121]
	v_mfma_f32_16x16x32_bf16 v[114:117], v[172:175], v[188:191], v[114:117]
	v_mfma_f32_16x16x32_bf16 v[110:113], v[164:167], v[196:199], v[110:113]
	v_mfma_f32_16x16x32_bf16 v[106:109], v[172:175], v[196:199], v[106:109]
	v_mfma_f32_16x16x32_bf16 v[102:105], v[164:167], v[232:235], v[102:105]
	v_mfma_f32_16x16x32_bf16 v[98:101], v[172:175], v[232:235], v[98:101]
	v_mfma_f32_16x16x32_bf16 v[126:129], v[168:171], v[184:187], v[126:129]
	v_mfma_f32_16x16x32_bf16 v[122:125], v[176:179], v[184:187], v[122:125]
	v_mfma_f32_16x16x32_bf16 v[118:121], v[168:171], v[192:195], v[118:121]
	v_mfma_f32_16x16x32_bf16 v[114:117], v[176:179], v[192:195], v[114:117]
	v_mfma_f32_16x16x32_bf16 v[110:113], v[168:171], v[200:203], v[110:113]
	v_mfma_f32_16x16x32_bf16 v[106:109], v[176:179], v[200:203], v[106:109]
	v_mfma_f32_16x16x32_bf16 v[102:105], v[168:171], v[236:239], v[102:105]
	v_mfma_f32_16x16x32_bf16 v[98:101], v[176:179], v[236:239], v[98:101]
	s_barrier
	s_add_i32 m0, s1, 0xff00
	ds_read_b128 v[240:243], v151 offset:16384
	ds_read_b128 v[244:247], v151 offset:17408
	ds_read_b128 v[248:251], v151 offset:18432
	ds_read_b128 v[222:225], v151 offset:19456
	global_load_lds_dwordx4 v216, vcc offset:256
	s_add_i32 m0, s1, 0x11f00
	s_nop 0
	global_load_lds_dwordx4 v217, vcc offset:256
	s_barrier
	s_waitcnt lgkmcnt(0)
	v_mfma_f32_16x16x32_bf16 v[94:97], v[240:243], v[180:183], v[94:97]
	v_mfma_f32_16x16x32_bf16 v[90:93], v[248:251], v[180:183], v[90:93]
	v_mfma_f32_16x16x32_bf16 v[86:89], v[240:243], v[188:191], v[86:89]
	v_mfma_f32_16x16x32_bf16 v[82:85], v[248:251], v[188:191], v[82:85]
	v_mfma_f32_16x16x32_bf16 v[78:81], v[240:243], v[196:199], v[78:81]
	v_mfma_f32_16x16x32_bf16 v[74:77], v[248:251], v[196:199], v[74:77]
	v_mfma_f32_16x16x32_bf16 v[70:73], v[240:243], v[232:235], v[70:73]
	v_mfma_f32_16x16x32_bf16 v[66:69], v[248:251], v[232:235], v[66:69]
	v_mfma_f32_16x16x32_bf16 v[94:97], v[244:247], v[184:187], v[94:97]
	v_mfma_f32_16x16x32_bf16 v[90:93], v[222:225], v[184:187], v[90:93]
	v_mfma_f32_16x16x32_bf16 v[86:89], v[244:247], v[192:195], v[86:89]
	v_mfma_f32_16x16x32_bf16 v[82:85], v[222:225], v[192:195], v[82:85]
	v_mfma_f32_16x16x32_bf16 v[78:81], v[244:247], v[200:203], v[78:81]
	v_mfma_f32_16x16x32_bf16 v[74:77], v[222:225], v[200:203], v[74:77]
	v_mfma_f32_16x16x32_bf16 v[70:73], v[244:247], v[236:239], v[70:73]
	v_mfma_f32_16x16x32_bf16 v[66:69], v[222:225], v[236:239], v[66:69]
	s_mov_b32 m0, s1
	s_barrier
	ds_read_b128 v[180:183], v0 offset:16384
	ds_read_b128 v[184:187], v0 offset:17408
	ds_read_b128 v[188:191], v0 offset:18432
	ds_read_b128 v[192:195], v0 offset:19456
	ds_read_b128 v[196:199], v0 offset:20480
	ds_read_b128 v[200:203], v0 offset:21504
	ds_read_b128 v[232:235], v0 offset:22528
	ds_read_b128 v[236:239], v0 offset:23552
	global_load_lds_dwordx4 v218, s[98:99]
	s_add_i32 m0, s1, 0x1f00
	s_nop 0
	global_load_lds_dwordx4 v205, s[98:99] offset:256
	s_barrier
	s_waitcnt lgkmcnt(0)
	v_mfma_f32_16x16x32_bf16 v[62:65], v[164:167], v[180:183], v[62:65]
	v_mfma_f32_16x16x32_bf16 v[58:61], v[172:175], v[180:183], v[58:61]
	v_mfma_f32_16x16x32_bf16 v[54:57], v[164:167], v[188:191], v[54:57]
	v_mfma_f32_16x16x32_bf16 v[50:53], v[172:175], v[188:191], v[50:53]
	v_mfma_f32_16x16x32_bf16 v[46:49], v[164:167], v[196:199], v[46:49]
	v_mfma_f32_16x16x32_bf16 v[42:45], v[172:175], v[196:199], v[42:45]
	v_mfma_f32_16x16x32_bf16 v[38:41], v[164:167], v[232:235], v[38:41]
	v_mfma_f32_16x16x32_bf16 v[34:37], v[172:175], v[232:235], v[34:37]
	v_mfma_f32_16x16x32_bf16 v[62:65], v[168:171], v[184:187], v[62:65]
	v_mfma_f32_16x16x32_bf16 v[58:61], v[176:179], v[184:187], v[58:61]
	v_mfma_f32_16x16x32_bf16 v[54:57], v[168:171], v[192:195], v[54:57]
	v_mfma_f32_16x16x32_bf16 v[50:53], v[176:179], v[192:195], v[50:53]
	v_mfma_f32_16x16x32_bf16 v[46:49], v[168:171], v[200:203], v[46:49]
	v_mfma_f32_16x16x32_bf16 v[42:45], v[176:179], v[200:203], v[42:45]
	v_mfma_f32_16x16x32_bf16 v[38:41], v[168:171], v[236:239], v[38:41]
	v_mfma_f32_16x16x32_bf16 v[34:37], v[176:179], v[236:239], v[34:37]
	s_barrier
	s_add_i32 m0, s1, 0x14000
	s_nop 0
	global_load_lds_dwordx4 v228, vcc
	s_add_i32 m0, s1, 0x16000
	s_nop 0
	global_load_lds_dwordx4 v229, vcc
	s_waitcnt vmcnt(6)
	s_barrier
	v_mfma_f32_16x16x32_bf16 v[30:33], v[240:243], v[180:183], v[30:33]
	v_mfma_f32_16x16x32_bf16 v[26:29], v[248:251], v[180:183], v[26:29]
	v_mfma_f32_16x16x32_bf16 v[22:25], v[240:243], v[188:191], v[22:25]
	v_mfma_f32_16x16x32_bf16 v[18:21], v[248:251], v[188:191], v[18:21]
	v_mfma_f32_16x16x32_bf16 v[14:17], v[240:243], v[196:199], v[14:17]
	v_mfma_f32_16x16x32_bf16 v[10:13], v[248:251], v[196:199], v[10:13]
	v_mfma_f32_16x16x32_bf16 v[6:9], v[240:243], v[232:235], v[6:9]
	v_mfma_f32_16x16x32_bf16 v[2:5], v[248:251], v[232:235], v[2:5]
	v_mfma_f32_16x16x32_bf16 v[30:33], v[244:247], v[184:187], v[30:33]
	v_mfma_f32_16x16x32_bf16 v[26:29], v[222:225], v[184:187], v[26:29]
	v_mfma_f32_16x16x32_bf16 v[22:25], v[244:247], v[192:195], v[22:25]
	v_mfma_f32_16x16x32_bf16 v[18:21], v[222:225], v[192:195], v[18:21]
	v_mfma_f32_16x16x32_bf16 v[14:17], v[244:247], v[200:203], v[14:17]
	v_mfma_f32_16x16x32_bf16 v[10:13], v[222:225], v[200:203], v[10:13]
	v_mfma_f32_16x16x32_bf16 v[6:9], v[244:247], v[236:239], v[6:9]
	v_mfma_f32_16x16x32_bf16 v[2:5], v[222:225], v[236:239], v[2:5]
	s_barrier
	ds_read_b128 v[164:167], v151 offset:32768
	ds_read_b128 v[168:171], v151 offset:33792
	ds_read_b128 v[172:175], v151 offset:34816
	ds_read_b128 v[176:179], v151 offset:35840
	s_add_i32 m0, s1, 0x3f80
	ds_read_b128 v[180:183], v0 offset:32768
	ds_read_b128 v[184:187], v0 offset:33792
	ds_read_b128 v[188:191], v0 offset:34816
	ds_read_b128 v[192:195], v0 offset:35840
	ds_read_b128 v[196:199], v0 offset:36864
	ds_read_b128 v[200:203], v0 offset:37888
	ds_read_b128 v[222:225], v0 offset:38912
	ds_read_b128 v[232:235], v0 offset:39936
	global_load_lds_dwordx4 v210, s[98:99] offset:128
	s_add_i32 m0, s1, 0x5f80
	s_nop 0
	global_load_lds_dwordx4 v211, s[98:99] offset:128
	s_waitcnt lgkmcnt(8)
	s_barrier
	s_waitcnt lgkmcnt(0)
	v_mfma_f32_16x16x32_bf16 v[126:129], v[164:167], v[180:183], v[126:129]
	v_mfma_f32_16x16x32_bf16 v[122:125], v[172:175], v[180:183], v[122:125]
	v_mfma_f32_16x16x32_bf16 v[118:121], v[164:167], v[188:191], v[118:121]
	v_mfma_f32_16x16x32_bf16 v[114:117], v[172:175], v[188:191], v[114:117]
	v_mfma_f32_16x16x32_bf16 v[110:113], v[164:167], v[196:199], v[110:113]
	v_mfma_f32_16x16x32_bf16 v[106:109], v[172:175], v[196:199], v[106:109]
	v_mfma_f32_16x16x32_bf16 v[102:105], v[164:167], v[222:225], v[102:105]
	v_mfma_f32_16x16x32_bf16 v[98:101], v[172:175], v[222:225], v[98:101]
	v_mfma_f32_16x16x32_bf16 v[126:129], v[168:171], v[184:187], v[126:129]
	v_mfma_f32_16x16x32_bf16 v[122:125], v[176:179], v[184:187], v[122:125]
	v_mfma_f32_16x16x32_bf16 v[118:121], v[168:171], v[192:195], v[118:121]
	v_mfma_f32_16x16x32_bf16 v[114:117], v[176:179], v[192:195], v[114:117]
	v_mfma_f32_16x16x32_bf16 v[110:113], v[168:171], v[200:203], v[110:113]
	v_mfma_f32_16x16x32_bf16 v[106:109], v[176:179], v[200:203], v[106:109]
	v_mfma_f32_16x16x32_bf16 v[102:105], v[168:171], v[232:235], v[102:105]
	v_mfma_f32_16x16x32_bf16 v[98:101], v[176:179], v[232:235], v[98:101]
	s_barrier
	s_add_i32 m0, s1, 0x17e80
	ds_read_b128 v[236:239], v151 offset:49152
	ds_read_b128 v[240:243], v151 offset:50176
	ds_read_b128 v[244:247], v151 offset:51200
	ds_read_b128 v[248:251], v151 offset:52224
	global_load_lds_dwordx4 v216, vcc offset:384
	s_add_i32 m0, s1, 0x19e80
	s_nop 0
	global_load_lds_dwordx4 v217, vcc offset:384
	s_barrier
	s_waitcnt lgkmcnt(0)
	v_mfma_f32_16x16x32_bf16 v[94:97], v[236:239], v[180:183], v[94:97]
	v_mfma_f32_16x16x32_bf16 v[90:93], v[244:247], v[180:183], v[90:93]
	v_mfma_f32_16x16x32_bf16 v[86:89], v[236:239], v[188:191], v[86:89]
	v_mfma_f32_16x16x32_bf16 v[82:85], v[244:247], v[188:191], v[82:85]
	v_mfma_f32_16x16x32_bf16 v[78:81], v[236:239], v[196:199], v[78:81]
	v_mfma_f32_16x16x32_bf16 v[74:77], v[244:247], v[196:199], v[74:77]
	v_mfma_f32_16x16x32_bf16 v[70:73], v[236:239], v[222:225], v[70:73]
	v_mfma_f32_16x16x32_bf16 v[66:69], v[244:247], v[222:225], v[66:69]
	v_mfma_f32_16x16x32_bf16 v[94:97], v[240:243], v[184:187], v[94:97]
	v_mfma_f32_16x16x32_bf16 v[90:93], v[248:251], v[184:187], v[90:93]
	v_mfma_f32_16x16x32_bf16 v[86:89], v[240:243], v[192:195], v[86:89]
	v_mfma_f32_16x16x32_bf16 v[82:85], v[248:251], v[192:195], v[82:85]
	v_mfma_f32_16x16x32_bf16 v[78:81], v[240:243], v[200:203], v[78:81]
	v_mfma_f32_16x16x32_bf16 v[74:77], v[248:251], v[200:203], v[74:77]
	v_mfma_f32_16x16x32_bf16 v[70:73], v[240:243], v[232:235], v[70:73]
	v_mfma_f32_16x16x32_bf16 v[66:69], v[248:251], v[232:235], v[66:69]
	s_add_i32 m0, s1, 0x7e80
	s_barrier
	ds_read_b128 v[180:183], v0 offset:49152
	ds_read_b128 v[184:187], v0 offset:50176
	ds_read_b128 v[188:191], v0 offset:51200
	ds_read_b128 v[192:195], v0 offset:52224
	ds_read_b128 v[196:199], v0 offset:53248
	ds_read_b128 v[200:203], v0 offset:54272
	ds_read_b128 v[222:225], v0 offset:55296
	ds_read_b128 v[232:235], v0 offset:56320
	global_load_lds_dwordx4 v204, s[98:99] offset:384
	s_add_i32 m0, s1, 0x9e80
	s_nop 0
	global_load_lds_dwordx4 v205, s[98:99] offset:384
	s_barrier
	s_waitcnt lgkmcnt(0)
	v_mfma_f32_16x16x32_bf16 v[62:65], v[164:167], v[180:183], v[62:65]
	v_mfma_f32_16x16x32_bf16 v[58:61], v[172:175], v[180:183], v[58:61]
	v_mfma_f32_16x16x32_bf16 v[54:57], v[164:167], v[188:191], v[54:57]
	v_mfma_f32_16x16x32_bf16 v[50:53], v[172:175], v[188:191], v[50:53]
	v_mfma_f32_16x16x32_bf16 v[46:49], v[164:167], v[196:199], v[46:49]
	v_mfma_f32_16x16x32_bf16 v[42:45], v[172:175], v[196:199], v[42:45]
	v_mfma_f32_16x16x32_bf16 v[38:41], v[164:167], v[222:225], v[38:41]
	v_mfma_f32_16x16x32_bf16 v[34:37], v[172:175], v[222:225], v[34:37]
	v_mfma_f32_16x16x32_bf16 v[62:65], v[168:171], v[184:187], v[62:65]
	v_mfma_f32_16x16x32_bf16 v[58:61], v[176:179], v[184:187], v[58:61]
	v_mfma_f32_16x16x32_bf16 v[54:57], v[168:171], v[192:195], v[54:57]
	v_mfma_f32_16x16x32_bf16 v[50:53], v[176:179], v[192:195], v[50:53]
	v_mfma_f32_16x16x32_bf16 v[46:49], v[168:171], v[200:203], v[46:49]
	v_mfma_f32_16x16x32_bf16 v[42:45], v[176:179], v[200:203], v[42:45]
	v_mfma_f32_16x16x32_bf16 v[38:41], v[168:171], v[232:235], v[38:41]
	v_mfma_f32_16x16x32_bf16 v[34:37], v[176:179], v[232:235], v[34:37]
	s_barrier
	s_add_i32 m0, s1, 0x1bf80
	s_nop 0
	global_load_lds_dwordx4 v228, vcc offset:128
	s_add_i32 m0, s1, 0x1df80
	s_nop 0
	global_load_lds_dwordx4 v229, vcc offset:128
	s_waitcnt vmcnt(6)
	s_barrier
	v_mfma_f32_16x16x32_bf16 v[30:33], v[236:239], v[180:183], v[30:33]
	v_mfma_f32_16x16x32_bf16 v[26:29], v[244:247], v[180:183], v[26:29]
	v_mfma_f32_16x16x32_bf16 v[22:25], v[236:239], v[188:191], v[22:25]
	v_mfma_f32_16x16x32_bf16 v[18:21], v[244:247], v[188:191], v[18:21]
	v_mfma_f32_16x16x32_bf16 v[14:17], v[236:239], v[196:199], v[14:17]
	v_mfma_f32_16x16x32_bf16 v[10:13], v[244:247], v[196:199], v[10:13]
	v_mfma_f32_16x16x32_bf16 v[6:9], v[236:239], v[222:225], v[6:9]
	v_mfma_f32_16x16x32_bf16 v[2:5], v[244:247], v[222:225], v[2:5]
	v_mfma_f32_16x16x32_bf16 v[30:33], v[240:243], v[184:187], v[30:33]
	v_mfma_f32_16x16x32_bf16 v[26:29], v[248:251], v[184:187], v[26:29]
	v_mfma_f32_16x16x32_bf16 v[22:25], v[240:243], v[192:195], v[22:25]
	v_mfma_f32_16x16x32_bf16 v[18:21], v[248:251], v[192:195], v[18:21]
	v_mfma_f32_16x16x32_bf16 v[14:17], v[240:243], v[200:203], v[14:17]
	v_mfma_f32_16x16x32_bf16 v[10:13], v[248:251], v[200:203], v[10:13]
	v_mfma_f32_16x16x32_bf16 v[6:9], v[240:243], v[232:235], v[6:9]
	v_mfma_f32_16x16x32_bf16 v[2:5], v[248:251], v[232:235], v[2:5]
	s_add_i32 s0, s0, 2
	s_add_u32 s8, s8, 0x100
	s_addc_u32 s9, s9, 0
	s_add_u32 s98, s98, 0x100
	s_addc_u32 s99, s99, 0
	s_add_u32 vcc_lo, vcc_lo, 0x100
	s_addc_u32 vcc_hi, vcc_hi, 0
	s_cmp_lt_u32 s0, 28
	s_barrier
	s_cbranch_scc1 .LBB0_678
	s_add_i32 s1, s1, 0x1e000
	s_mov_b64 s[8:9], 0xf80
	v_readfirstlane_b32 s0, v162
	v_lshl_add_u64 v[132:133], v[132:133], 0, s[8:9]
	s_mov_b32 m0, s0
	v_readfirstlane_b32 s0, v163
	ds_read_b128 v[134:137], v151
	ds_read_b128 v[138:141], v151 offset:1024
	ds_read_b128 v[152:155], v151 offset:2048
	ds_read_b128 v[156:159], v151 offset:3072
	ds_read_b128 v[164:167], v0
	ds_read_b128 v[168:171], v0 offset:1024
	ds_read_b128 v[172:175], v0 offset:2048
	ds_read_b128 v[176:179], v0 offset:3072
	ds_read_b128 v[180:183], v0 offset:4096
	ds_read_b128 v[184:187], v0 offset:5120
	ds_read_b128 v[188:191], v0 offset:6144
	ds_read_b128 v[192:195], v0 offset:7168
	global_load_lds_dwordx4 v[132:133], off
	v_lshl_add_u64 v[130:131], v[130:131], 0, s[8:9]
	s_mov_b32 m0, s0
	s_nop 0
	global_load_lds_dwordx4 v[130:131], off
	s_barrier
	s_waitcnt lgkmcnt(0)
	s_setprio 1
	s_waitcnt lgkmcnt(0)
	v_mfma_f32_16x16x32_bf16 v[126:129], v[134:137], v[164:167], v[126:129]
	v_mfma_f32_16x16x32_bf16 v[122:125], v[152:155], v[164:167], v[122:125]
	v_mfma_f32_16x16x32_bf16 v[114:117], v[152:155], v[172:175], v[114:117]
	v_mfma_f32_16x16x32_bf16 v[106:109], v[152:155], v[180:183], v[106:109]
	v_mfma_f32_16x16x32_bf16 v[98:101], v[152:155], v[188:191], v[98:101]
	v_mfma_f32_16x16x32_bf16 v[126:129], v[138:141], v[168:171], v[126:129]
	v_mfma_f32_16x16x32_bf16 v[122:125], v[156:159], v[168:171], v[122:125]
	v_mfma_f32_16x16x32_bf16 v[118:121], v[134:137], v[172:175], v[118:121]
	v_mfma_f32_16x16x32_bf16 v[114:117], v[156:159], v[176:179], v[114:117]
	v_mfma_f32_16x16x32_bf16 v[110:113], v[134:137], v[180:183], v[110:113]
	v_mfma_f32_16x16x32_bf16 v[106:109], v[156:159], v[184:187], v[106:109]
	v_mfma_f32_16x16x32_bf16 v[102:105], v[134:137], v[188:191], v[102:105]
	v_mfma_f32_16x16x32_bf16 v[98:101], v[156:159], v[192:195], v[98:101]
	v_mfma_f32_16x16x32_bf16 v[130:133], v[138:141], v[176:179], v[118:121]
	v_mfma_f32_16x16x32_bf16 v[160:163], v[138:141], v[184:187], v[110:113]
	v_mfma_f32_16x16x32_bf16 v[196:199], v[138:141], v[192:195], v[102:105]
	s_setprio 0
	s_barrier
	s_nop 0
	ds_read_b128 v[102:105], v151 offset:16384
	ds_read_b128 v[110:113], v151 offset:17408
	ds_read_b128 v[118:121], v151 offset:18432
	ds_read_b128 v[200:203], v151 offset:19456
	s_barrier
	s_waitcnt lgkmcnt(0)
	s_setprio 1
	s_waitcnt lgkmcnt(1)
	v_mfma_f32_16x16x32_bf16 v[90:93], v[118:121], v[164:167], v[90:93]
	v_mfma_f32_16x16x32_bf16 v[86:89], v[102:105], v[172:175], v[86:89]
	v_mfma_f32_16x16x32_bf16 v[82:85], v[118:121], v[172:175], v[82:85]
	v_mfma_f32_16x16x32_bf16 v[78:81], v[102:105], v[180:183], v[78:81]
	v_mfma_f32_16x16x32_bf16 v[70:73], v[102:105], v[188:191], v[70:73]
	v_mfma_f32_16x16x32_bf16 v[94:97], v[102:105], v[164:167], v[94:97]
	s_waitcnt lgkmcnt(0)
	v_mfma_f32_16x16x32_bf16 v[90:93], v[200:203], v[168:171], v[90:93]
	v_mfma_f32_16x16x32_bf16 v[86:89], v[110:113], v[176:179], v[86:89]
	v_mfma_f32_16x16x32_bf16 v[82:85], v[200:203], v[176:179], v[82:85]
	v_mfma_f32_16x16x32_bf16 v[78:81], v[110:113], v[184:187], v[78:81]
	v_mfma_f32_16x16x32_bf16 v[74:77], v[118:121], v[180:183], v[74:77]
	v_mfma_f32_16x16x32_bf16 v[70:73], v[110:113], v[192:195], v[70:73]
	v_mfma_f32_16x16x32_bf16 v[66:69], v[118:121], v[188:191], v[66:69]
	v_mfma_f32_16x16x32_bf16 v[222:225], v[110:113], v[168:171], v[94:97]
	v_mfma_f32_16x16x32_bf16 v[164:167], v[200:203], v[184:187], v[74:77]
	v_mfma_f32_16x16x32_bf16 v[168:171], v[200:203], v[192:195], v[66:69]
	s_setprio 0
	s_barrier
	s_nop 2
	ds_read_b128 v[66:69], v0 offset:16384
	ds_read_b128 v[74:77], v0 offset:17408
	ds_read_b128 v[94:97], v0 offset:18432
	ds_read_b128 v[172:175], v0 offset:19456
	ds_read_b128 v[176:179], v0 offset:20480
	ds_read_b128 v[180:183], v0 offset:21504
	ds_read_b128 v[184:187], v0 offset:22528
	ds_read_b128 v[188:191], v0 offset:23552
	s_waitcnt vmcnt(4)
	s_barrier
	s_waitcnt lgkmcnt(0)
	s_setprio 1
	s_waitcnt lgkmcnt(5)
	v_mfma_f32_16x16x32_bf16 v[54:57], v[134:137], v[94:97], v[54:57]
	v_mfma_f32_16x16x32_bf16 v[50:53], v[152:155], v[94:97], v[50:53]
	v_mfma_f32_16x16x32_bf16 v[62:65], v[134:137], v[66:69], v[62:65]
	v_mfma_f32_16x16x32_bf16 v[58:61], v[152:155], v[66:69], v[58:61]
	s_waitcnt lgkmcnt(4)
	v_mfma_f32_16x16x32_bf16 v[54:57], v[138:141], v[172:175], v[54:57]
	v_mfma_f32_16x16x32_bf16 v[50:53], v[156:159], v[172:175], v[50:53]
	s_waitcnt lgkmcnt(3)
	v_mfma_f32_16x16x32_bf16 v[46:49], v[134:137], v[176:179], v[46:49]
	v_mfma_f32_16x16x32_bf16 v[42:45], v[152:155], v[176:179], v[42:45]
	s_waitcnt lgkmcnt(1)
	v_mfma_f32_16x16x32_bf16 v[38:41], v[134:137], v[184:187], v[38:41]
	v_mfma_f32_16x16x32_bf16 v[34:37], v[152:155], v[184:187], v[34:37]
	v_mfma_f32_16x16x32_bf16 v[192:195], v[138:141], v[74:77], v[62:65]
	v_mfma_f32_16x16x32_bf16 v[232:235], v[156:159], v[74:77], v[58:61]
	v_mfma_f32_16x16x32_bf16 v[236:239], v[138:141], v[180:183], v[46:49]
	v_mfma_f32_16x16x32_bf16 v[240:243], v[156:159], v[180:183], v[42:45]
	s_waitcnt lgkmcnt(0)
	v_mfma_f32_16x16x32_bf16 v[134:137], v[138:141], v[188:191], v[38:41]
	v_mfma_f32_16x16x32_bf16 v[138:141], v[156:159], v[188:191], v[34:37]
	s_setprio 0
	s_setprio 1
	v_mfma_f32_16x16x32_bf16 v[30:33], v[102:105], v[66:69], v[30:33]
	v_mfma_f32_16x16x32_bf16 v[26:29], v[118:121], v[66:69], v[26:29]
	v_mfma_f32_16x16x32_bf16 v[14:17], v[102:105], v[176:179], v[14:17]
	v_mfma_f32_16x16x32_bf16 v[10:13], v[118:121], v[176:179], v[10:13]
	v_mfma_f32_16x16x32_bf16 v[30:33], v[110:113], v[74:77], v[30:33]
	v_mfma_f32_16x16x32_bf16 v[26:29], v[200:203], v[74:77], v[26:29]
	v_mfma_f32_16x16x32_bf16 v[22:25], v[102:105], v[94:97], v[22:25]
	v_mfma_f32_16x16x32_bf16 v[18:21], v[118:121], v[94:97], v[18:21]
	v_mfma_f32_16x16x32_bf16 v[14:17], v[110:113], v[180:183], v[14:17]
	v_mfma_f32_16x16x32_bf16 v[10:13], v[200:203], v[180:183], v[10:13]
	v_mfma_f32_16x16x32_bf16 v[6:9], v[102:105], v[184:187], v[6:9]
	v_mfma_f32_16x16x32_bf16 v[2:5], v[118:121], v[184:187], v[2:5]
	v_mfma_f32_16x16x32_bf16 v[152:155], v[110:113], v[172:175], v[22:25]
	v_mfma_f32_16x16x32_bf16 v[156:159], v[200:203], v[172:175], v[18:21]
	v_mfma_f32_16x16x32_bf16 v[172:175], v[110:113], v[188:191], v[6:9]
	v_mfma_f32_16x16x32_bf16 v[176:179], v[200:203], v[188:191], v[2:5]
	s_setprio 0
	s_barrier
	s_nop 1
	ds_read_b128 v[2:5], v151 offset:32768
	ds_read_b128 v[6:9], v151 offset:33792
	ds_read_b128 v[180:183], v151 offset:34816
	ds_read_b128 v[184:187], v151 offset:35840
	ds_read_b128 v[18:21], v0 offset:32768
	ds_read_b128 v[22:25], v0 offset:33792
	ds_read_b128 v[38:41], v0 offset:34816
	ds_read_b128 v[46:49], v0 offset:35840
	ds_read_b128 v[58:61], v0 offset:36864
	ds_read_b128 v[66:69], v0 offset:37888
	ds_read_b128 v[188:191], v0 offset:38912
	ds_read_b128 v[200:203], v0 offset:39936
	s_waitcnt vmcnt(2)
	s_barrier
	s_waitcnt lgkmcnt(0)
	s_setprio 1
	s_waitcnt lgkmcnt(7)
	v_mfma_f32_16x16x32_bf16 v[34:37], v[2:5], v[18:21], v[126:129]
	s_waitcnt lgkmcnt(6)
	v_mfma_f32_16x16x32_bf16 v[118:121], v[6:9], v[22:25], v[34:37]
	v_mfma_f32_16x16x32_bf16 v[34:37], v[180:183], v[18:21], v[122:125]
	v_mfma_f32_16x16x32_bf16 v[110:113], v[184:187], v[22:25], v[34:37]
	s_waitcnt lgkmcnt(5)
	v_mfma_f32_16x16x32_bf16 v[34:37], v[2:5], v[38:41], v[130:133]
	s_waitcnt lgkmcnt(4)
	v_mfma_f32_16x16x32_bf16 v[102:105], v[6:9], v[46:49], v[34:37]
	v_mfma_f32_16x16x32_bf16 v[34:37], v[180:183], v[38:41], v[114:117]
	v_mfma_f32_16x16x32_bf16 v[94:97], v[184:187], v[46:49], v[34:37]
	s_waitcnt lgkmcnt(3)
	v_mfma_f32_16x16x32_bf16 v[34:37], v[2:5], v[58:61], v[160:163]
	s_waitcnt lgkmcnt(2)
	v_mfma_f32_16x16x32_bf16 v[74:77], v[6:9], v[66:69], v[34:37]
	v_mfma_f32_16x16x32_bf16 v[34:37], v[180:183], v[58:61], v[106:109]
	v_mfma_f32_16x16x32_bf16 v[62:65], v[184:187], v[66:69], v[34:37]
	s_waitcnt lgkmcnt(1)
	v_mfma_f32_16x16x32_bf16 v[34:37], v[2:5], v[188:191], v[196:199]
	s_waitcnt lgkmcnt(0)
	v_mfma_f32_16x16x32_bf16 v[42:45], v[6:9], v[200:203], v[34:37]
	v_mfma_f32_16x16x32_bf16 v[34:37], v[180:183], v[188:191], v[98:101]
	v_mfma_f32_16x16x32_bf16 v[34:37], v[184:187], v[200:203], v[34:37]
	s_setprio 0
	s_barrier
	ds_read_b128 v[130:133], v151 offset:49152
	ds_read_b128 v[160:163], v151 offset:50176
	ds_read_b128 v[196:199], v151 offset:51200
	ds_read_b128 v[148:151], v151 offset:52224
	s_waitcnt vmcnt(0)
	s_barrier
	s_waitcnt lgkmcnt(0)
	s_setprio 1
	s_waitcnt lgkmcnt(3)
	v_mfma_f32_16x16x32_bf16 v[98:101], v[130:133], v[18:21], v[222:225]
	s_waitcnt lgkmcnt(1)
	v_mfma_f32_16x16x32_bf16 v[18:21], v[196:199], v[18:21], v[90:93]
	s_waitcnt lgkmcnt(0)
	v_mfma_f32_16x16x32_bf16 v[122:125], v[148:151], v[22:25], v[18:21]
	v_mfma_f32_16x16x32_bf16 v[18:21], v[130:133], v[38:41], v[86:89]
	v_mfma_f32_16x16x32_bf16 v[114:117], v[160:163], v[46:49], v[18:21]
	v_mfma_f32_16x16x32_bf16 v[18:21], v[196:199], v[38:41], v[82:85]
	v_mfma_f32_16x16x32_bf16 v[106:109], v[148:151], v[46:49], v[18:21]
	v_mfma_f32_16x16x32_bf16 v[18:21], v[130:133], v[58:61], v[78:81]
	v_mfma_f32_16x16x32_bf16 v[126:129], v[160:163], v[22:25], v[98:101]
	v_mfma_f32_16x16x32_bf16 v[98:101], v[160:163], v[66:69], v[18:21]
	v_mfma_f32_16x16x32_bf16 v[18:21], v[196:199], v[58:61], v[164:167]
	v_mfma_f32_16x16x32_bf16 v[90:93], v[148:151], v[66:69], v[18:21]
	v_mfma_f32_16x16x32_bf16 v[18:21], v[130:133], v[188:191], v[70:73]
	v_mfma_f32_16x16x32_bf16 v[66:69], v[160:163], v[200:203], v[18:21]
	v_mfma_f32_16x16x32_bf16 v[18:21], v[196:199], v[188:191], v[168:171]
	v_mfma_f32_16x16x32_bf16 v[58:61], v[148:151], v[200:203], v[18:21]
	s_setprio 0
	s_barrier
	ds_read_b128 v[82:85], v0 offset:49152
	ds_read_b128 v[164:167], v0 offset:50176
	ds_read_b128 v[168:171], v0 offset:51200
	ds_read_b128 v[188:191], v0 offset:52224
	ds_read_b128 v[200:203], v0 offset:53248
	ds_read_b128 v[222:225], v0 offset:54272
	ds_read_b128 v[244:247], v0 offset:55296
	ds_read_b128 v[248:251], v0 offset:56320
	s_barrier
	s_waitcnt lgkmcnt(0)
	s_setprio 1
	s_waitcnt lgkmcnt(7)
	v_mfma_f32_16x16x32_bf16 v[18:21], v[2:5], v[82:85], v[192:195]
	s_waitcnt lgkmcnt(6)
	v_mfma_f32_16x16x32_bf16 v[78:81], v[6:9], v[164:167], v[18:21]
	v_mfma_f32_16x16x32_bf16 v[18:21], v[180:183], v[82:85], v[232:235]
	v_mfma_f32_16x16x32_bf16 v[70:73], v[184:187], v[164:167], v[18:21]
	s_waitcnt lgkmcnt(5)
	v_mfma_f32_16x16x32_bf16 v[18:21], v[2:5], v[168:171], v[54:57]
	s_waitcnt lgkmcnt(4)
	v_mfma_f32_16x16x32_bf16 v[46:49], v[6:9], v[188:191], v[18:21]
	v_mfma_f32_16x16x32_bf16 v[18:21], v[180:183], v[168:171], v[50:53]
	v_mfma_f32_16x16x32_bf16 v[38:41], v[184:187], v[188:191], v[18:21]
	s_waitcnt lgkmcnt(3)
	v_mfma_f32_16x16x32_bf16 v[18:21], v[2:5], v[200:203], v[236:239]
	s_waitcnt lgkmcnt(1)
	v_mfma_f32_16x16x32_bf16 v[2:5], v[2:5], v[244:247], v[134:137]
	v_mfma_f32_16x16x32_bf16 v[22:25], v[6:9], v[222:225], v[18:21]
	v_mfma_f32_16x16x32_bf16 v[18:21], v[180:183], v[200:203], v[240:243]
	s_waitcnt lgkmcnt(0)
	v_mfma_f32_16x16x32_bf16 v[6:9], v[6:9], v[248:251], v[2:5]
	v_mfma_f32_16x16x32_bf16 v[2:5], v[180:183], v[244:247], v[138:141]
	v_mfma_f32_16x16x32_bf16 v[18:21], v[184:187], v[222:225], v[18:21]
	v_mfma_f32_16x16x32_bf16 v[2:5], v[184:187], v[248:251], v[2:5]
	s_setprio 0
	s_setprio 1
	v_mfma_f32_16x16x32_bf16 v[26:29], v[196:199], v[82:85], v[26:29]
	v_mfma_f32_16x16x32_bf16 v[30:33], v[130:133], v[82:85], v[30:33]
	v_mfma_f32_16x16x32_bf16 v[82:85], v[148:151], v[164:167], v[26:29]
	v_mfma_f32_16x16x32_bf16 v[26:29], v[130:133], v[168:171], v[152:155]
	v_mfma_f32_16x16x32_bf16 v[54:57], v[160:163], v[188:191], v[26:29]
	v_mfma_f32_16x16x32_bf16 v[26:29], v[196:199], v[168:171], v[156:159]
	v_mfma_f32_16x16x32_bf16 v[10:13], v[196:199], v[200:203], v[10:13]
	v_mfma_f32_16x16x32_bf16 v[50:53], v[148:151], v[188:191], v[26:29]
	v_mfma_f32_16x16x32_bf16 v[14:17], v[130:133], v[200:203], v[14:17]
	v_mfma_f32_16x16x32_bf16 v[26:29], v[148:151], v[222:225], v[10:13]
	v_mfma_f32_16x16x32_bf16 v[10:13], v[130:133], v[244:247], v[172:175]
	v_mfma_f32_16x16x32_bf16 v[86:89], v[160:163], v[164:167], v[30:33]
	v_mfma_f32_16x16x32_bf16 v[30:33], v[160:163], v[222:225], v[14:17]
	v_mfma_f32_16x16x32_bf16 v[14:17], v[160:163], v[248:251], v[10:13]
	v_mfma_f32_16x16x32_bf16 v[10:13], v[196:199], v[244:247], v[176:179]
	v_mfma_f32_16x16x32_bf16 v[10:13], v[148:151], v[248:251], v[10:13]
	s_setprio 0
	s_movk_i32 s0, 0x100
	v_cmp_gt_u32_e32 vcc, s0, v142
	s_barrier
	s_and_saveexec_b64 s[0:1], vcc
	s_cbranch_execz .LBB0_674
	s_barrier
	s_branch .LBB0_674

.LBB0_689:
	ds_read_b128 v[104:107], v95
	ds_read_b128 v[108:111], v95 offset:1024
	ds_read_b128 v[112:115], v95 offset:2048
	ds_read_b128 v[116:119], v95 offset:3072
	v_lshl_add_u64 v[152:153], v[72:73], 0, s[10:11]
	v_lshl_add_u64 v[164:165], v[152:153], 0, s[34:35]
	s_add_i32 m0, s1, 0xc000
	ds_read_b128 v[120:123], v93
	ds_read_b128 v[124:127], v93 offset:1024
	ds_read_b128 v[128:131], v93 offset:2048
	ds_read_b128 v[132:135], v93 offset:3072
	ds_read_b128 v[136:139], v93 offset:4096
	ds_read_b128 v[140:143], v93 offset:5120
	ds_read_b128 v[144:147], v93 offset:6144
	ds_read_b128 v[148:151], v93 offset:7168
	global_load_lds_dwordx4 v[164:165], off
	v_lshl_add_u64 v[154:155], v[74:75], 0, s[10:11]
	s_add_i32 m0, s1, 0xe000
	v_lshl_add_u64 v[86:87], v[154:155], 0, s[34:35]
	global_load_lds_dwordx4 v[86:87], off
	s_waitcnt lgkmcnt(8)
	s_barrier
	s_waitcnt lgkmcnt(0)
	v_mfma_f32_16x16x32_bf16 v[62:65], v[104:107], v[120:123], v[62:65]
	v_mfma_f32_16x16x32_bf16 v[58:61], v[112:115], v[120:123], v[58:61]
	v_mfma_f32_16x16x32_bf16 v[54:57], v[104:107], v[128:131], v[54:57]
	v_mfma_f32_16x16x32_bf16 v[50:53], v[112:115], v[128:131], v[50:53]
	v_mfma_f32_16x16x32_bf16 v[46:49], v[104:107], v[136:139], v[46:49]
	v_mfma_f32_16x16x32_bf16 v[42:45], v[112:115], v[136:139], v[42:45]
	v_mfma_f32_16x16x32_bf16 v[38:41], v[104:107], v[144:147], v[38:41]
	v_mfma_f32_16x16x32_bf16 v[34:37], v[112:115], v[144:147], v[34:37]
	v_mfma_f32_16x16x32_bf16 v[62:65], v[108:111], v[124:127], v[62:65]
	v_mfma_f32_16x16x32_bf16 v[58:61], v[116:119], v[124:127], v[58:61]
	v_mfma_f32_16x16x32_bf16 v[54:57], v[108:111], v[132:135], v[54:57]
	v_mfma_f32_16x16x32_bf16 v[50:53], v[116:119], v[132:135], v[50:53]
	v_mfma_f32_16x16x32_bf16 v[46:49], v[108:111], v[140:143], v[46:49]
	v_mfma_f32_16x16x32_bf16 v[42:45], v[116:119], v[140:143], v[42:45]
	v_mfma_f32_16x16x32_bf16 v[38:41], v[108:111], v[148:151], v[38:41]
	v_mfma_f32_16x16x32_bf16 v[34:37], v[116:119], v[148:151], v[34:37]
	s_barrier
	v_lshl_add_u64 v[156:157], v[68:69], 0, s[10:11]
	s_add_i32 m0, s1, 0xff00
	s_nop 0
	global_load_lds_dwordx4 v[156:157], off offset:256
	v_lshl_add_u64 v[158:159], v[70:71], 0, s[10:11]
	s_add_i32 m0, s1, 0x11f00
	s_nop 0
	global_load_lds_dwordx4 v[158:159], off offset:256
	v_lshl_add_u64 v[88:89], v[152:153], 0, s[74:75]
	s_mov_b32 m0, s1
	s_barrier
	s_waitcnt lgkmcnt(0)
	s_barrier
	ds_read_b128 v[120:123], v93 offset:16384
	ds_read_b128 v[124:127], v93 offset:17408
	ds_read_b128 v[128:131], v93 offset:18432
	ds_read_b128 v[132:135], v93 offset:19456
	ds_read_b128 v[136:139], v93 offset:20480
	ds_read_b128 v[140:143], v93 offset:21504
	ds_read_b128 v[144:147], v93 offset:22528
	ds_read_b128 v[148:151], v93 offset:23552
	global_load_lds_dwordx4 v[88:89], off
	s_add_i32 m0, s1, 0x1f00
	s_nop 0
	global_load_lds_dwordx4 v[154:155], off offset:256
	s_barrier
	s_waitcnt lgkmcnt(0)
	v_mfma_f32_16x16x32_bf16 v[2:5], v[104:107], v[120:123], v[2:5]
	v_mfma_f32_16x16x32_bf16 v[6:9], v[112:115], v[120:123], v[6:9]
	v_mfma_f32_16x16x32_bf16 v[10:13], v[104:107], v[128:131], v[10:13]
	v_mfma_f32_16x16x32_bf16 v[14:17], v[112:115], v[128:131], v[14:17]
	v_mfma_f32_16x16x32_bf16 v[18:21], v[104:107], v[136:139], v[18:21]
	v_mfma_f32_16x16x32_bf16 v[22:25], v[112:115], v[136:139], v[22:25]
	v_mfma_f32_16x16x32_bf16 v[26:29], v[104:107], v[144:147], v[26:29]
	v_mfma_f32_16x16x32_bf16 v[30:33], v[112:115], v[144:147], v[30:33]
	v_mfma_f32_16x16x32_bf16 v[2:5], v[108:111], v[124:127], v[2:5]
	v_mfma_f32_16x16x32_bf16 v[6:9], v[116:119], v[124:127], v[6:9]
	v_mfma_f32_16x16x32_bf16 v[10:13], v[108:111], v[132:135], v[10:13]
	v_mfma_f32_16x16x32_bf16 v[14:17], v[116:119], v[132:135], v[14:17]
	v_mfma_f32_16x16x32_bf16 v[18:21], v[108:111], v[140:143], v[18:21]
	v_mfma_f32_16x16x32_bf16 v[22:25], v[116:119], v[140:143], v[22:25]
	v_mfma_f32_16x16x32_bf16 v[26:29], v[108:111], v[148:151], v[26:29]
	v_mfma_f32_16x16x32_bf16 v[30:33], v[116:119], v[148:151], v[30:33]
	s_barrier
	v_lshl_add_u64 v[160:161], v[76:77], 0, s[10:11]
	s_add_i32 m0, s1, 0x13f00
	s_nop 0
	global_load_lds_dwordx4 v[160:161], off offset:256
	s_add_i32 m0, s1, 0x15f00
	v_lshl_add_u64 v[162:163], v[78:79], 0, s[10:11]
	global_load_lds_dwordx4 v[162:163], off offset:256
	s_waitcnt vmcnt(6)
	s_barrier
	s_barrier
	ds_read_b128 v[104:107], v95 offset:32768
	ds_read_b128 v[108:111], v95 offset:33792
	ds_read_b128 v[112:115], v95 offset:34816
	ds_read_b128 v[116:119], v95 offset:35840
	s_add_i32 m0, s1, 0x3f80
	ds_read_b128 v[120:123], v93 offset:32768
	ds_read_b128 v[124:127], v93 offset:33792
	ds_read_b128 v[128:131], v93 offset:34816
	ds_read_b128 v[132:135], v93 offset:35840
	ds_read_b128 v[136:139], v93 offset:36864
	ds_read_b128 v[140:143], v93 offset:37888
	ds_read_b128 v[144:147], v93 offset:38912
	ds_read_b128 v[148:151], v93 offset:39936
	global_load_lds_dwordx4 v[164:165], off offset:128
	s_add_i32 m0, s1, 0x5f80
	s_nop 0
	global_load_lds_dwordx4 v[86:87], off offset:128
	s_waitcnt lgkmcnt(8)
	s_barrier
	s_waitcnt lgkmcnt(0)
	v_mfma_f32_16x16x32_bf16 v[62:65], v[104:107], v[120:123], v[62:65]
	v_mfma_f32_16x16x32_bf16 v[58:61], v[112:115], v[120:123], v[58:61]
	v_mfma_f32_16x16x32_bf16 v[54:57], v[104:107], v[128:131], v[54:57]
	v_mfma_f32_16x16x32_bf16 v[50:53], v[112:115], v[128:131], v[50:53]
	v_mfma_f32_16x16x32_bf16 v[46:49], v[104:107], v[136:139], v[46:49]
	v_mfma_f32_16x16x32_bf16 v[42:45], v[112:115], v[136:139], v[42:45]
	v_mfma_f32_16x16x32_bf16 v[38:41], v[104:107], v[144:147], v[38:41]
	v_mfma_f32_16x16x32_bf16 v[34:37], v[112:115], v[144:147], v[34:37]
	v_mfma_f32_16x16x32_bf16 v[62:65], v[108:111], v[124:127], v[62:65]
	v_mfma_f32_16x16x32_bf16 v[58:61], v[116:119], v[124:127], v[58:61]
	v_mfma_f32_16x16x32_bf16 v[54:57], v[108:111], v[132:135], v[54:57]
	v_mfma_f32_16x16x32_bf16 v[50:53], v[116:119], v[132:135], v[50:53]
	v_mfma_f32_16x16x32_bf16 v[46:49], v[108:111], v[140:143], v[46:49]
	v_mfma_f32_16x16x32_bf16 v[42:45], v[116:119], v[140:143], v[42:45]
	v_mfma_f32_16x16x32_bf16 v[38:41], v[108:111], v[148:151], v[38:41]
	v_mfma_f32_16x16x32_bf16 v[34:37], v[116:119], v[148:151], v[34:37]
	s_barrier
	s_add_i32 m0, s1, 0x17e80
	s_nop 0
	global_load_lds_dwordx4 v[156:157], off offset:384
	s_add_i32 m0, s1, 0x19e80
	s_nop 0
	global_load_lds_dwordx4 v[158:159], off offset:384
	s_add_i32 m0, s1, 0x7e80
	s_barrier
	s_waitcnt lgkmcnt(0)
	s_barrier
	ds_read_b128 v[120:123], v93 offset:49152
	ds_read_b128 v[124:127], v93 offset:50176
	ds_read_b128 v[128:131], v93 offset:51200
	ds_read_b128 v[132:135], v93 offset:52224
	ds_read_b128 v[136:139], v93 offset:53248
	ds_read_b128 v[140:143], v93 offset:54272
	ds_read_b128 v[144:147], v93 offset:55296
	ds_read_b128 v[148:151], v93 offset:56320
	global_load_lds_dwordx4 v[152:153], off offset:384
	s_add_i32 m0, s1, 0x9e80
	s_nop 0
	global_load_lds_dwordx4 v[154:155], off offset:384
	s_barrier
	s_waitcnt lgkmcnt(0)
	v_mfma_f32_16x16x32_bf16 v[2:5], v[104:107], v[120:123], v[2:5]
	v_mfma_f32_16x16x32_bf16 v[6:9], v[112:115], v[120:123], v[6:9]
	v_mfma_f32_16x16x32_bf16 v[10:13], v[104:107], v[128:131], v[10:13]
	v_mfma_f32_16x16x32_bf16 v[14:17], v[112:115], v[128:131], v[14:17]
	v_mfma_f32_16x16x32_bf16 v[18:21], v[104:107], v[136:139], v[18:21]
	v_mfma_f32_16x16x32_bf16 v[22:25], v[112:115], v[136:139], v[22:25]
	v_mfma_f32_16x16x32_bf16 v[26:29], v[104:107], v[144:147], v[26:29]
	v_mfma_f32_16x16x32_bf16 v[30:33], v[112:115], v[144:147], v[30:33]
	v_mfma_f32_16x16x32_bf16 v[2:5], v[108:111], v[124:127], v[2:5]
	v_mfma_f32_16x16x32_bf16 v[6:9], v[116:119], v[124:127], v[6:9]
	v_mfma_f32_16x16x32_bf16 v[10:13], v[108:111], v[132:135], v[10:13]
	v_mfma_f32_16x16x32_bf16 v[14:17], v[116:119], v[132:135], v[14:17]
	v_mfma_f32_16x16x32_bf16 v[18:21], v[108:111], v[140:143], v[18:21]
	v_mfma_f32_16x16x32_bf16 v[22:25], v[116:119], v[140:143], v[22:25]
	v_mfma_f32_16x16x32_bf16 v[26:29], v[108:111], v[148:151], v[26:29]
	v_mfma_f32_16x16x32_bf16 v[30:33], v[116:119], v[148:151], v[30:33]
	s_barrier
	s_add_i32 m0, s1, 0x1be80
	s_nop 0
	global_load_lds_dwordx4 v[160:161], off offset:384
	s_add_i32 m0, s1, 0x1de80
	s_add_i32 s0, s0, 2
	global_load_lds_dwordx4 v[162:163], off offset:384
	s_waitcnt vmcnt(6)
	s_add_u32 s10, s10, 0x100
	s_addc_u32 s11, s11, 0
	s_cmpk_lt_u32 s0, 0x54
	s_barrier
	s_barrier
	s_cbranch_scc1 .LBB0_689
	s_add_i32 s1, s1, 0x1e000
	s_add_u32 s0, s8, 0x2b80
	s_addc_u32 s1, s9, 0
	v_readfirstlane_b32 s8, v101
	v_lshl_add_u64 v[90:91], s[0:1], 0, v[0:1]
	s_mov_b32 m0, s8
	v_lshl_add_u64 v[66:67], s[0:1], 0, v[66:67]
	v_readfirstlane_b32 s0, v102
	ds_read_b128 v[68:71], v95
	ds_read_b128 v[72:75], v95 offset:1024
	ds_read_b128 v[76:79], v95 offset:2048
	ds_read_b128 v[86:89], v95 offset:3072
	ds_read_b128 v[96:99], v93
	ds_read_b128 v[104:107], v93 offset:1024
	ds_read_b128 v[108:111], v93 offset:2048
	ds_read_b128 v[112:115], v93 offset:3072
	ds_read_b128 v[116:119], v93 offset:4096
	ds_read_b128 v[120:123], v93 offset:5120
	ds_read_b128 v[124:127], v93 offset:6144
	ds_read_b128 v[128:131], v93 offset:7168
	global_load_lds_dwordx4 v[90:91], off
	s_mov_b32 m0, s0
	s_nop 0
	global_load_lds_dwordx4 v[66:67], off
	s_barrier
	s_waitcnt lgkmcnt(0)
	s_setprio 1
	s_waitcnt lgkmcnt(0)
	v_mfma_f32_16x16x32_bf16 v[62:65], v[68:71], v[96:99], v[62:65]
	v_mfma_f32_16x16x32_bf16 v[58:61], v[76:79], v[96:99], v[58:61]
	v_mfma_f32_16x16x32_bf16 v[54:57], v[68:71], v[108:111], v[54:57]
	v_mfma_f32_16x16x32_bf16 v[50:53], v[76:79], v[108:111], v[50:53]
	v_mfma_f32_16x16x32_bf16 v[46:49], v[68:71], v[116:119], v[46:49]
	v_mfma_f32_16x16x32_bf16 v[42:45], v[76:79], v[116:119], v[42:45]
	v_mfma_f32_16x16x32_bf16 v[38:41], v[68:71], v[124:127], v[38:41]
	v_mfma_f32_16x16x32_bf16 v[34:37], v[76:79], v[124:127], v[34:37]
	v_mfma_f32_16x16x32_bf16 v[62:65], v[72:75], v[104:107], v[62:65]
	v_mfma_f32_16x16x32_bf16 v[58:61], v[86:89], v[104:107], v[58:61]
	v_mfma_f32_16x16x32_bf16 v[54:57], v[72:75], v[112:115], v[54:57]
	v_mfma_f32_16x16x32_bf16 v[50:53], v[86:89], v[112:115], v[50:53]
	v_mfma_f32_16x16x32_bf16 v[46:49], v[72:75], v[120:123], v[46:49]
	v_mfma_f32_16x16x32_bf16 v[42:45], v[86:89], v[120:123], v[42:45]
	v_mfma_f32_16x16x32_bf16 v[38:41], v[72:75], v[128:131], v[38:41]
	v_mfma_f32_16x16x32_bf16 v[34:37], v[86:89], v[128:131], v[34:37]
	s_setprio 0
	s_barrier
	s_barrier
	s_waitcnt lgkmcnt(0)
	s_barrier
	ds_read_b128 v[96:99], v93 offset:16384
	ds_read_b128 v[100:103], v93 offset:17408
	ds_read_b128 v[104:107], v93 offset:18432
	ds_read_b128 v[108:111], v93 offset:19456
	ds_read_b128 v[112:115], v93 offset:20480
	ds_read_b128 v[116:119], v93 offset:21504
	ds_read_b128 v[120:123], v93 offset:22528
	ds_read_b128 v[124:127], v93 offset:23552
	s_waitcnt vmcnt(4)
	s_barrier
	s_waitcnt lgkmcnt(0)
	s_setprio 1
	s_waitcnt lgkmcnt(3)
	v_mfma_f32_16x16x32_bf16 v[18:21], v[68:71], v[112:115], v[18:21]
	v_mfma_f32_16x16x32_bf16 v[2:5], v[68:71], v[96:99], v[2:5]
	v_mfma_f32_16x16x32_bf16 v[6:9], v[76:79], v[96:99], v[6:9]
	s_waitcnt lgkmcnt(2)
	v_mfma_f32_16x16x32_bf16 v[96:99], v[72:75], v[116:119], v[18:21]
	v_mfma_f32_16x16x32_bf16 v[18:21], v[76:79], v[112:115], v[22:25]
	v_mfma_f32_16x16x32_bf16 v[2:5], v[72:75], v[100:103], v[2:5]
	v_mfma_f32_16x16x32_bf16 v[6:9], v[86:89], v[100:103], v[6:9]
	v_mfma_f32_16x16x32_bf16 v[10:13], v[68:71], v[104:107], v[10:13]
	v_mfma_f32_16x16x32_bf16 v[14:17], v[76:79], v[104:107], v[14:17]
	v_mfma_f32_16x16x32_bf16 v[100:103], v[86:89], v[116:119], v[18:21]
	s_waitcnt lgkmcnt(1)
	v_mfma_f32_16x16x32_bf16 v[18:21], v[68:71], v[120:123], v[26:29]
	v_mfma_f32_16x16x32_bf16 v[10:13], v[72:75], v[108:111], v[10:13]
	v_mfma_f32_16x16x32_bf16 v[14:17], v[86:89], v[108:111], v[14:17]
	s_waitcnt lgkmcnt(0)
	v_mfma_f32_16x16x32_bf16 v[66:69], v[72:75], v[124:127], v[18:21]
	v_mfma_f32_16x16x32_bf16 v[18:21], v[76:79], v[120:123], v[30:33]
	v_mfma_f32_16x16x32_bf16 v[70:73], v[86:89], v[124:127], v[18:21]
	s_setprio 0
	s_barrier
	ds_read_b128 v[74:77], v95 offset:32768
	ds_read_b128 v[86:89], v95 offset:33792
	ds_read_b128 v[104:107], v95 offset:34816
	ds_read_b128 v[108:111], v95 offset:35840
	s_nop 0
	ds_read_b128 v[18:21], v93 offset:32768
	ds_read_b128 v[22:25], v93 offset:33792
	ds_read_b128 v[26:29], v93 offset:34816
	ds_read_b128 v[30:33], v93 offset:35840
	ds_read_b128 v[112:115], v93 offset:36864
	ds_read_b128 v[116:119], v93 offset:37888
	ds_read_b128 v[120:123], v93 offset:38912
	ds_read_b128 v[124:127], v93 offset:39936
	s_waitcnt vmcnt(2)
	s_barrier
	s_waitcnt lgkmcnt(0)
	s_setprio 1
	s_waitcnt lgkmcnt(7)
	v_mfma_f32_16x16x32_bf16 v[62:65], v[74:77], v[18:21], v[62:65]
	v_mfma_f32_16x16x32_bf16 v[18:21], v[104:107], v[18:21], v[58:61]
	s_waitcnt lgkmcnt(6)
	v_mfma_f32_16x16x32_bf16 v[58:61], v[108:111], v[22:25], v[18:21]
	s_waitcnt lgkmcnt(5)
	v_mfma_f32_16x16x32_bf16 v[18:21], v[74:77], v[26:29], v[54:57]
	s_waitcnt lgkmcnt(4)
	v_mfma_f32_16x16x32_bf16 v[54:57], v[86:89], v[30:33], v[18:21]
	v_mfma_f32_16x16x32_bf16 v[18:21], v[104:107], v[26:29], v[50:53]
	v_mfma_f32_16x16x32_bf16 v[50:53], v[108:111], v[30:33], v[18:21]
	s_waitcnt lgkmcnt(3)
	v_mfma_f32_16x16x32_bf16 v[18:21], v[74:77], v[112:115], v[46:49]
	s_waitcnt lgkmcnt(2)
	v_mfma_f32_16x16x32_bf16 v[46:49], v[86:89], v[116:119], v[18:21]
	v_mfma_f32_16x16x32_bf16 v[18:21], v[104:107], v[112:115], v[42:45]
	v_mfma_f32_16x16x32_bf16 v[42:45], v[108:111], v[116:119], v[18:21]
	s_waitcnt lgkmcnt(1)
	v_mfma_f32_16x16x32_bf16 v[18:21], v[74:77], v[120:123], v[38:41]
	s_waitcnt lgkmcnt(0)
	v_mfma_f32_16x16x32_bf16 v[38:41], v[86:89], v[124:127], v[18:21]
	v_mfma_f32_16x16x32_bf16 v[18:21], v[104:107], v[120:123], v[34:37]
	v_mfma_f32_16x16x32_bf16 v[62:65], v[86:89], v[22:25], v[62:65]
	v_mfma_f32_16x16x32_bf16 v[34:37], v[108:111], v[124:127], v[18:21]
	s_setprio 0
	s_barrier
	s_waitcnt vmcnt(0)
	s_barrier
	s_waitcnt lgkmcnt(0)
	s_barrier
	s_nop 1
	ds_read_b128 v[18:21], v93 offset:49152
	ds_read_b128 v[22:25], v93 offset:50176
	ds_read_b128 v[112:115], v93 offset:51200
	ds_read_b128 v[116:119], v93 offset:52224
	ds_read_b128 v[120:123], v93 offset:53248
	ds_read_b128 v[124:127], v93 offset:54272
	ds_read_b128 v[128:131], v93 offset:55296
	ds_read_b128 v[90:93], v93 offset:56320
	s_barrier
	s_waitcnt lgkmcnt(0)
	s_setprio 1
	s_waitcnt lgkmcnt(7)
	v_mfma_f32_16x16x32_bf16 v[2:5], v[74:77], v[18:21], v[2:5]
	s_waitcnt lgkmcnt(6)
	v_mfma_f32_16x16x32_bf16 v[30:33], v[86:89], v[22:25], v[2:5]
	v_mfma_f32_16x16x32_bf16 v[2:5], v[104:107], v[18:21], v[6:9]
	v_mfma_f32_16x16x32_bf16 v[26:29], v[108:111], v[22:25], v[2:5]
	s_waitcnt lgkmcnt(5)
	v_mfma_f32_16x16x32_bf16 v[2:5], v[74:77], v[112:115], v[10:13]
	s_waitcnt lgkmcnt(4)
	v_mfma_f32_16x16x32_bf16 v[22:25], v[86:89], v[116:119], v[2:5]
	v_mfma_f32_16x16x32_bf16 v[2:5], v[104:107], v[112:115], v[14:17]
	v_mfma_f32_16x16x32_bf16 v[18:21], v[108:111], v[116:119], v[2:5]
	s_waitcnt lgkmcnt(3)
	v_mfma_f32_16x16x32_bf16 v[2:5], v[74:77], v[120:123], v[96:99]
	s_waitcnt lgkmcnt(2)
	v_mfma_f32_16x16x32_bf16 v[14:17], v[86:89], v[124:127], v[2:5]
	v_mfma_f32_16x16x32_bf16 v[2:5], v[104:107], v[120:123], v[100:103]
	v_mfma_f32_16x16x32_bf16 v[10:13], v[108:111], v[124:127], v[2:5]
	s_waitcnt lgkmcnt(1)
	v_mfma_f32_16x16x32_bf16 v[2:5], v[74:77], v[128:131], v[66:69]
	s_waitcnt lgkmcnt(0)
	v_mfma_f32_16x16x32_bf16 v[6:9], v[86:89], v[90:93], v[2:5]
	v_mfma_f32_16x16x32_bf16 v[2:5], v[104:107], v[128:131], v[70:73]
	v_mfma_f32_16x16x32_bf16 v[2:5], v[108:111], v[90:93], v[2:5]
	s_setprio 0
	s_movk_i32 s0, 0x100
	v_cmp_gt_u32_e32 vcc, s0, v80
	s_barrier
	s_and_saveexec_b64 s[0:1], vcc
	s_cbranch_execz .LBB0_692
	s_barrier

.LBB0_760:
	s_or_b64 exec, exec, s[14:15]
	v_mov_b32_e32 v131, v1
	v_add_u32_e32 v155, 0x18000, v145
	v_lshl_add_u64 v[10:11], s[0:1], 0, v[0:1]
	v_lshl_add_u64 v[12:13], s[0:1], 0, v[130:131]
	v_lshl_add_u64 v[18:19], s[12:13], 0, v[0:1]
	v_lshl_add_u64 v[20:21], s[12:13], 0, v[130:131]
	s_mov_b64 s[12:13], 0x80
	v_readfirstlane_b32 s0, v155
	v_add_u32_e32 v156, 0x1a000, v145
	v_lshl_add_u64 v[10:11], v[10:11], 0, s[12:13]
	s_mov_b32 m0, s0
	v_readfirstlane_b32 s0, v156
	v_add_u32_e32 v157, 0x8000, v145
	v_lshl_add_u64 v[14:15], s[8:9], 0, v[0:1]
	s_waitcnt vmcnt(4)
	s_barrier
	global_load_lds_dwordx4 v[10:11], off
	v_lshl_add_u64 v[10:11], v[12:13], 0, s[12:13]
	s_mov_b32 m0, s0
	v_readfirstlane_b32 s0, v157
	v_add_u32_e32 v158, 0xa000, v145
	v_lshl_add_u64 v[16:17], s[8:9], 0, v[130:131]
	global_load_lds_dwordx4 v[10:11], off
	v_lshl_add_u64 v[10:11], v[14:15], 0, s[12:13]
	s_mov_b32 m0, s0
	v_readfirstlane_b32 s0, v158
	v_add_u32_e32 v159, 0x1c000, v145
	global_load_lds_dwordx4 v[10:11], off
	v_lshl_add_u64 v[10:11], v[16:17], 0, s[12:13]
	s_mov_b32 m0, s0
	v_readfirstlane_b32 s0, v159
	v_add_u32_e32 v160, 0x1e000, v145
	global_load_lds_dwordx4 v[10:11], off
	v_lshl_add_u64 v[10:11], v[18:19], 0, s[12:13]
	s_mov_b32 m0, s0
	v_readfirstlane_b32 s0, v160
	global_load_lds_dwordx4 v[10:11], off
	v_lshl_add_u64 v[10:11], v[20:21], 0, s[12:13]
	s_mov_b32 m0, s0
	s_movk_i32 s13, 0x1600
	global_load_lds_dwordx4 v[10:11], off
	v_lshrrev_b32_e32 v10, 1, v2
	v_mul_lo_u32 v2, v4, s13
	s_mov_b32 s12, 0x16000
	v_mad_u64_u32 v[10:11], s[0:1], v10, s12, v[2:3]
	v_or_b32_e32 v2, v10, v3
	v_add_lshl_u32 v2, v2, v5, 1
	v_lshrrev_b32_e32 v5, 1, v6
	v_mul_lo_u32 v4, v8, s13
	v_mad_u64_u32 v[4:5], s[12:13], v5, s12, v[4:5]
	s_add_u32 s0, s16, s57
	v_or_b32_e32 v4, v4, v7
	v_mov_b32_e32 v3, v1
	s_addc_u32 s1, s17, s54
	v_add_lshl_u32 v4, v4, v9, 1
	v_mov_b32_e32 v5, v1
	v_and_b32_e32 v144, 15, v140
	v_bfe_u32 v143, v140, 4, 2
	v_lshlrev_b32_e32 v24, 2, v140
	v_lshl_add_u64 v[132:133], s[0:1], 0, v[2:3]
	v_lshl_add_u64 v[134:135], s[0:1], 0, v[4:5]
	s_add_u32 s0, s20, s10
	v_bfe_u32 v142, v140, 6, 2
	v_lshlrev_b32_e32 v22, 6, v144
	v_lshlrev_b32_e32 v23, 4, v143
	v_and_b32_e32 v24, 32, v24
	s_waitcnt vmcnt(6)
	s_addc_u32 s1, s21, s11
	v_bitop3_b32 v22, v23, v24, v22 bitop3:0x36
	v_lshlrev_b32_e32 v23, 13, v141
	v_lshl_or_b32 v24, v142, 12, v212
	v_lshl_add_u64 v[136:137], s[0:1], 0, v[2:3]
	v_mov_b32_e32 v2, 0
	v_lshl_add_u64 v[138:139], s[0:1], 0, v[4:5]
	s_mov_b32 s0, -2
	s_mov_b64 s[10:11], 0
	v_add_u32_e32 v148, v24, v22
	v_add_u32_e32 v147, v23, v22
	v_mov_b32_e32 v3, v2
	v_mov_b32_e32 v4, v2
	v_mov_b32_e32 v5, v2
	v_mov_b32_e32 v6, v2
	v_mov_b32_e32 v7, v2
	v_mov_b32_e32 v8, v2
	v_mov_b32_e32 v9, v2
	v_mov_b32_e32 v10, v2
	v_mov_b32_e32 v11, v2
	v_mov_b32_e32 v12, v2
	v_mov_b32_e32 v13, v2
	v_mov_b32_e32 v14, v2
	v_mov_b32_e32 v15, v2
	v_mov_b32_e32 v16, v2
	v_mov_b32_e32 v17, v2
	v_mov_b32_e32 v18, v2
	v_mov_b32_e32 v19, v2
	v_mov_b32_e32 v20, v2
	v_mov_b32_e32 v21, v2
	v_mov_b32_e32 v22, v2
	v_mov_b32_e32 v23, v2
	v_mov_b32_e32 v24, v2
	v_mov_b32_e32 v25, v2
	v_mov_b32_e32 v26, v2
	v_mov_b32_e32 v27, v2
	v_mov_b32_e32 v28, v2
	v_mov_b32_e32 v29, v2
	v_mov_b32_e32 v30, v2
	v_mov_b32_e32 v31, v2
	v_mov_b32_e32 v32, v2
	v_mov_b32_e32 v33, v2
	v_mov_b32_e32 v34, v2
	v_mov_b32_e32 v35, v2
	v_mov_b32_e32 v36, v2
	v_mov_b32_e32 v37, v2
	v_mov_b32_e32 v38, v2
	v_mov_b32_e32 v39, v2
	v_mov_b32_e32 v40, v2
	v_mov_b32_e32 v41, v2
	v_mov_b32_e32 v42, v2
	v_mov_b32_e32 v43, v2
	v_mov_b32_e32 v44, v2
	v_mov_b32_e32 v45, v2
	v_mov_b32_e32 v46, v2
	v_mov_b32_e32 v47, v2
	v_mov_b32_e32 v48, v2
	v_mov_b32_e32 v49, v2
	v_mov_b32_e32 v50, v2
	v_mov_b32_e32 v51, v2
	v_mov_b32_e32 v52, v2
	v_mov_b32_e32 v53, v2
	v_mov_b32_e32 v54, v2
	v_mov_b32_e32 v55, v2
	v_mov_b32_e32 v56, v2
	v_mov_b32_e32 v57, v2
	v_mov_b32_e32 v58, v2
	v_mov_b32_e32 v59, v2
	v_mov_b32_e32 v60, v2
	v_mov_b32_e32 v61, v2
	v_mov_b32_e32 v62, v2
	v_mov_b32_e32 v63, v2
	v_mov_b32_e32 v64, v2
	v_mov_b32_e32 v65, v2
	v_mov_b32_e32 v66, v2
	v_mov_b32_e32 v67, v2
	v_mov_b32_e32 v68, v2
	v_mov_b32_e32 v69, v2
	v_mov_b32_e32 v70, v2
	v_mov_b32_e32 v71, v2
	v_mov_b32_e32 v72, v2
	v_mov_b32_e32 v73, v2
	v_mov_b32_e32 v74, v2
	v_mov_b32_e32 v75, v2
	v_mov_b32_e32 v76, v2
	v_mov_b32_e32 v77, v2
	v_mov_b32_e32 v78, v2
	v_mov_b32_e32 v79, v2
	v_mov_b32_e32 v80, v2
	v_mov_b32_e32 v81, v2
	v_mov_b32_e32 v82, v2
	v_mov_b32_e32 v83, v2
	v_mov_b32_e32 v84, v2
	v_mov_b32_e32 v85, v2
	v_mov_b32_e32 v86, v2
	v_mov_b32_e32 v87, v2
	v_mov_b32_e32 v88, v2
	v_mov_b32_e32 v89, v2
	v_mov_b32_e32 v90, v2
	v_mov_b32_e32 v91, v2
	v_mov_b32_e32 v92, v2
	v_mov_b32_e32 v93, v2
	v_mov_b32_e32 v94, v2
	v_mov_b32_e32 v95, v2
	v_mov_b32_e32 v96, v2
	v_mov_b32_e32 v97, v2
	v_mov_b32_e32 v98, v2
	v_mov_b32_e32 v99, v2
	v_mov_b32_e32 v100, v2
	v_mov_b32_e32 v101, v2
	v_mov_b32_e32 v102, v2
	v_mov_b32_e32 v103, v2
	v_mov_b32_e32 v104, v2
	v_mov_b32_e32 v105, v2
	v_mov_b32_e32 v106, v2
	v_mov_b32_e32 v107, v2
	v_mov_b32_e32 v108, v2
	v_mov_b32_e32 v109, v2
	v_mov_b32_e32 v110, v2
	v_mov_b32_e32 v111, v2
	v_mov_b32_e32 v112, v2
	v_mov_b32_e32 v113, v2
	v_mov_b32_e32 v114, v2
	v_mov_b32_e32 v115, v2
	v_mov_b32_e32 v116, v2
	v_mov_b32_e32 v117, v2
	v_mov_b32_e32 v118, v2
	v_mov_b32_e32 v119, v2
	v_mov_b32_e32 v120, v2
	v_mov_b32_e32 v121, v2
	v_mov_b32_e32 v122, v2
	v_mov_b32_e32 v123, v2
	v_mov_b32_e32 v124, v2
	v_mov_b32_e32 v125, v2
	v_mov_b32_e32 v126, v2
	v_mov_b32_e32 v127, v2
	v_mov_b32_e32 v128, v2
	v_mov_b32_e32 v129, v2
	s_barrier
	v_add_u32_e32 v161, 0xc000, v145
	v_add_u32_e32 v162, 0xe000, v145
	v_readfirstlane_b32 s1, v145
	s_nop 1
	v_readfirstlane_b32 s98, v136
	v_readfirstlane_b32 s99, v137
	s_nop 3
	s_sub_u32 s98, s98, 0x400000
	s_subb_u32 s99, s99, 0
	v_subrev_u32_e32 v204, s98, v136
	v_add_u32_e32 v216, 0x160080, v204
	v_subrev_u32_e32 v205, s98, v138
	v_add_u32_e32 v217, 0x160080, v205
	v_readfirstlane_b32 vcc_lo, v132
	v_readfirstlane_b32 vcc_hi, v133
	s_nop 3
	s_sub_u32 vcc_lo, vcc_lo, 0x400000
	s_subb_u32 vcc_hi, vcc_hi, 0
	v_subrev_u32_e32 v210, vcc_lo, v132
	v_add_u32_e32 v218, 0x160100, v210
	v_subrev_u32_e32 v211, vcc_lo, v134
	v_add_u32_e32 v219, 0x160100, v211
	v_add_u32_e32 v228, 0x100, v204
	s_add_u32 s98, s98, s10
	s_addc_u32 s99, s99, s11
	s_add_u32 vcc_lo, vcc_lo, s10
	s_addc_u32 vcc_hi, vcc_hi, s11
	s_nop 4
.LBB0_761:
	ds_read_b128 v[164:167], v148
	ds_read_b128 v[168:171], v148 offset:1024
	ds_read_b128 v[172:175], v148 offset:2048
	ds_read_b128 v[176:179], v148 offset:3072
	s_add_i32 m0, s1, 0xc000
	ds_read_b128 v[180:183], v147
	ds_read_b128 v[184:187], v147 offset:1024
	ds_read_b128 v[188:191], v147 offset:2048
	ds_read_b128 v[192:195], v147 offset:3072
	ds_read_b128 v[196:199], v147 offset:4096
	ds_read_b128 v[200:203], v147 offset:5120
	ds_read_b128 v[222:225], v147 offset:6144
	ds_read_b128 v[232:235], v147 offset:7168
	global_load_lds_dwordx4 v216, s[98:99]
	s_add_i32 m0, s1, 0xe000
	s_nop 0
	global_load_lds_dwordx4 v217, s[98:99]
	s_waitcnt lgkmcnt(8)
	s_barrier
	s_waitcnt lgkmcnt(0)
	v_mfma_f32_16x16x32_bf16 v[126:129], v[164:167], v[180:183], v[126:129]
	v_mfma_f32_16x16x32_bf16 v[122:125], v[172:175], v[180:183], v[122:125]
	v_mfma_f32_16x16x32_bf16 v[118:121], v[164:167], v[188:191], v[118:121]
	v_mfma_f32_16x16x32_bf16 v[114:117], v[172:175], v[188:191], v[114:117]
	v_mfma_f32_16x16x32_bf16 v[110:113], v[164:167], v[196:199], v[110:113]
	v_mfma_f32_16x16x32_bf16 v[106:109], v[172:175], v[196:199], v[106:109]
	v_mfma_f32_16x16x32_bf16 v[102:105], v[164:167], v[222:225], v[102:105]
	v_mfma_f32_16x16x32_bf16 v[98:101], v[172:175], v[222:225], v[98:101]
	v_mfma_f32_16x16x32_bf16 v[126:129], v[168:171], v[184:187], v[126:129]
	v_mfma_f32_16x16x32_bf16 v[122:125], v[176:179], v[184:187], v[122:125]
	v_mfma_f32_16x16x32_bf16 v[118:121], v[168:171], v[192:195], v[118:121]
	v_mfma_f32_16x16x32_bf16 v[114:117], v[176:179], v[192:195], v[114:117]
	v_mfma_f32_16x16x32_bf16 v[110:113], v[168:171], v[200:203], v[110:113]
	v_mfma_f32_16x16x32_bf16 v[106:109], v[176:179], v[200:203], v[106:109]
	v_mfma_f32_16x16x32_bf16 v[102:105], v[168:171], v[232:235], v[102:105]
	v_mfma_f32_16x16x32_bf16 v[98:101], v[176:179], v[232:235], v[98:101]
	s_barrier
	s_add_i32 m0, s1, 0xff00
	ds_read_b128 v[236:239], v148 offset:16384
	ds_read_b128 v[240:243], v148 offset:17408
	ds_read_b128 v[244:247], v148 offset:18432
	ds_read_b128 v[248:251], v148 offset:19456
	global_load_lds_dwordx4 v210, vcc offset:256
	s_add_i32 m0, s1, 0x11f00
	s_nop 0
	global_load_lds_dwordx4 v211, vcc offset:256
	s_barrier
	s_waitcnt lgkmcnt(0)
	v_mfma_f32_16x16x32_bf16 v[94:97], v[236:239], v[180:183], v[94:97]
	v_mfma_f32_16x16x32_bf16 v[90:93], v[244:247], v[180:183], v[90:93]
	v_mfma_f32_16x16x32_bf16 v[86:89], v[236:239], v[188:191], v[86:89]
	v_mfma_f32_16x16x32_bf16 v[82:85], v[244:247], v[188:191], v[82:85]
	v_mfma_f32_16x16x32_bf16 v[78:81], v[236:239], v[196:199], v[78:81]
	v_mfma_f32_16x16x32_bf16 v[74:77], v[244:247], v[196:199], v[74:77]
	v_mfma_f32_16x16x32_bf16 v[70:73], v[236:239], v[222:225], v[70:73]
	v_mfma_f32_16x16x32_bf16 v[66:69], v[244:247], v[222:225], v[66:69]
	v_mfma_f32_16x16x32_bf16 v[94:97], v[240:243], v[184:187], v[94:97]
	v_mfma_f32_16x16x32_bf16 v[90:93], v[248:251], v[184:187], v[90:93]
	v_mfma_f32_16x16x32_bf16 v[86:89], v[240:243], v[192:195], v[86:89]
	v_mfma_f32_16x16x32_bf16 v[82:85], v[248:251], v[192:195], v[82:85]
	v_mfma_f32_16x16x32_bf16 v[78:81], v[240:243], v[200:203], v[78:81]
	v_mfma_f32_16x16x32_bf16 v[74:77], v[248:251], v[200:203], v[74:77]
	v_mfma_f32_16x16x32_bf16 v[70:73], v[240:243], v[232:235], v[70:73]
	v_mfma_f32_16x16x32_bf16 v[66:69], v[248:251], v[232:235], v[66:69]
	s_mov_b32 m0, s1
	s_barrier
	ds_read_b128 v[180:183], v147 offset:16384
	ds_read_b128 v[184:187], v147 offset:17408
	ds_read_b128 v[188:191], v147 offset:18432
	ds_read_b128 v[192:195], v147 offset:19456
	ds_read_b128 v[196:199], v147 offset:20480
	ds_read_b128 v[200:203], v147 offset:21504
	ds_read_b128 v[222:225], v147 offset:22528
	ds_read_b128 v[232:235], v147 offset:23552
	global_load_lds_dwordx4 v228, s[98:99]
	s_add_i32 m0, s1, 0x1f00
	s_nop 0
	global_load_lds_dwordx4 v205, s[98:99] offset:256
	s_barrier
	s_waitcnt lgkmcnt(0)
	v_mfma_f32_16x16x32_bf16 v[62:65], v[164:167], v[180:183], v[62:65]
	v_mfma_f32_16x16x32_bf16 v[58:61], v[172:175], v[180:183], v[58:61]
	v_mfma_f32_16x16x32_bf16 v[54:57], v[164:167], v[188:191], v[54:57]
	v_mfma_f32_16x16x32_bf16 v[50:53], v[172:175], v[188:191], v[50:53]
	v_mfma_f32_16x16x32_bf16 v[46:49], v[164:167], v[196:199], v[46:49]
	v_mfma_f32_16x16x32_bf16 v[42:45], v[172:175], v[196:199], v[42:45]
	v_mfma_f32_16x16x32_bf16 v[38:41], v[164:167], v[222:225], v[38:41]
	v_mfma_f32_16x16x32_bf16 v[34:37], v[172:175], v[222:225], v[34:37]
	v_mfma_f32_16x16x32_bf16 v[62:65], v[168:171], v[184:187], v[62:65]
	v_mfma_f32_16x16x32_bf16 v[58:61], v[176:179], v[184:187], v[58:61]
	v_mfma_f32_16x16x32_bf16 v[54:57], v[168:171], v[192:195], v[54:57]
	v_mfma_f32_16x16x32_bf16 v[50:53], v[176:179], v[192:195], v[50:53]
	v_mfma_f32_16x16x32_bf16 v[46:49], v[168:171], v[200:203], v[46:49]
	v_mfma_f32_16x16x32_bf16 v[42:45], v[176:179], v[200:203], v[42:45]
	v_mfma_f32_16x16x32_bf16 v[38:41], v[168:171], v[232:235], v[38:41]
	v_mfma_f32_16x16x32_bf16 v[34:37], v[176:179], v[232:235], v[34:37]
	s_barrier
	s_add_i32 m0, s1, 0x14000
	s_nop 0
	global_load_lds_dwordx4 v218, vcc
	s_add_i32 m0, s1, 0x16000
	s_nop 0
	global_load_lds_dwordx4 v219, vcc
	s_waitcnt vmcnt(6)
	s_barrier
	v_mfma_f32_16x16x32_bf16 v[30:33], v[236:239], v[180:183], v[30:33]
	v_mfma_f32_16x16x32_bf16 v[26:29], v[244:247], v[180:183], v[26:29]
	v_mfma_f32_16x16x32_bf16 v[22:25], v[236:239], v[188:191], v[22:25]
	v_mfma_f32_16x16x32_bf16 v[18:21], v[244:247], v[188:191], v[18:21]
	v_mfma_f32_16x16x32_bf16 v[14:17], v[236:239], v[196:199], v[14:17]
	v_mfma_f32_16x16x32_bf16 v[10:13], v[244:247], v[196:199], v[10:13]
	v_mfma_f32_16x16x32_bf16 v[6:9], v[236:239], v[222:225], v[6:9]
	v_mfma_f32_16x16x32_bf16 v[2:5], v[244:247], v[222:225], v[2:5]
	v_mfma_f32_16x16x32_bf16 v[30:33], v[240:243], v[184:187], v[30:33]
	v_mfma_f32_16x16x32_bf16 v[26:29], v[248:251], v[184:187], v[26:29]
	v_mfma_f32_16x16x32_bf16 v[22:25], v[240:243], v[192:195], v[22:25]
	v_mfma_f32_16x16x32_bf16 v[18:21], v[248:251], v[192:195], v[18:21]
	v_mfma_f32_16x16x32_bf16 v[14:17], v[240:243], v[200:203], v[14:17]
	v_mfma_f32_16x16x32_bf16 v[10:13], v[248:251], v[200:203], v[10:13]
	v_mfma_f32_16x16x32_bf16 v[6:9], v[240:243], v[232:235], v[6:9]
	v_mfma_f32_16x16x32_bf16 v[2:5], v[248:251], v[232:235], v[2:5]
	s_barrier
	ds_read_b128 v[164:167], v148 offset:32768
	ds_read_b128 v[168:171], v148 offset:33792
	ds_read_b128 v[172:175], v148 offset:34816
	ds_read_b128 v[176:179], v148 offset:35840
	s_add_i32 m0, s1, 0x3f80
	ds_read_b128 v[180:183], v147 offset:32768
	ds_read_b128 v[184:187], v147 offset:33792
	ds_read_b128 v[188:191], v147 offset:34816
	ds_read_b128 v[192:195], v147 offset:35840
	ds_read_b128 v[196:199], v147 offset:36864
	ds_read_b128 v[200:203], v147 offset:37888
	ds_read_b128 v[222:225], v147 offset:38912
	ds_read_b128 v[232:235], v147 offset:39936
	global_load_lds_dwordx4 v216, s[98:99] offset:128
	s_add_i32 m0, s1, 0x5f80
	s_nop 0
	global_load_lds_dwordx4 v217, s[98:99] offset:128
	s_waitcnt lgkmcnt(8)
	s_barrier
	s_waitcnt lgkmcnt(0)
	v_mfma_f32_16x16x32_bf16 v[126:129], v[164:167], v[180:183], v[126:129]
	v_mfma_f32_16x16x32_bf16 v[122:125], v[172:175], v[180:183], v[122:125]
	v_mfma_f32_16x16x32_bf16 v[118:121], v[164:167], v[188:191], v[118:121]
	v_mfma_f32_16x16x32_bf16 v[114:117], v[172:175], v[188:191], v[114:117]
	v_mfma_f32_16x16x32_bf16 v[110:113], v[164:167], v[196:199], v[110:113]
	v_mfma_f32_16x16x32_bf16 v[106:109], v[172:175], v[196:199], v[106:109]
	v_mfma_f32_16x16x32_bf16 v[102:105], v[164:167], v[222:225], v[102:105]
	v_mfma_f32_16x16x32_bf16 v[98:101], v[172:175], v[222:225], v[98:101]
	v_mfma_f32_16x16x32_bf16 v[126:129], v[168:171], v[184:187], v[126:129]
	v_mfma_f32_16x16x32_bf16 v[122:125], v[176:179], v[184:187], v[122:125]
	v_mfma_f32_16x16x32_bf16 v[118:121], v[168:171], v[192:195], v[118:121]
	v_mfma_f32_16x16x32_bf16 v[114:117], v[176:179], v[192:195], v[114:117]
	v_mfma_f32_16x16x32_bf16 v[110:113], v[168:171], v[200:203], v[110:113]
	v_mfma_f32_16x16x32_bf16 v[106:109], v[176:179], v[200:203], v[106:109]
	v_mfma_f32_16x16x32_bf16 v[102:105], v[168:171], v[232:235], v[102:105]
	v_mfma_f32_16x16x32_bf16 v[98:101], v[176:179], v[232:235], v[98:101]
	s_barrier
	s_add_i32 m0, s1, 0x17e80
	ds_read_b128 v[236:239], v148 offset:49152
	ds_read_b128 v[240:243], v148 offset:50176
	ds_read_b128 v[244:247], v148 offset:51200
	ds_read_b128 v[248:251], v148 offset:52224
	global_load_lds_dwordx4 v210, vcc offset:384
	s_add_i32 m0, s1, 0x19e80
	s_nop 0
	global_load_lds_dwordx4 v211, vcc offset:384
	s_barrier
	s_waitcnt lgkmcnt(0)
	v_mfma_f32_16x16x32_bf16 v[94:97], v[236:239], v[180:183], v[94:97]
	v_mfma_f32_16x16x32_bf16 v[90:93], v[244:247], v[180:183], v[90:93]
	v_mfma_f32_16x16x32_bf16 v[86:89], v[236:239], v[188:191], v[86:89]
	v_mfma_f32_16x16x32_bf16 v[82:85], v[244:247], v[188:191], v[82:85]
	v_mfma_f32_16x16x32_bf16 v[78:81], v[236:239], v[196:199], v[78:81]
	v_mfma_f32_16x16x32_bf16 v[74:77], v[244:247], v[196:199], v[74:77]
	v_mfma_f32_16x16x32_bf16 v[70:73], v[236:239], v[222:225], v[70:73]
	v_mfma_f32_16x16x32_bf16 v[66:69], v[244:247], v[222:225], v[66:69]
	v_mfma_f32_16x16x32_bf16 v[94:97], v[240:243], v[184:187], v[94:97]
	v_mfma_f32_16x16x32_bf16 v[90:93], v[248:251], v[184:187], v[90:93]
	v_mfma_f32_16x16x32_bf16 v[86:89], v[240:243], v[192:195], v[86:89]
	v_mfma_f32_16x16x32_bf16 v[82:85], v[248:251], v[192:195], v[82:85]
	v_mfma_f32_16x16x32_bf16 v[78:81], v[240:243], v[200:203], v[78:81]
	v_mfma_f32_16x16x32_bf16 v[74:77], v[248:251], v[200:203], v[74:77]
	v_mfma_f32_16x16x32_bf16 v[70:73], v[240:243], v[232:235], v[70:73]
	v_mfma_f32_16x16x32_bf16 v[66:69], v[248:251], v[232:235], v[66:69]
	s_add_i32 m0, s1, 0x7e80
	s_barrier
	ds_read_b128 v[180:183], v147 offset:49152
	ds_read_b128 v[184:187], v147 offset:50176
	ds_read_b128 v[188:191], v147 offset:51200
	ds_read_b128 v[192:195], v147 offset:52224
	ds_read_b128 v[196:199], v147 offset:53248
	ds_read_b128 v[200:203], v147 offset:54272
	ds_read_b128 v[222:225], v147 offset:55296
	ds_read_b128 v[232:235], v147 offset:56320
	global_load_lds_dwordx4 v204, s[98:99] offset:384
	s_add_i32 m0, s1, 0x9e80
	s_nop 0
	global_load_lds_dwordx4 v205, s[98:99] offset:384
	s_barrier
	s_waitcnt lgkmcnt(0)
	v_mfma_f32_16x16x32_bf16 v[62:65], v[164:167], v[180:183], v[62:65]
	v_mfma_f32_16x16x32_bf16 v[58:61], v[172:175], v[180:183], v[58:61]
	v_mfma_f32_16x16x32_bf16 v[54:57], v[164:167], v[188:191], v[54:57]
	v_mfma_f32_16x16x32_bf16 v[50:53], v[172:175], v[188:191], v[50:53]
	v_mfma_f32_16x16x32_bf16 v[46:49], v[164:167], v[196:199], v[46:49]
	v_mfma_f32_16x16x32_bf16 v[42:45], v[172:175], v[196:199], v[42:45]
	v_mfma_f32_16x16x32_bf16 v[38:41], v[164:167], v[222:225], v[38:41]
	v_mfma_f32_16x16x32_bf16 v[34:37], v[172:175], v[222:225], v[34:37]
	v_mfma_f32_16x16x32_bf16 v[62:65], v[168:171], v[184:187], v[62:65]
	v_mfma_f32_16x16x32_bf16 v[58:61], v[176:179], v[184:187], v[58:61]
	v_mfma_f32_16x16x32_bf16 v[54:57], v[168:171], v[192:195], v[54:57]
	v_mfma_f32_16x16x32_bf16 v[50:53], v[176:179], v[192:195], v[50:53]
	v_mfma_f32_16x16x32_bf16 v[46:49], v[168:171], v[200:203], v[46:49]
	v_mfma_f32_16x16x32_bf16 v[42:45], v[176:179], v[200:203], v[42:45]
	v_mfma_f32_16x16x32_bf16 v[38:41], v[168:171], v[232:235], v[38:41]
	v_mfma_f32_16x16x32_bf16 v[34:37], v[176:179], v[232:235], v[34:37]
	s_barrier
	s_add_i32 m0, s1, 0x1bf80
	s_nop 0
	global_load_lds_dwordx4 v218, vcc offset:128
	s_add_i32 m0, s1, 0x1df80
	s_nop 0
	global_load_lds_dwordx4 v219, vcc offset:128
	s_waitcnt vmcnt(6)
	s_barrier
	v_mfma_f32_16x16x32_bf16 v[30:33], v[236:239], v[180:183], v[30:33]
	v_mfma_f32_16x16x32_bf16 v[26:29], v[244:247], v[180:183], v[26:29]
	v_mfma_f32_16x16x32_bf16 v[22:25], v[236:239], v[188:191], v[22:25]
	v_mfma_f32_16x16x32_bf16 v[18:21], v[244:247], v[188:191], v[18:21]
	v_mfma_f32_16x16x32_bf16 v[14:17], v[236:239], v[196:199], v[14:17]
	v_mfma_f32_16x16x32_bf16 v[10:13], v[244:247], v[196:199], v[10:13]
	v_mfma_f32_16x16x32_bf16 v[6:9], v[236:239], v[222:225], v[6:9]
	v_mfma_f32_16x16x32_bf16 v[2:5], v[244:247], v[222:225], v[2:5]
	v_mfma_f32_16x16x32_bf16 v[30:33], v[240:243], v[184:187], v[30:33]
	v_mfma_f32_16x16x32_bf16 v[26:29], v[248:251], v[184:187], v[26:29]
	v_mfma_f32_16x16x32_bf16 v[22:25], v[240:243], v[192:195], v[22:25]
	v_mfma_f32_16x16x32_bf16 v[18:21], v[248:251], v[192:195], v[18:21]
	v_mfma_f32_16x16x32_bf16 v[14:17], v[240:243], v[200:203], v[14:17]
	v_mfma_f32_16x16x32_bf16 v[10:13], v[248:251], v[200:203], v[10:13]
	v_mfma_f32_16x16x32_bf16 v[6:9], v[240:243], v[232:235], v[6:9]
	v_mfma_f32_16x16x32_bf16 v[2:5], v[248:251], v[232:235], v[2:5]
	s_add_i32 s0, s0, 2
	s_add_u32 s10, s10, 0x100
	s_addc_u32 s11, s11, 0
	s_add_u32 s98, s98, 0x100
	s_addc_u32 s99, s99, 0
	s_add_u32 vcc_lo, vcc_lo, 0x100
	s_addc_u32 vcc_hi, vcc_hi, 0
	s_cmpk_lt_u32 s0, 0x54
	s_barrier
	s_cbranch_scc1 .LBB0_761
	s_add_i32 s1, s1, 0x1e000
	s_add_u32 s0, s8, 0x162b80
	s_addc_u32 s1, s9, 0
	v_readfirstlane_b32 s8, v161
	v_lshl_add_u64 v[158:159], s[0:1], 0, v[0:1]
	s_mov_b32 m0, s8
	v_lshl_add_u64 v[130:131], s[0:1], 0, v[130:131]
	v_readfirstlane_b32 s0, v162
	ds_read_b128 v[132:135], v148
	ds_read_b128 v[136:139], v148 offset:1024
	ds_read_b128 v[150:153], v148 offset:2048
	ds_read_b128 v[154:157], v148 offset:3072
	ds_read_b128 v[164:167], v147
	ds_read_b128 v[168:171], v147 offset:1024
	ds_read_b128 v[172:175], v147 offset:2048
	ds_read_b128 v[176:179], v147 offset:3072
	ds_read_b128 v[180:183], v147 offset:4096
	ds_read_b128 v[184:187], v147 offset:5120
	ds_read_b128 v[188:191], v147 offset:6144
	ds_read_b128 v[192:195], v147 offset:7168
	global_load_lds_dwordx4 v[158:159], off
	s_mov_b32 m0, s0
	s_nop 0
	global_load_lds_dwordx4 v[130:131], off
	s_barrier
	s_waitcnt lgkmcnt(0)
	s_setprio 1
	s_waitcnt lgkmcnt(0)
	v_mfma_f32_16x16x32_bf16 v[122:125], v[150:153], v[164:167], v[122:125]
	v_mfma_f32_16x16x32_bf16 v[118:121], v[132:135], v[172:175], v[118:121]
	v_mfma_f32_16x16x32_bf16 v[114:117], v[150:153], v[172:175], v[114:117]
	v_mfma_f32_16x16x32_bf16 v[102:105], v[132:135], v[188:191], v[102:105]
	v_mfma_f32_16x16x32_bf16 v[98:101], v[150:153], v[188:191], v[98:101]
	v_mfma_f32_16x16x32_bf16 v[126:129], v[132:135], v[164:167], v[126:129]
	v_mfma_f32_16x16x32_bf16 v[122:125], v[154:157], v[168:171], v[122:125]
	v_mfma_f32_16x16x32_bf16 v[118:121], v[136:139], v[176:179], v[118:121]
	v_mfma_f32_16x16x32_bf16 v[114:117], v[154:157], v[176:179], v[114:117]
	v_mfma_f32_16x16x32_bf16 v[110:113], v[132:135], v[180:183], v[110:113]
	v_mfma_f32_16x16x32_bf16 v[106:109], v[150:153], v[180:183], v[106:109]
	v_mfma_f32_16x16x32_bf16 v[102:105], v[136:139], v[192:195], v[102:105]
	v_mfma_f32_16x16x32_bf16 v[98:101], v[154:157], v[192:195], v[98:101]
	v_mfma_f32_16x16x32_bf16 v[126:129], v[136:139], v[168:171], v[126:129]
	v_mfma_f32_16x16x32_bf16 v[158:161], v[136:139], v[184:187], v[110:113]
	v_mfma_f32_16x16x32_bf16 v[196:199], v[154:157], v[184:187], v[106:109]
	s_setprio 0
	s_barrier
	ds_read_b128 v[106:109], v148 offset:16384
	ds_read_b128 v[110:113], v148 offset:17408
	ds_read_b128 v[200:203], v148 offset:18432
	ds_read_b128 v[222:225], v148 offset:19456
	s_barrier
	s_waitcnt lgkmcnt(0)
	s_setprio 1
	s_waitcnt lgkmcnt(3)
	v_mfma_f32_16x16x32_bf16 v[86:89], v[106:109], v[172:175], v[86:89]
	s_waitcnt lgkmcnt(1)
	v_mfma_f32_16x16x32_bf16 v[82:85], v[200:203], v[172:175], v[82:85]
	v_mfma_f32_16x16x32_bf16 v[70:73], v[106:109], v[188:191], v[70:73]
	v_mfma_f32_16x16x32_bf16 v[66:69], v[200:203], v[188:191], v[66:69]
	v_mfma_f32_16x16x32_bf16 v[94:97], v[106:109], v[164:167], v[94:97]
	v_mfma_f32_16x16x32_bf16 v[90:93], v[200:203], v[164:167], v[90:93]
	v_mfma_f32_16x16x32_bf16 v[86:89], v[110:113], v[176:179], v[86:89]
	s_waitcnt lgkmcnt(0)
	v_mfma_f32_16x16x32_bf16 v[82:85], v[222:225], v[176:179], v[82:85]
	v_mfma_f32_16x16x32_bf16 v[78:81], v[106:109], v[180:183], v[78:81]
	v_mfma_f32_16x16x32_bf16 v[74:77], v[200:203], v[180:183], v[74:77]
	v_mfma_f32_16x16x32_bf16 v[70:73], v[110:113], v[192:195], v[70:73]
	v_mfma_f32_16x16x32_bf16 v[66:69], v[222:225], v[192:195], v[66:69]
	v_mfma_f32_16x16x32_bf16 v[232:235], v[110:113], v[168:171], v[94:97]
	v_mfma_f32_16x16x32_bf16 v[162:165], v[222:225], v[168:171], v[90:93]
	v_mfma_f32_16x16x32_bf16 v[166:169], v[110:113], v[184:187], v[78:81]
	v_mfma_f32_16x16x32_bf16 v[170:173], v[222:225], v[184:187], v[74:77]
	s_setprio 0
	s_barrier
	s_nop 0
	ds_read_b128 v[74:77], v147 offset:16384
	ds_read_b128 v[78:81], v147 offset:17408
	ds_read_b128 v[90:93], v147 offset:18432
	ds_read_b128 v[94:97], v147 offset:19456
	ds_read_b128 v[174:177], v147 offset:20480
	ds_read_b128 v[178:181], v147 offset:21504
	ds_read_b128 v[182:185], v147 offset:22528
	ds_read_b128 v[186:189], v147 offset:23552
	s_waitcnt vmcnt(4)
	s_barrier
	s_waitcnt lgkmcnt(0)
	s_setprio 1
	s_waitcnt lgkmcnt(7)
	v_mfma_f32_16x16x32_bf16 v[62:65], v[132:135], v[74:77], v[62:65]
	v_mfma_f32_16x16x32_bf16 v[58:61], v[150:153], v[74:77], v[58:61]
	s_waitcnt lgkmcnt(5)
	v_mfma_f32_16x16x32_bf16 v[54:57], v[132:135], v[90:93], v[54:57]
	v_mfma_f32_16x16x32_bf16 v[50:53], v[150:153], v[90:93], v[50:53]
	s_waitcnt lgkmcnt(1)
	v_mfma_f32_16x16x32_bf16 v[38:41], v[132:135], v[182:185], v[38:41]
	v_mfma_f32_16x16x32_bf16 v[34:37], v[150:153], v[182:185], v[34:37]
	v_mfma_f32_16x16x32_bf16 v[62:65], v[136:139], v[78:81], v[62:65]
	v_mfma_f32_16x16x32_bf16 v[58:61], v[154:157], v[78:81], v[58:61]
	v_mfma_f32_16x16x32_bf16 v[54:57], v[136:139], v[94:97], v[54:57]
	v_mfma_f32_16x16x32_bf16 v[50:53], v[154:157], v[94:97], v[50:53]
	v_mfma_f32_16x16x32_bf16 v[46:49], v[132:135], v[174:177], v[46:49]
	v_mfma_f32_16x16x32_bf16 v[42:45], v[150:153], v[174:177], v[42:45]
	s_waitcnt lgkmcnt(0)
	v_mfma_f32_16x16x32_bf16 v[38:41], v[136:139], v[186:189], v[38:41]
	v_mfma_f32_16x16x32_bf16 v[34:37], v[154:157], v[186:189], v[34:37]
	v_mfma_f32_16x16x32_bf16 v[190:193], v[136:139], v[178:181], v[46:49]
	v_mfma_f32_16x16x32_bf16 v[236:239], v[154:157], v[178:181], v[42:45]
	s_setprio 0
	s_setprio 1
	v_mfma_f32_16x16x32_bf16 v[22:25], v[106:109], v[90:93], v[22:25]
	v_mfma_f32_16x16x32_bf16 v[18:21], v[200:203], v[90:93], v[18:21]
	v_mfma_f32_16x16x32_bf16 v[6:9], v[106:109], v[182:185], v[6:9]
	v_mfma_f32_16x16x32_bf16 v[2:5], v[200:203], v[182:185], v[2:5]
	v_mfma_f32_16x16x32_bf16 v[30:33], v[106:109], v[74:77], v[30:33]
	v_mfma_f32_16x16x32_bf16 v[26:29], v[200:203], v[74:77], v[26:29]
	v_mfma_f32_16x16x32_bf16 v[22:25], v[110:113], v[94:97], v[22:25]
	v_mfma_f32_16x16x32_bf16 v[18:21], v[222:225], v[94:97], v[18:21]
	v_mfma_f32_16x16x32_bf16 v[14:17], v[106:109], v[174:177], v[14:17]
	v_mfma_f32_16x16x32_bf16 v[10:13], v[200:203], v[174:177], v[10:13]
	v_mfma_f32_16x16x32_bf16 v[6:9], v[110:113], v[186:189], v[6:9]
	v_mfma_f32_16x16x32_bf16 v[2:5], v[222:225], v[186:189], v[2:5]
	v_mfma_f32_16x16x32_bf16 v[134:137], v[110:113], v[78:81], v[30:33]
	v_mfma_f32_16x16x32_bf16 v[150:153], v[222:225], v[78:81], v[26:29]
	v_mfma_f32_16x16x32_bf16 v[154:157], v[110:113], v[178:181], v[14:17]
	v_mfma_f32_16x16x32_bf16 v[174:177], v[222:225], v[178:181], v[10:13]
	s_setprio 0
	s_barrier
	s_nop 0
	ds_read_b128 v[10:13], v148 offset:32768
	ds_read_b128 v[14:17], v148 offset:33792
	ds_read_b128 v[178:181], v148 offset:34816
	ds_read_b128 v[182:185], v148 offset:35840
	ds_read_b128 v[26:29], v147 offset:32768
	ds_read_b128 v[30:33], v147 offset:33792
	ds_read_b128 v[42:45], v147 offset:34816
	ds_read_b128 v[46:49], v147 offset:35840
	ds_read_b128 v[186:189], v147 offset:36864
	ds_read_b128 v[200:203], v147 offset:37888
	ds_read_b128 v[222:225], v147 offset:38912
	ds_read_b128 v[240:243], v147 offset:39936
	s_waitcnt vmcnt(2)
	s_barrier
	s_waitcnt lgkmcnt(0)
	s_setprio 1
	s_waitcnt lgkmcnt(7)
	v_mfma_f32_16x16x32_bf16 v[74:77], v[10:13], v[26:29], v[126:129]
	s_waitcnt lgkmcnt(6)
	v_mfma_f32_16x16x32_bf16 v[130:133], v[14:17], v[30:33], v[74:77]
	v_mfma_f32_16x16x32_bf16 v[74:77], v[178:181], v[26:29], v[122:125]
	v_mfma_f32_16x16x32_bf16 v[122:125], v[182:185], v[30:33], v[74:77]
	s_waitcnt lgkmcnt(5)
	v_mfma_f32_16x16x32_bf16 v[74:77], v[10:13], v[42:45], v[118:121]
	s_waitcnt lgkmcnt(4)
	v_mfma_f32_16x16x32_bf16 v[110:113], v[14:17], v[46:49], v[74:77]
	v_mfma_f32_16x16x32_bf16 v[74:77], v[178:181], v[42:45], v[114:117]
	v_mfma_f32_16x16x32_bf16 v[106:109], v[182:185], v[46:49], v[74:77]
	s_waitcnt lgkmcnt(3)
	v_mfma_f32_16x16x32_bf16 v[74:77], v[10:13], v[186:189], v[158:161]
	s_waitcnt lgkmcnt(2)
	v_mfma_f32_16x16x32_bf16 v[94:97], v[14:17], v[200:203], v[74:77]
	v_mfma_f32_16x16x32_bf16 v[74:77], v[178:181], v[186:189], v[196:199]
	v_mfma_f32_16x16x32_bf16 v[90:93], v[182:185], v[200:203], v[74:77]
	s_waitcnt lgkmcnt(1)
	v_mfma_f32_16x16x32_bf16 v[74:77], v[10:13], v[222:225], v[102:105]
	s_waitcnt lgkmcnt(0)
	v_mfma_f32_16x16x32_bf16 v[78:81], v[14:17], v[240:243], v[74:77]
	v_mfma_f32_16x16x32_bf16 v[74:77], v[178:181], v[222:225], v[98:101]
	v_mfma_f32_16x16x32_bf16 v[74:77], v[182:185], v[240:243], v[74:77]
	s_setprio 0
	s_barrier
	ds_read_b128 v[126:129], v148 offset:49152
	ds_read_b128 v[158:161], v148 offset:50176
	ds_read_b128 v[194:197], v148 offset:51200
	ds_read_b128 v[244:247], v148 offset:52224
	s_waitcnt vmcnt(0)
	s_barrier
	s_waitcnt lgkmcnt(0)
	s_setprio 1
	s_waitcnt lgkmcnt(3)
	v_mfma_f32_16x16x32_bf16 v[98:101], v[126:129], v[26:29], v[232:235]
	s_waitcnt lgkmcnt(1)
	v_mfma_f32_16x16x32_bf16 v[26:29], v[194:197], v[26:29], v[162:165]
	s_waitcnt lgkmcnt(0)
	v_mfma_f32_16x16x32_bf16 v[114:117], v[244:247], v[30:33], v[26:29]
	v_mfma_f32_16x16x32_bf16 v[26:29], v[126:129], v[42:45], v[86:89]
	v_mfma_f32_16x16x32_bf16 v[102:105], v[158:161], v[46:49], v[26:29]
	v_mfma_f32_16x16x32_bf16 v[26:29], v[194:197], v[42:45], v[82:85]
	v_mfma_f32_16x16x32_bf16 v[118:121], v[158:161], v[30:33], v[98:101]
	v_mfma_f32_16x16x32_bf16 v[98:101], v[244:247], v[46:49], v[26:29]
	v_mfma_f32_16x16x32_bf16 v[26:29], v[126:129], v[186:189], v[166:169]
	v_mfma_f32_16x16x32_bf16 v[86:89], v[158:161], v[200:203], v[26:29]
	v_mfma_f32_16x16x32_bf16 v[26:29], v[194:197], v[186:189], v[170:173]
	v_mfma_f32_16x16x32_bf16 v[82:85], v[244:247], v[200:203], v[26:29]
	v_mfma_f32_16x16x32_bf16 v[26:29], v[126:129], v[222:225], v[70:73]
	v_mfma_f32_16x16x32_bf16 v[70:73], v[158:161], v[240:243], v[26:29]
	v_mfma_f32_16x16x32_bf16 v[26:29], v[194:197], v[222:225], v[66:69]
	v_mfma_f32_16x16x32_bf16 v[66:69], v[244:247], v[240:243], v[26:29]
	s_setprio 0
	s_barrier
	ds_read_b128 v[162:165], v147 offset:49152
	ds_read_b128 v[166:169], v147 offset:50176
	ds_read_b128 v[170:173], v147 offset:51200
	ds_read_b128 v[186:189], v147 offset:52224
	ds_read_b128 v[198:201], v147 offset:53248
	ds_read_b128 v[202:205], v147 offset:54272
	ds_read_b128 v[222:225], v147 offset:55296
	ds_read_b128 v[146:149], v147 offset:56320
	s_barrier
	s_waitcnt lgkmcnt(0)
	s_setprio 1
	s_waitcnt lgkmcnt(7)
	v_mfma_f32_16x16x32_bf16 v[26:29], v[10:13], v[162:165], v[62:65]
	s_waitcnt lgkmcnt(6)
	v_mfma_f32_16x16x32_bf16 v[62:65], v[14:17], v[166:169], v[26:29]
	v_mfma_f32_16x16x32_bf16 v[26:29], v[178:181], v[162:165], v[58:61]
	v_mfma_f32_16x16x32_bf16 v[58:61], v[182:185], v[166:169], v[26:29]
	s_waitcnt lgkmcnt(5)
	v_mfma_f32_16x16x32_bf16 v[26:29], v[10:13], v[170:173], v[54:57]
	s_waitcnt lgkmcnt(4)
	v_mfma_f32_16x16x32_bf16 v[46:49], v[14:17], v[186:189], v[26:29]
	v_mfma_f32_16x16x32_bf16 v[26:29], v[178:181], v[170:173], v[50:53]
	v_mfma_f32_16x16x32_bf16 v[42:45], v[182:185], v[186:189], v[26:29]
	s_waitcnt lgkmcnt(3)
	v_mfma_f32_16x16x32_bf16 v[26:29], v[10:13], v[198:201], v[190:193]
	s_waitcnt lgkmcnt(1)
	v_mfma_f32_16x16x32_bf16 v[10:13], v[10:13], v[222:225], v[38:41]
	v_mfma_f32_16x16x32_bf16 v[30:33], v[14:17], v[202:205], v[26:29]
	v_mfma_f32_16x16x32_bf16 v[26:29], v[178:181], v[198:201], v[236:239]
	s_waitcnt lgkmcnt(0)
	v_mfma_f32_16x16x32_bf16 v[14:17], v[14:17], v[146:149], v[10:13]
	v_mfma_f32_16x16x32_bf16 v[10:13], v[178:181], v[222:225], v[34:37]
	v_mfma_f32_16x16x32_bf16 v[26:29], v[182:185], v[202:205], v[26:29]
	v_mfma_f32_16x16x32_bf16 v[10:13], v[182:185], v[146:149], v[10:13]
	s_setprio 0
	s_setprio 1
	v_mfma_f32_16x16x32_bf16 v[34:37], v[126:129], v[162:165], v[134:137]
	v_mfma_f32_16x16x32_bf16 v[54:57], v[158:161], v[166:169], v[34:37]
	v_mfma_f32_16x16x32_bf16 v[34:37], v[194:197], v[162:165], v[150:153]
	v_mfma_f32_16x16x32_bf16 v[18:21], v[194:197], v[170:173], v[18:21]
	v_mfma_f32_16x16x32_bf16 v[50:53], v[244:247], v[166:169], v[34:37]
	v_mfma_f32_16x16x32_bf16 v[22:25], v[126:129], v[170:173], v[22:25]
	v_mfma_f32_16x16x32_bf16 v[34:37], v[244:247], v[186:189], v[18:21]
	v_mfma_f32_16x16x32_bf16 v[18:21], v[126:129], v[198:201], v[154:157]
	v_mfma_f32_16x16x32_bf16 v[38:41], v[158:161], v[186:189], v[22:25]
	v_mfma_f32_16x16x32_bf16 v[22:25], v[158:161], v[202:205], v[18:21]
	v_mfma_f32_16x16x32_bf16 v[18:21], v[194:197], v[198:201], v[174:177]
	v_mfma_f32_16x16x32_bf16 v[6:9], v[126:129], v[222:225], v[6:9]
	v_mfma_f32_16x16x32_bf16 v[2:5], v[194:197], v[222:225], v[2:5]
	v_mfma_f32_16x16x32_bf16 v[18:21], v[244:247], v[202:205], v[18:21]
	v_mfma_f32_16x16x32_bf16 v[6:9], v[158:161], v[146:149], v[6:9]
	v_mfma_f32_16x16x32_bf16 v[2:5], v[244:247], v[146:149], v[2:5]
	s_setprio 0
	s_movk_i32 s0, 0x100
	v_cmp_gt_u32_e32 vcc, s0, v140
	s_barrier
	s_and_saveexec_b64 s[0:1], vcc
	s_cbranch_execz .LBB0_764
	s_barrier
